# v8
# speedup vs baseline: 1.0314x; 1.0110x over previous
.LBB0_587:
	s_or_b64 exec, exec, s[6:7]
	v_lshlrev_b32_e32 v2, 3, v33
	v_mov_b32_e32 v78, v34
	v_lshlrev_b32_e32 v178, 1, v2
	v_ashrrev_i32_e32 v79, 31, v78
	s_waitcnt lgkmcnt(0)
	v_lshlrev_b64 v[0:1], 7, v[78:79]
	v_lshl_add_u64 v[0:1], s[74:75], 0, v[0:1]
	v_lshl_add_u64 v[118:119], v[0:1], 0, v[178:179]
	s_mov_b32 s6, 0x10000
	v_add_co_u32_e32 v4, vcc, s6, v118
	global_load_dwordx4 v[124:127], v[118:119], off
	s_nop 0
	v_addc_co_u32_e32 v5, vcc, 0, v119, vcc
	global_load_dwordx4 v[128:131], v[4:5], off
	s_mov_b64 s[8:9], 0x10000
	v_lshl_add_u64 v[120:121], v[118:119], 0, s[8:9]
	ds_read_b128 v[20:23], v104
	ds_read_b128 v[106:109], v104 offset:32
	global_load_dwordx4 v[132:135], v[118:119], off offset:32
	global_load_dwordx4 v[136:139], v[120:121], off offset:32
	v_readlane_b32 s10, v255, 12
	v_readlane_b32 s11, v255, 13
	v_ashrrev_i32_e32 v85, 31, v84
	v_lshlrev_b64 v[84:85], 9, v[84:85]
	v_ashrrev_i32_e32 v87, 31, v86
	v_lshlrev_b64 v[86:87], 9, v[86:87]
	v_ashrrev_i32_e32 v91, 31, v90
	v_lshlrev_b64 v[90:91], 9, v[90:91]
	v_ashrrev_i32_e32 v93, 31, v92
	v_lshlrev_b64 v[92:93], 9, v[92:93]
	v_ashrrev_i32_e32 v95, 31, v94
	v_lshlrev_b64 v[94:95], 9, v[94:95]
	v_ashrrev_i32_e32 v97, 31, v96
	v_lshlrev_b64 v[96:97], 9, v[96:97]
	v_ashrrev_i32_e32 v99, 31, v98
	v_lshlrev_b64 v[98:99], 9, v[98:99]
	v_ashrrev_i32_e32 v101, 31, v100
	v_lshlrev_b64 v[100:101], 9, v[100:101]
	v_ashrrev_i32_e32 v89, 31, v88
	v_lshlrev_b64 v[88:89], 9, v[88:89]
	v_lshlrev_b64 v[76:77], 9, v[76:77]
	global_load_dwordx4 v[140:143], v[118:119], off offset:64
	global_load_dwordx4 v[144:147], v[120:121], off offset:64
	global_load_dwordx4 v[152:155], v[118:119], off offset:96
	global_load_dwordx4 v[160:163], v[120:121], off offset:96
	s_waitcnt vmcnt(4) lgkmcnt(0)
	v_mfma_f32_32x32x16_bf16 v[0:15], v[20:23], v[124:127], 0
	v_mfma_f32_32x32x16_bf16 v[16:31], v[20:23], v[128:131], 0
	v_mfma_f32_32x32x16_bf16 v[0:15], v[106:109], v[132:135], v[0:15]
	v_mfma_f32_32x32x16_bf16 v[16:31], v[106:109], v[136:139], v[16:31]
	ds_read_b128 v[106:109], v104 offset:64
	s_waitcnt vmcnt(2) lgkmcnt(0)
	v_mfma_f32_32x32x16_bf16 v[0:15], v[106:109], v[140:143], v[0:15]
	v_mfma_f32_32x32x16_bf16 v[16:31], v[106:109], v[144:147], v[16:31]
	ds_read_b128 v[106:109], v104 offset:96
	s_waitcnt vmcnt(0) lgkmcnt(0)
	v_mfma_f32_32x32x16_bf16 v[0:15], v[106:109], v[152:155], v[0:15]
	v_mfma_f32_32x32x16_bf16 v[16:31], v[106:109], v[160:163], v[16:31]
	v_lshl_add_u64 v[106:107], v[78:79], 2, s[10:11]
	global_load_dword v33, v[106:107], off
	global_load_dword v35, v[106:107], off offset:2048
	v_lshl_add_u64 v[106:107], v[74:75], 0, v[78:79]
	v_lshlrev_b64 v[106:107], 2, v[106:107]
	v_lshl_add_u64 v[108:109], s[70:71], 0, v[106:107]
	v_lshl_add_u64 v[106:107], s[78:79], 0, v[106:107]
	s_waitcnt vmcnt(1)
	s_nop 2
	v_add_f32_e32 v0, v0, v33
	v_max_f32_e64 v81, -v0, 0
	v_mul_f32_e64 v0, |v0|, s92
	v_exp_f32_e32 v0, v0
	s_waitcnt vmcnt(0)
	v_add_f32_e32 v16, v16, v35
	v_add_f32_e32 v2, v2, v33
	v_add_f32_e32 v0, 1.0, v0
	v_cmp_gt_f32_e32 vcc, s96, v0
	s_nop 1
	v_cndmask_b32_e64 v83, 0, 32, vcc
	v_ldexp_f32 v0, v0, v83
	v_log_f32_e32 v0, v0
	s_nop 0
	v_mul_f32_e32 v83, 0x3f317217, v0
	v_fma_f32 v83, v0, s2, -v83
	v_fmac_f32_e32 v83, 0x3377d1cf, v0
	v_fmac_f32_e32 v83, 0x3f317217, v0
	v_cmp_lt_f32_e64 s[4:5], |v0|, s3
	s_nop 1
	v_cndmask_b32_e64 v0, v0, v83, s[4:5]
	v_cndmask_b32_e32 v83, 0, v219, vcc
	v_sub_f32_e32 v0, v0, v83
	v_add_f32_e32 v0, v81, v0
	v_max_f32_e64 v81, -v16, 0
	v_mul_f32_e64 v16, |v16|, s92
	v_exp_f32_e32 v16, v16
	v_sub_f32_e32 v0, -0.5, v0
	v_mul_f32_e32 v0, 0x3fb8aa3b, v0
	v_exp_f32_e32 v0, v0
	v_add_f32_e32 v16, 1.0, v16
	v_cmp_gt_f32_e32 vcc, s96, v16
	v_mul_f32_e32 v0, 0xbfb8aa3b, v0
	s_nop 0
	v_cndmask_b32_e64 v83, 0, 32, vcc
	v_ldexp_f32 v16, v16, v83
	v_log_f32_e32 v16, v16
	v_exp_f32_e32 v0, v0
	v_mul_f32_e32 v83, 0x3f317217, v16
	v_fma_f32 v83, v16, s2, -v83
	v_fmac_f32_e32 v83, 0x3377d1cf, v16
	v_fmac_f32_e32 v83, 0x3f317217, v16
	v_cmp_lt_f32_e64 s[4:5], |v16|, s3
	global_store_dword v[108:109], v0, off
	s_nop 0
	v_cndmask_b32_e64 v16, v16, v83, s[4:5]
	v_cndmask_b32_e32 v83, 0, v219, vcc
	v_sub_f32_e32 v16, v16, v83
	v_add_f32_e32 v16, v81, v16
	v_sub_f32_e32 v0, -0.5, v16
	v_mul_f32_e32 v0, 0x3fb8aa3b, v0
	v_exp_f32_e32 v0, v0
	s_nop 0
	v_mul_f32_e32 v0, 0xbfb8aa3b, v0
	v_exp_f32_e32 v0, v0
	global_store_dword v[106:107], v0, off
	v_add_f32_e32 v0, v1, v33
	v_max_f32_e64 v16, -v0, 0
	v_mul_f32_e64 v0, |v0|, s92
	v_exp_f32_e32 v0, v0
	v_add_f32_e32 v1, v17, v35
	v_lshl_add_u64 v[106:107], v[72:73], 0, v[78:79]
	v_add_f32_e32 v0, 1.0, v0
	v_cmp_gt_f32_e32 vcc, s96, v0
	s_nop 1
	v_cndmask_b32_e64 v17, 0, 32, vcc
	v_ldexp_f32 v0, v0, v17
	v_log_f32_e32 v0, v0
	s_nop 0
	v_mul_f32_e32 v17, 0x3f317217, v0
	v_fma_f32 v17, v0, s2, -v17
	v_fmac_f32_e32 v17, 0x3377d1cf, v0
	v_fmac_f32_e32 v17, 0x3f317217, v0
	v_cmp_lt_f32_e64 s[4:5], |v0|, s3
	s_nop 1
	v_cndmask_b32_e64 v0, v0, v17, s[4:5]
	v_cndmask_b32_e32 v17, 0, v219, vcc
	v_sub_f32_e32 v0, v0, v17
	v_add_f32_e32 v81, v16, v0
	v_max_f32_e64 v0, -v1, 0
	v_mul_f32_e64 v1, |v1|, s92
	v_exp_f32_e32 v1, v1
	v_sub_f32_e32 v81, -0.5, v81
	v_mul_f32_e32 v81, 0x3fb8aa3b, v81
	v_exp_f32_e32 v81, v81
	v_add_f32_e32 v1, 1.0, v1
	v_cmp_gt_f32_e32 vcc, s96, v1
	v_mul_f32_e32 v81, 0xbfb8aa3b, v81
	s_nop 0
	v_cndmask_b32_e64 v16, 0, 32, vcc
	v_ldexp_f32 v1, v1, v16
	v_log_f32_e32 v1, v1
	v_exp_f32_e32 v81, v81
	v_mul_f32_e32 v16, 0x3f317217, v1
	v_fma_f32 v16, v1, s2, -v16
	v_fmac_f32_e32 v16, 0x3377d1cf, v1
	v_fmac_f32_e32 v16, 0x3f317217, v1
	v_cmp_lt_f32_e64 s[4:5], |v1|, s3
	s_nop 1
	v_cndmask_b32_e64 v1, v1, v16, s[4:5]
	v_cndmask_b32_e32 v16, 0, v219, vcc
	v_sub_f32_e32 v1, v1, v16
	v_add_f32_e32 v83, v0, v1
	v_lshlrev_b64 v[0:1], 2, v[106:107]
	v_lshl_add_u64 v[16:17], s[70:71], 0, v[0:1]
	global_store_dword v[16:17], v81, off
	v_sub_f32_e32 v16, -0.5, v83
	v_mul_f32_e32 v16, 0x3fb8aa3b, v16
	v_exp_f32_e32 v16, v16
	v_max_f32_e64 v17, -v2, 0
	v_mul_f32_e64 v2, |v2|, s92
	v_exp_f32_e32 v2, v2
	v_mul_f32_e32 v16, 0xbfb8aa3b, v16
	v_exp_f32_e32 v16, v16
	v_lshl_add_u64 v[0:1], s[78:79], 0, v[0:1]
	v_add_f32_e32 v2, 1.0, v2
	v_cmp_gt_f32_e32 vcc, s96, v2
	global_store_dword v[0:1], v16, off
	v_add_f32_e32 v16, v18, v35
	v_cndmask_b32_e64 v18, 0, 32, vcc
	v_ldexp_f32 v2, v2, v18
	v_log_f32_e32 v2, v2
	v_lshl_add_u64 v[0:1], v[70:71], 0, v[78:79]
	v_lshlrev_b64 v[0:1], 2, v[0:1]
	v_ashrrev_i32_e32 v83, 31, v82
	v_mul_f32_e32 v18, 0x3f317217, v2
	v_fma_f32 v18, v2, s2, -v18
	v_fmac_f32_e32 v18, 0x3377d1cf, v2
	v_fmac_f32_e32 v18, 0x3f317217, v2
	v_cmp_lt_f32_e64 s[4:5], |v2|, s3
	v_lshlrev_b64 v[82:83], 9, v[82:83]
	v_ashrrev_i32_e32 v81, 31, v80
	v_cndmask_b32_e64 v2, v2, v18, s[4:5]
	v_cndmask_b32_e32 v18, 0, v219, vcc
	v_sub_f32_e32 v2, v2, v18
	v_add_f32_e32 v2, v17, v2
	v_max_f32_e64 v17, -v16, 0
	v_mul_f32_e64 v16, |v16|, s92
	v_exp_f32_e32 v16, v16
	v_sub_f32_e32 v2, -0.5, v2
	v_mul_f32_e32 v2, 0x3fb8aa3b, v2
	v_exp_f32_e32 v2, v2
	v_add_f32_e32 v16, 1.0, v16
	v_cmp_gt_f32_e32 vcc, s96, v16
	v_lshlrev_b64 v[80:81], 9, v[80:81]
	v_mul_f32_e32 v2, 0xbfb8aa3b, v2
	v_cndmask_b32_e64 v18, 0, 32, vcc
	v_ldexp_f32 v16, v16, v18
	v_log_f32_e32 v16, v16
	v_exp_f32_e32 v2, v2
	v_mul_f32_e32 v18, 0x3f317217, v16
	v_fma_f32 v18, v16, s2, -v18
	v_fmac_f32_e32 v18, 0x3377d1cf, v16
	v_fmac_f32_e32 v18, 0x3f317217, v16
	v_cmp_lt_f32_e64 s[4:5], |v16|, s3
	s_nop 1
	v_cndmask_b32_e64 v16, v16, v18, s[4:5]
	v_cndmask_b32_e32 v18, 0, v219, vcc
	v_sub_f32_e32 v16, v16, v18
	v_add_f32_e32 v18, v17, v16
	v_lshl_add_u64 v[16:17], s[70:71], 0, v[0:1]
	global_store_dword v[16:17], v2, off
	v_sub_f32_e32 v2, -0.5, v18
	v_mul_f32_e32 v2, 0x3fb8aa3b, v2
	v_exp_f32_e32 v2, v2
	v_lshl_add_u64 v[0:1], s[78:79], 0, v[0:1]
	v_mul_f32_e32 v2, 0xbfb8aa3b, v2
	v_exp_f32_e32 v2, v2
	global_store_dword v[0:1], v2, off
	v_add_f32_e32 v2, v3, v33
	v_max_f32_e64 v16, -v2, 0
	v_mul_f32_e64 v2, |v2|, s92
	v_exp_f32_e32 v2, v2
	v_add_f32_e32 v3, v19, v35
	v_lshl_add_u64 v[0:1], v[68:69], 0, v[78:79]
	v_lshlrev_b64 v[0:1], 2, v[0:1]
	v_add_f32_e32 v2, 1.0, v2
	v_cmp_gt_f32_e32 vcc, s96, v2
	s_nop 1
	v_cndmask_b32_e64 v17, 0, 32, vcc
	v_ldexp_f32 v2, v2, v17
	v_log_f32_e32 v2, v2
	s_nop 0
	v_mul_f32_e32 v17, 0x3f317217, v2
	v_fma_f32 v17, v2, s2, -v17
	v_fmac_f32_e32 v17, 0x3377d1cf, v2
	v_fmac_f32_e32 v17, 0x3f317217, v2
	v_cmp_lt_f32_e64 s[4:5], |v2|, s3
	s_nop 1
	v_cndmask_b32_e64 v2, v2, v17, s[4:5]
	v_cndmask_b32_e32 v17, 0, v219, vcc
	v_sub_f32_e32 v2, v2, v17
	v_add_f32_e32 v16, v16, v2
	v_max_f32_e64 v2, -v3, 0
	v_mul_f32_e64 v3, |v3|, s92
	v_exp_f32_e32 v3, v3
	v_sub_f32_e32 v16, -0.5, v16
	v_mul_f32_e32 v16, 0x3fb8aa3b, v16
	v_exp_f32_e32 v16, v16
	v_add_f32_e32 v3, 1.0, v3
	v_cmp_gt_f32_e32 vcc, s96, v3
	v_mul_f32_e32 v16, 0xbfb8aa3b, v16
	s_nop 0
	v_cndmask_b32_e64 v17, 0, 32, vcc
	v_ldexp_f32 v3, v3, v17
	v_log_f32_e32 v3, v3
	v_exp_f32_e32 v16, v16
	v_mul_f32_e32 v17, 0x3f317217, v3
	v_fma_f32 v17, v3, s2, -v17
	v_fmac_f32_e32 v17, 0x3377d1cf, v3
	v_fmac_f32_e32 v17, 0x3f317217, v3
	v_cmp_lt_f32_e64 s[4:5], |v3|, s3
	s_nop 1
	v_cndmask_b32_e64 v3, v3, v17, s[4:5]
	v_cndmask_b32_e32 v17, 0, v219, vcc
	v_sub_f32_e32 v3, v3, v17
	v_add_f32_e32 v17, v2, v3
	v_lshl_add_u64 v[2:3], s[70:71], 0, v[0:1]
	global_store_dword v[2:3], v16, off
	v_sub_f32_e32 v2, -0.5, v17
	v_mul_f32_e32 v2, 0x3fb8aa3b, v2
	v_exp_f32_e32 v2, v2
	v_lshl_add_u64 v[0:1], s[78:79], 0, v[0:1]
	v_add_f32_e32 v3, v20, v35
	v_mul_f32_e32 v2, 0xbfb8aa3b, v2
	v_exp_f32_e32 v2, v2
	global_store_dword v[0:1], v2, off
	v_add_f32_e32 v2, v4, v33
	v_max_f32_e64 v4, -v2, 0
	v_mul_f32_e64 v2, |v2|, s92
	v_exp_f32_e32 v2, v2
	v_lshl_add_u64 v[0:1], v[84:85], 0, v[78:79]
	v_lshlrev_b64 v[0:1], 2, v[0:1]
	v_add_f32_e32 v2, 1.0, v2
	v_cmp_gt_f32_e32 vcc, s96, v2
	s_nop 1
	v_cndmask_b32_e64 v16, 0, 32, vcc
	v_ldexp_f32 v2, v2, v16
	v_log_f32_e32 v2, v2
	s_nop 0
	v_mul_f32_e32 v16, 0x3f317217, v2
	v_fma_f32 v16, v2, s2, -v16
	v_fmac_f32_e32 v16, 0x3377d1cf, v2
	v_fmac_f32_e32 v16, 0x3f317217, v2
	v_cmp_lt_f32_e64 s[4:5], |v2|, s3
	s_nop 1
	v_cndmask_b32_e64 v2, v2, v16, s[4:5]
	v_cndmask_b32_e32 v16, 0, v219, vcc
	v_sub_f32_e32 v2, v2, v16
	v_add_f32_e32 v4, v4, v2
	v_max_f32_e64 v2, -v3, 0
	v_mul_f32_e64 v3, |v3|, s92
	v_exp_f32_e32 v3, v3
	v_sub_f32_e32 v4, -0.5, v4
	v_mul_f32_e32 v4, 0x3fb8aa3b, v4
	v_exp_f32_e32 v4, v4
	v_add_f32_e32 v3, 1.0, v3
	v_cmp_gt_f32_e32 vcc, s96, v3
	v_mul_f32_e32 v4, 0xbfb8aa3b, v4
	s_nop 0
	v_cndmask_b32_e64 v16, 0, 32, vcc
	v_ldexp_f32 v3, v3, v16
	v_log_f32_e32 v3, v3
	v_exp_f32_e32 v4, v4
	v_mul_f32_e32 v16, 0x3f317217, v3
	v_fma_f32 v16, v3, s2, -v16
	v_fmac_f32_e32 v16, 0x3377d1cf, v3
	v_fmac_f32_e32 v16, 0x3f317217, v3
	v_cmp_lt_f32_e64 s[4:5], |v3|, s3
	s_nop 1
	v_cndmask_b32_e64 v3, v3, v16, s[4:5]
	v_cndmask_b32_e32 v16, 0, v219, vcc
	v_sub_f32_e32 v3, v3, v16
	v_add_f32_e32 v16, v2, v3
	v_lshl_add_u64 v[2:3], s[70:71], 0, v[0:1]
	global_store_dword v[2:3], v4, off
	v_sub_f32_e32 v2, -0.5, v16
	v_mul_f32_e32 v2, 0x3fb8aa3b, v2
	v_exp_f32_e32 v2, v2
	v_lshl_add_u64 v[0:1], s[78:79], 0, v[0:1]
	v_add_f32_e32 v3, v21, v35
	v_mul_f32_e32 v2, 0xbfb8aa3b, v2
	v_exp_f32_e32 v2, v2
	global_store_dword v[0:1], v2, off
	v_add_f32_e32 v2, v5, v33
	v_max_f32_e64 v4, -v2, 0
	v_mul_f32_e64 v2, |v2|, s92
	v_exp_f32_e32 v2, v2
	v_lshl_add_u64 v[0:1], v[86:87], 0, v[78:79]
	v_lshlrev_b64 v[0:1], 2, v[0:1]
	v_add_f32_e32 v2, 1.0, v2
	v_cmp_gt_f32_e32 vcc, s96, v2
	s_nop 1
	v_cndmask_b32_e64 v5, 0, 32, vcc
	v_ldexp_f32 v2, v2, v5
	v_log_f32_e32 v2, v2
	s_nop 0
	v_mul_f32_e32 v5, 0x3f317217, v2
	v_fma_f32 v5, v2, s2, -v5
	v_fmac_f32_e32 v5, 0x3377d1cf, v2
	v_fmac_f32_e32 v5, 0x3f317217, v2
	v_cmp_lt_f32_e64 s[4:5], |v2|, s3
	s_nop 1
	v_cndmask_b32_e64 v2, v2, v5, s[4:5]
	v_cndmask_b32_e32 v5, 0, v219, vcc
	v_sub_f32_e32 v2, v2, v5
	v_add_f32_e32 v4, v4, v2
	v_max_f32_e64 v2, -v3, 0
	v_mul_f32_e64 v3, |v3|, s92
	v_exp_f32_e32 v3, v3
	v_sub_f32_e32 v4, -0.5, v4
	v_mul_f32_e32 v4, 0x3fb8aa3b, v4
	v_exp_f32_e32 v4, v4
	v_add_f32_e32 v3, 1.0, v3
	v_cmp_gt_f32_e32 vcc, s96, v3
	v_mul_f32_e32 v4, 0xbfb8aa3b, v4
	s_nop 0
	v_cndmask_b32_e64 v5, 0, 32, vcc
	v_ldexp_f32 v3, v3, v5
	v_log_f32_e32 v3, v3
	v_exp_f32_e32 v4, v4
	v_mul_f32_e32 v5, 0x3f317217, v3
	v_fma_f32 v5, v3, s2, -v5
	v_fmac_f32_e32 v5, 0x3377d1cf, v3
	v_fmac_f32_e32 v5, 0x3f317217, v3
	v_cmp_lt_f32_e64 s[4:5], |v3|, s3
	s_nop 1
	v_cndmask_b32_e64 v3, v3, v5, s[4:5]
	v_cndmask_b32_e32 v5, 0, v219, vcc
	v_sub_f32_e32 v3, v3, v5
	v_add_f32_e32 v5, v2, v3
	v_lshl_add_u64 v[2:3], s[70:71], 0, v[0:1]
	global_store_dword v[2:3], v4, off
	v_sub_f32_e32 v2, -0.5, v5
	v_mul_f32_e32 v2, 0x3fb8aa3b, v2
	v_exp_f32_e32 v2, v2
	v_lshl_add_u64 v[0:1], s[78:79], 0, v[0:1]
	v_add_f32_e32 v3, v22, v35
	v_mul_f32_e32 v2, 0xbfb8aa3b, v2
	v_exp_f32_e32 v2, v2
	global_store_dword v[0:1], v2, off
	v_add_f32_e32 v2, v6, v33
	v_max_f32_e64 v4, -v2, 0
	v_mul_f32_e64 v2, |v2|, s92
	v_exp_f32_e32 v2, v2
	v_lshl_add_u64 v[0:1], v[90:91], 0, v[78:79]
	v_lshlrev_b64 v[0:1], 2, v[0:1]
	v_add_f32_e32 v2, 1.0, v2
	v_cmp_gt_f32_e32 vcc, s96, v2
	s_nop 1
	v_cndmask_b32_e64 v5, 0, 32, vcc
	v_ldexp_f32 v2, v2, v5
	v_log_f32_e32 v2, v2
	s_nop 0
	v_mul_f32_e32 v5, 0x3f317217, v2
	v_fma_f32 v5, v2, s2, -v5
	v_fmac_f32_e32 v5, 0x3377d1cf, v2
	v_fmac_f32_e32 v5, 0x3f317217, v2
	v_cmp_lt_f32_e64 s[4:5], |v2|, s3
	s_nop 1
	v_cndmask_b32_e64 v2, v2, v5, s[4:5]
	v_cndmask_b32_e32 v5, 0, v219, vcc
	v_sub_f32_e32 v2, v2, v5
	v_add_f32_e32 v4, v4, v2
	v_max_f32_e64 v2, -v3, 0
	v_mul_f32_e64 v3, |v3|, s92
	v_exp_f32_e32 v3, v3
	v_sub_f32_e32 v4, -0.5, v4
	v_mul_f32_e32 v4, 0x3fb8aa3b, v4
	v_exp_f32_e32 v4, v4
	v_add_f32_e32 v3, 1.0, v3
	v_cmp_gt_f32_e32 vcc, s96, v3
	v_mul_f32_e32 v4, 0xbfb8aa3b, v4
	s_nop 0
	v_cndmask_b32_e64 v5, 0, 32, vcc
	v_ldexp_f32 v3, v3, v5
	v_log_f32_e32 v3, v3
	v_exp_f32_e32 v4, v4
	v_mul_f32_e32 v5, 0x3f317217, v3
	v_fma_f32 v5, v3, s2, -v5
	v_fmac_f32_e32 v5, 0x3377d1cf, v3
	v_fmac_f32_e32 v5, 0x3f317217, v3
	v_cmp_lt_f32_e64 s[4:5], |v3|, s3
	s_nop 1
	v_cndmask_b32_e64 v3, v3, v5, s[4:5]
	v_cndmask_b32_e32 v5, 0, v219, vcc
	v_sub_f32_e32 v3, v3, v5
	v_add_f32_e32 v5, v2, v3
	v_lshl_add_u64 v[2:3], s[70:71], 0, v[0:1]
	global_store_dword v[2:3], v4, off
	v_sub_f32_e32 v2, -0.5, v5
	v_mul_f32_e32 v2, 0x3fb8aa3b, v2
	v_exp_f32_e32 v2, v2
	v_lshl_add_u64 v[0:1], s[78:79], 0, v[0:1]
	v_add_f32_e32 v3, v23, v35
	v_mul_f32_e32 v2, 0xbfb8aa3b, v2
	v_exp_f32_e32 v2, v2
	global_store_dword v[0:1], v2, off
	v_add_f32_e32 v2, v7, v33
	v_max_f32_e64 v4, -v2, 0
	v_mul_f32_e64 v2, |v2|, s92
	v_exp_f32_e32 v2, v2
	v_lshl_add_u64 v[0:1], v[92:93], 0, v[78:79]
	v_lshlrev_b64 v[0:1], 2, v[0:1]
	v_add_f32_e32 v2, 1.0, v2
	v_cmp_gt_f32_e32 vcc, s96, v2
	s_nop 1
	v_cndmask_b32_e64 v5, 0, 32, vcc
	v_ldexp_f32 v2, v2, v5
	v_log_f32_e32 v2, v2
	s_nop 0
	v_mul_f32_e32 v5, 0x3f317217, v2
	v_fma_f32 v5, v2, s2, -v5
	v_fmac_f32_e32 v5, 0x3377d1cf, v2
	v_fmac_f32_e32 v5, 0x3f317217, v2
	v_cmp_lt_f32_e64 s[4:5], |v2|, s3
	s_nop 1
	v_cndmask_b32_e64 v2, v2, v5, s[4:5]
	v_cndmask_b32_e32 v5, 0, v219, vcc
	v_sub_f32_e32 v2, v2, v5
	v_add_f32_e32 v4, v4, v2
	v_max_f32_e64 v2, -v3, 0
	v_mul_f32_e64 v3, |v3|, s92
	v_exp_f32_e32 v3, v3
	v_sub_f32_e32 v4, -0.5, v4
	v_mul_f32_e32 v4, 0x3fb8aa3b, v4
	v_exp_f32_e32 v4, v4
	v_add_f32_e32 v3, 1.0, v3
	v_cmp_gt_f32_e32 vcc, s96, v3
	v_mul_f32_e32 v4, 0xbfb8aa3b, v4
	s_nop 0
	v_cndmask_b32_e64 v5, 0, 32, vcc
	v_ldexp_f32 v3, v3, v5
	v_log_f32_e32 v3, v3
	v_exp_f32_e32 v4, v4
	v_mul_f32_e32 v5, 0x3f317217, v3
	v_fma_f32 v5, v3, s2, -v5
	v_fmac_f32_e32 v5, 0x3377d1cf, v3
	v_fmac_f32_e32 v5, 0x3f317217, v3
	v_cmp_lt_f32_e64 s[4:5], |v3|, s3
	s_nop 1
	v_cndmask_b32_e64 v3, v3, v5, s[4:5]
	v_cndmask_b32_e32 v5, 0, v219, vcc
	v_sub_f32_e32 v3, v3, v5
	v_add_f32_e32 v5, v2, v3
	v_lshl_add_u64 v[2:3], s[70:71], 0, v[0:1]
	global_store_dword v[2:3], v4, off
	v_sub_f32_e32 v2, -0.5, v5
	v_mul_f32_e32 v2, 0x3fb8aa3b, v2
	v_exp_f32_e32 v2, v2
	v_lshl_add_u64 v[0:1], s[78:79], 0, v[0:1]
	v_add_f32_e32 v3, v24, v35
	v_mul_f32_e32 v2, 0xbfb8aa3b, v2
	v_exp_f32_e32 v2, v2
	global_store_dword v[0:1], v2, off
	v_add_f32_e32 v2, v8, v33
	v_max_f32_e64 v4, -v2, 0
	v_mul_f32_e64 v2, |v2|, s92
	v_exp_f32_e32 v2, v2
	v_lshl_add_u64 v[0:1], v[94:95], 0, v[78:79]
	v_lshlrev_b64 v[0:1], 2, v[0:1]
	v_add_f32_e32 v2, 1.0, v2
	v_cmp_gt_f32_e32 vcc, s96, v2
	s_nop 1
	v_cndmask_b32_e64 v5, 0, 32, vcc
	v_ldexp_f32 v2, v2, v5
	v_log_f32_e32 v2, v2
	s_nop 0
	v_mul_f32_e32 v5, 0x3f317217, v2
	v_fma_f32 v5, v2, s2, -v5
	v_fmac_f32_e32 v5, 0x3377d1cf, v2
	v_fmac_f32_e32 v5, 0x3f317217, v2
	v_cmp_lt_f32_e64 s[4:5], |v2|, s3
	s_nop 1
	v_cndmask_b32_e64 v2, v2, v5, s[4:5]
	v_cndmask_b32_e32 v5, 0, v219, vcc
	v_sub_f32_e32 v2, v2, v5
	v_add_f32_e32 v4, v4, v2
	v_max_f32_e64 v2, -v3, 0
	v_mul_f32_e64 v3, |v3|, s92
	v_exp_f32_e32 v3, v3
	v_sub_f32_e32 v4, -0.5, v4
	v_mul_f32_e32 v4, 0x3fb8aa3b, v4
	v_exp_f32_e32 v4, v4
	v_add_f32_e32 v3, 1.0, v3
	v_cmp_gt_f32_e32 vcc, s96, v3
	v_mul_f32_e32 v4, 0xbfb8aa3b, v4
	s_nop 0
	v_cndmask_b32_e64 v5, 0, 32, vcc
	v_ldexp_f32 v3, v3, v5
	v_log_f32_e32 v3, v3
	v_exp_f32_e32 v4, v4
	v_mul_f32_e32 v5, 0x3f317217, v3
	v_fma_f32 v5, v3, s2, -v5
	v_fmac_f32_e32 v5, 0x3377d1cf, v3
	v_fmac_f32_e32 v5, 0x3f317217, v3
	v_cmp_lt_f32_e64 s[4:5], |v3|, s3
	s_nop 1
	v_cndmask_b32_e64 v3, v3, v5, s[4:5]
	v_cndmask_b32_e32 v5, 0, v219, vcc
	v_sub_f32_e32 v3, v3, v5
	v_add_f32_e32 v5, v2, v3
	v_lshl_add_u64 v[2:3], s[70:71], 0, v[0:1]
	global_store_dword v[2:3], v4, off
	v_sub_f32_e32 v2, -0.5, v5
	v_mul_f32_e32 v2, 0x3fb8aa3b, v2
	v_exp_f32_e32 v2, v2
	v_lshl_add_u64 v[0:1], s[78:79], 0, v[0:1]
	v_add_f32_e32 v3, v25, v35
	v_mul_f32_e32 v2, 0xbfb8aa3b, v2
	v_exp_f32_e32 v2, v2
	global_store_dword v[0:1], v2, off
	v_add_f32_e32 v2, v9, v33
	v_max_f32_e64 v4, -v2, 0
	v_mul_f32_e64 v2, |v2|, s92
	v_exp_f32_e32 v2, v2
	v_lshl_add_u64 v[0:1], v[96:97], 0, v[78:79]
	v_lshlrev_b64 v[0:1], 2, v[0:1]
	v_add_f32_e32 v2, 1.0, v2
	v_cmp_gt_f32_e32 vcc, s96, v2
	s_nop 1
	v_cndmask_b32_e64 v5, 0, 32, vcc
	v_ldexp_f32 v2, v2, v5
	v_log_f32_e32 v2, v2
	s_nop 0
	v_mul_f32_e32 v5, 0x3f317217, v2
	v_fma_f32 v5, v2, s2, -v5
	v_fmac_f32_e32 v5, 0x3377d1cf, v2
	v_fmac_f32_e32 v5, 0x3f317217, v2
	v_cmp_lt_f32_e64 s[4:5], |v2|, s3
	s_nop 1
	v_cndmask_b32_e64 v2, v2, v5, s[4:5]
	v_cndmask_b32_e32 v5, 0, v219, vcc
	v_sub_f32_e32 v2, v2, v5
	v_add_f32_e32 v4, v4, v2
	v_max_f32_e64 v2, -v3, 0
	v_mul_f32_e64 v3, |v3|, s92
	v_exp_f32_e32 v3, v3
	v_sub_f32_e32 v4, -0.5, v4
	v_mul_f32_e32 v4, 0x3fb8aa3b, v4
	v_exp_f32_e32 v4, v4
	v_add_f32_e32 v3, 1.0, v3
	v_cmp_gt_f32_e32 vcc, s96, v3
	v_mul_f32_e32 v4, 0xbfb8aa3b, v4
	s_nop 0
	v_cndmask_b32_e64 v5, 0, 32, vcc
	v_ldexp_f32 v3, v3, v5
	v_log_f32_e32 v3, v3
	v_exp_f32_e32 v4, v4
	v_mul_f32_e32 v5, 0x3f317217, v3
	v_fma_f32 v5, v3, s2, -v5
	v_fmac_f32_e32 v5, 0x3377d1cf, v3
	v_fmac_f32_e32 v5, 0x3f317217, v3
	v_cmp_lt_f32_e64 s[4:5], |v3|, s3
	s_nop 1
	v_cndmask_b32_e64 v3, v3, v5, s[4:5]
	v_cndmask_b32_e32 v5, 0, v219, vcc
	v_sub_f32_e32 v3, v3, v5
	v_add_f32_e32 v5, v2, v3
	v_lshl_add_u64 v[2:3], s[70:71], 0, v[0:1]
	global_store_dword v[2:3], v4, off
	v_sub_f32_e32 v2, -0.5, v5
	v_mul_f32_e32 v2, 0x3fb8aa3b, v2
	v_exp_f32_e32 v2, v2
	v_lshl_add_u64 v[0:1], s[78:79], 0, v[0:1]
	v_add_f32_e32 v3, v26, v35
	v_mul_f32_e32 v2, 0xbfb8aa3b, v2
	v_exp_f32_e32 v2, v2
	global_store_dword v[0:1], v2, off
	v_add_f32_e32 v2, v10, v33
	v_max_f32_e64 v4, -v2, 0
	v_mul_f32_e64 v2, |v2|, s92
	v_exp_f32_e32 v2, v2
	v_lshl_add_u64 v[0:1], v[98:99], 0, v[78:79]
	v_lshlrev_b64 v[0:1], 2, v[0:1]
	v_add_f32_e32 v2, 1.0, v2
	v_cmp_gt_f32_e32 vcc, s96, v2
	s_nop 1
	v_cndmask_b32_e64 v5, 0, 32, vcc
	v_ldexp_f32 v2, v2, v5
	v_log_f32_e32 v2, v2
	s_nop 0
	v_mul_f32_e32 v5, 0x3f317217, v2
	v_fma_f32 v5, v2, s2, -v5
	v_fmac_f32_e32 v5, 0x3377d1cf, v2
	v_fmac_f32_e32 v5, 0x3f317217, v2
	v_cmp_lt_f32_e64 s[4:5], |v2|, s3
	s_nop 1
	v_cndmask_b32_e64 v2, v2, v5, s[4:5]
	v_cndmask_b32_e32 v5, 0, v219, vcc
	v_sub_f32_e32 v2, v2, v5
	v_add_f32_e32 v4, v4, v2
	v_max_f32_e64 v2, -v3, 0
	v_mul_f32_e64 v3, |v3|, s92
	v_exp_f32_e32 v3, v3
	v_sub_f32_e32 v4, -0.5, v4
	v_mul_f32_e32 v4, 0x3fb8aa3b, v4
	v_exp_f32_e32 v4, v4
	v_add_f32_e32 v3, 1.0, v3
	v_cmp_gt_f32_e32 vcc, s96, v3
	v_mul_f32_e32 v4, 0xbfb8aa3b, v4
	s_nop 0
	v_cndmask_b32_e64 v5, 0, 32, vcc
	v_ldexp_f32 v3, v3, v5
	v_log_f32_e32 v3, v3
	v_exp_f32_e32 v4, v4
	v_mul_f32_e32 v5, 0x3f317217, v3
	v_fma_f32 v5, v3, s2, -v5
	v_fmac_f32_e32 v5, 0x3377d1cf, v3
	v_fmac_f32_e32 v5, 0x3f317217, v3
	v_cmp_lt_f32_e64 s[4:5], |v3|, s3
	s_nop 1
	v_cndmask_b32_e64 v3, v3, v5, s[4:5]
	v_cndmask_b32_e32 v5, 0, v219, vcc
	v_sub_f32_e32 v3, v3, v5
	v_add_f32_e32 v5, v2, v3
	v_lshl_add_u64 v[2:3], s[70:71], 0, v[0:1]
	global_store_dword v[2:3], v4, off
	v_sub_f32_e32 v2, -0.5, v5
	v_mul_f32_e32 v2, 0x3fb8aa3b, v2
	v_exp_f32_e32 v2, v2
	v_lshl_add_u64 v[0:1], s[78:79], 0, v[0:1]
	v_add_f32_e32 v3, v27, v35
	v_mul_f32_e32 v2, 0xbfb8aa3b, v2
	v_exp_f32_e32 v2, v2
	global_store_dword v[0:1], v2, off
	v_add_f32_e32 v2, v11, v33
	v_max_f32_e64 v4, -v2, 0
	v_mul_f32_e64 v2, |v2|, s92
	v_exp_f32_e32 v2, v2
	v_lshl_add_u64 v[0:1], v[100:101], 0, v[78:79]
	v_lshlrev_b64 v[0:1], 2, v[0:1]
	v_add_f32_e32 v2, 1.0, v2
	v_cmp_gt_f32_e32 vcc, s96, v2
	s_nop 1
	v_cndmask_b32_e64 v5, 0, 32, vcc
	v_ldexp_f32 v2, v2, v5
	v_log_f32_e32 v2, v2
	s_nop 0
	v_mul_f32_e32 v5, 0x3f317217, v2
	v_fma_f32 v5, v2, s2, -v5
	v_fmac_f32_e32 v5, 0x3377d1cf, v2
	v_fmac_f32_e32 v5, 0x3f317217, v2
	v_cmp_lt_f32_e64 s[4:5], |v2|, s3
	s_nop 1
	v_cndmask_b32_e64 v2, v2, v5, s[4:5]
	v_cndmask_b32_e32 v5, 0, v219, vcc
	v_sub_f32_e32 v2, v2, v5
	v_add_f32_e32 v4, v4, v2
	v_max_f32_e64 v2, -v3, 0
	v_mul_f32_e64 v3, |v3|, s92
	v_exp_f32_e32 v3, v3
	v_sub_f32_e32 v4, -0.5, v4
	v_mul_f32_e32 v4, 0x3fb8aa3b, v4
	v_exp_f32_e32 v4, v4
	v_add_f32_e32 v3, 1.0, v3
	v_cmp_gt_f32_e32 vcc, s96, v3
	v_mul_f32_e32 v4, 0xbfb8aa3b, v4
	s_nop 0
	v_cndmask_b32_e64 v5, 0, 32, vcc
	v_ldexp_f32 v3, v3, v5
	v_log_f32_e32 v3, v3
	v_exp_f32_e32 v4, v4
	v_mul_f32_e32 v5, 0x3f317217, v3
	v_fma_f32 v5, v3, s2, -v5
	v_fmac_f32_e32 v5, 0x3377d1cf, v3
	v_fmac_f32_e32 v5, 0x3f317217, v3
	v_cmp_lt_f32_e64 s[4:5], |v3|, s3
	s_nop 1
	v_cndmask_b32_e64 v3, v3, v5, s[4:5]
	v_cndmask_b32_e32 v5, 0, v219, vcc
	v_sub_f32_e32 v3, v3, v5
	v_add_f32_e32 v5, v2, v3
	v_lshl_add_u64 v[2:3], s[70:71], 0, v[0:1]
	global_store_dword v[2:3], v4, off
	v_sub_f32_e32 v2, -0.5, v5
	v_mul_f32_e32 v2, 0x3fb8aa3b, v2
	v_exp_f32_e32 v2, v2
	v_lshl_add_u64 v[0:1], s[78:79], 0, v[0:1]
	v_add_f32_e32 v3, v28, v35
	v_mul_f32_e32 v2, 0xbfb8aa3b, v2
	v_exp_f32_e32 v2, v2
	global_store_dword v[0:1], v2, off
	v_add_f32_e32 v2, v12, v33
	v_max_f32_e64 v4, -v2, 0
	v_mul_f32_e64 v2, |v2|, s92
	v_exp_f32_e32 v2, v2
	v_lshl_add_u64 v[0:1], v[88:89], 0, v[78:79]
	v_lshlrev_b64 v[0:1], 2, v[0:1]
	v_add_f32_e32 v2, 1.0, v2
	v_cmp_gt_f32_e32 vcc, s96, v2
	s_nop 1
	v_cndmask_b32_e64 v5, 0, 32, vcc
	v_ldexp_f32 v2, v2, v5
	v_log_f32_e32 v2, v2
	s_nop 0
	v_mul_f32_e32 v5, 0x3f317217, v2
	v_fma_f32 v5, v2, s2, -v5
	v_fmac_f32_e32 v5, 0x3377d1cf, v2
	v_fmac_f32_e32 v5, 0x3f317217, v2
	v_cmp_lt_f32_e64 s[4:5], |v2|, s3
	s_nop 1
	v_cndmask_b32_e64 v2, v2, v5, s[4:5]
	v_cndmask_b32_e32 v5, 0, v219, vcc
	v_sub_f32_e32 v2, v2, v5
	v_add_f32_e32 v4, v4, v2
	v_max_f32_e64 v2, -v3, 0
	v_mul_f32_e64 v3, |v3|, s92
	v_exp_f32_e32 v3, v3
	v_sub_f32_e32 v4, -0.5, v4
	v_mul_f32_e32 v4, 0x3fb8aa3b, v4
	v_exp_f32_e32 v4, v4
	v_add_f32_e32 v3, 1.0, v3
	v_cmp_gt_f32_e32 vcc, s96, v3
	v_mul_f32_e32 v4, 0xbfb8aa3b, v4
	s_nop 0
	v_cndmask_b32_e64 v5, 0, 32, vcc
	v_ldexp_f32 v3, v3, v5
	v_log_f32_e32 v3, v3
	v_exp_f32_e32 v4, v4
	v_mul_f32_e32 v5, 0x3f317217, v3
	v_fma_f32 v5, v3, s2, -v5
	v_fmac_f32_e32 v5, 0x3377d1cf, v3
	v_fmac_f32_e32 v5, 0x3f317217, v3
	v_cmp_lt_f32_e64 s[4:5], |v3|, s3
	s_nop 1
	v_cndmask_b32_e64 v3, v3, v5, s[4:5]
	v_cndmask_b32_e32 v5, 0, v219, vcc
	v_sub_f32_e32 v3, v3, v5
	v_add_f32_e32 v5, v2, v3
	v_lshl_add_u64 v[2:3], s[70:71], 0, v[0:1]
	global_store_dword v[2:3], v4, off
	v_sub_f32_e32 v2, -0.5, v5
	v_mul_f32_e32 v2, 0x3fb8aa3b, v2
	v_exp_f32_e32 v2, v2
	v_lshl_add_u64 v[0:1], s[78:79], 0, v[0:1]
	v_add_f32_e32 v3, v29, v35
	v_mul_f32_e32 v2, 0xbfb8aa3b, v2
	v_exp_f32_e32 v2, v2
	global_store_dword v[0:1], v2, off
	v_add_f32_e32 v2, v13, v33
	v_max_f32_e64 v4, -v2, 0
	v_mul_f32_e64 v2, |v2|, s92
	v_exp_f32_e32 v2, v2
	v_lshl_add_u64 v[0:1], v[82:83], 0, v[78:79]
	v_lshlrev_b64 v[0:1], 2, v[0:1]
	v_add_f32_e32 v2, 1.0, v2
	v_cmp_gt_f32_e32 vcc, s96, v2
	s_nop 1
	v_cndmask_b32_e64 v5, 0, 32, vcc
	v_ldexp_f32 v2, v2, v5
	v_log_f32_e32 v2, v2
	s_nop 0
	v_mul_f32_e32 v5, 0x3f317217, v2
	v_fma_f32 v5, v2, s2, -v5
	v_fmac_f32_e32 v5, 0x3377d1cf, v2
	v_fmac_f32_e32 v5, 0x3f317217, v2
	v_cmp_lt_f32_e64 s[4:5], |v2|, s3
	s_nop 1
	v_cndmask_b32_e64 v2, v2, v5, s[4:5]
	v_cndmask_b32_e32 v5, 0, v219, vcc
	v_sub_f32_e32 v2, v2, v5
	v_add_f32_e32 v4, v4, v2
	v_max_f32_e64 v2, -v3, 0
	v_mul_f32_e64 v3, |v3|, s92
	v_exp_f32_e32 v3, v3
	v_sub_f32_e32 v4, -0.5, v4
	v_mul_f32_e32 v4, 0x3fb8aa3b, v4
	v_exp_f32_e32 v4, v4
	v_add_f32_e32 v3, 1.0, v3
	v_cmp_gt_f32_e32 vcc, s96, v3
	v_mul_f32_e32 v4, 0xbfb8aa3b, v4
	s_nop 0
	v_cndmask_b32_e64 v5, 0, 32, vcc
	v_ldexp_f32 v3, v3, v5
	v_log_f32_e32 v3, v3
	v_exp_f32_e32 v4, v4
	v_mul_f32_e32 v5, 0x3f317217, v3
	v_fma_f32 v5, v3, s2, -v5
	v_fmac_f32_e32 v5, 0x3377d1cf, v3
	v_fmac_f32_e32 v5, 0x3f317217, v3
	v_cmp_lt_f32_e64 s[4:5], |v3|, s3
	s_nop 1
	v_cndmask_b32_e64 v3, v3, v5, s[4:5]
	v_cndmask_b32_e32 v5, 0, v219, vcc
	v_sub_f32_e32 v3, v3, v5
	v_add_f32_e32 v5, v2, v3
	v_lshl_add_u64 v[2:3], s[70:71], 0, v[0:1]
	global_store_dword v[2:3], v4, off
	v_sub_f32_e32 v2, -0.5, v5
	v_mul_f32_e32 v2, 0x3fb8aa3b, v2
	v_exp_f32_e32 v2, v2
	v_lshl_add_u64 v[0:1], s[78:79], 0, v[0:1]
	v_add_f32_e32 v3, v30, v35
	v_mul_f32_e32 v2, 0xbfb8aa3b, v2
	v_exp_f32_e32 v2, v2
	global_store_dword v[0:1], v2, off
	v_add_f32_e32 v2, v14, v33
	v_max_f32_e64 v4, -v2, 0
	v_mul_f32_e64 v2, |v2|, s92
	v_exp_f32_e32 v2, v2
	v_lshl_add_u64 v[0:1], v[80:81], 0, v[78:79]
	v_lshlrev_b64 v[0:1], 2, v[0:1]
	v_add_f32_e32 v2, 1.0, v2
	v_cmp_gt_f32_e32 vcc, s96, v2
	s_nop 1
	v_cndmask_b32_e64 v5, 0, 32, vcc
	v_ldexp_f32 v2, v2, v5
	v_log_f32_e32 v2, v2
	s_nop 0
	v_mul_f32_e32 v5, 0x3f317217, v2
	v_fma_f32 v5, v2, s2, -v5
	v_fmac_f32_e32 v5, 0x3377d1cf, v2
	v_fmac_f32_e32 v5, 0x3f317217, v2
	v_cmp_lt_f32_e64 s[4:5], |v2|, s3
	s_nop 1
	v_cndmask_b32_e64 v2, v2, v5, s[4:5]
	v_cndmask_b32_e32 v5, 0, v219, vcc
	v_sub_f32_e32 v2, v2, v5
	v_add_f32_e32 v4, v4, v2
	v_max_f32_e64 v2, -v3, 0
	v_mul_f32_e64 v3, |v3|, s92
	v_exp_f32_e32 v3, v3
	v_sub_f32_e32 v4, -0.5, v4
	v_mul_f32_e32 v4, 0x3fb8aa3b, v4
	v_exp_f32_e32 v4, v4
	v_add_f32_e32 v3, 1.0, v3
	v_cmp_gt_f32_e32 vcc, s96, v3
	v_mul_f32_e32 v4, 0xbfb8aa3b, v4
	s_nop 0
	v_cndmask_b32_e64 v5, 0, 32, vcc
	v_ldexp_f32 v3, v3, v5
	v_log_f32_e32 v3, v3
	v_exp_f32_e32 v4, v4
	v_mul_f32_e32 v5, 0x3f317217, v3
	v_fma_f32 v5, v3, s2, -v5
	v_fmac_f32_e32 v5, 0x3377d1cf, v3
	v_fmac_f32_e32 v5, 0x3f317217, v3
	v_cmp_lt_f32_e64 s[4:5], |v3|, s3
	s_nop 1
	v_cndmask_b32_e64 v3, v3, v5, s[4:5]
	v_cndmask_b32_e32 v5, 0, v219, vcc
	v_sub_f32_e32 v3, v3, v5
	v_add_f32_e32 v5, v2, v3
	v_lshl_add_u64 v[2:3], s[70:71], 0, v[0:1]
	global_store_dword v[2:3], v4, off
	v_sub_f32_e32 v2, -0.5, v5
	v_mul_f32_e32 v2, 0x3fb8aa3b, v2
	v_exp_f32_e32 v2, v2
	v_lshl_add_u64 v[0:1], s[78:79], 0, v[0:1]
	v_add_f32_e32 v3, v31, v35
	v_mul_f32_e32 v2, 0xbfb8aa3b, v2
	v_exp_f32_e32 v2, v2
	global_store_dword v[0:1], v2, off
	v_add_f32_e32 v2, v15, v33
	v_max_f32_e64 v4, -v2, 0
	v_mul_f32_e64 v2, |v2|, s92
	v_exp_f32_e32 v2, v2
	v_lshl_add_u64 v[0:1], v[76:77], 0, v[78:79]
	v_lshlrev_b64 v[0:1], 2, v[0:1]
	v_mov_b32_e32 v78, v32
	v_add_f32_e32 v2, 1.0, v2
	v_cmp_gt_f32_e32 vcc, s96, v2
	s_nop 1
	v_cndmask_b32_e64 v5, 0, 32, vcc
	v_ldexp_f32 v2, v2, v5
	v_log_f32_e32 v2, v2
	s_nop 0
	v_mul_f32_e32 v5, 0x3f317217, v2
	v_fma_f32 v5, v2, s2, -v5
	v_fmac_f32_e32 v5, 0x3377d1cf, v2
	v_fmac_f32_e32 v5, 0x3f317217, v2
	v_cmp_lt_f32_e64 s[4:5], |v2|, s3
	s_nop 1
	v_cndmask_b32_e64 v2, v2, v5, s[4:5]
	v_cndmask_b32_e32 v5, 0, v219, vcc
	v_sub_f32_e32 v2, v2, v5
	v_add_f32_e32 v4, v4, v2
	v_max_f32_e64 v2, -v3, 0
	v_mul_f32_e64 v3, |v3|, s92
	v_exp_f32_e32 v3, v3
	v_sub_f32_e32 v4, -0.5, v4
	v_mul_f32_e32 v4, 0x3fb8aa3b, v4
	v_exp_f32_e32 v4, v4
	v_add_f32_e32 v3, 1.0, v3
	v_cmp_gt_f32_e32 vcc, s96, v3
	v_mul_f32_e32 v4, 0xbfb8aa3b, v4
	s_nop 0
	v_cndmask_b32_e64 v5, 0, 32, vcc
	v_ldexp_f32 v3, v3, v5
	v_log_f32_e32 v3, v3
	v_exp_f32_e32 v4, v4
	v_mul_f32_e32 v5, 0x3f317217, v3
	v_fma_f32 v5, v3, s2, -v5
	v_fmac_f32_e32 v5, 0x3377d1cf, v3
	v_fmac_f32_e32 v5, 0x3f317217, v3
	v_cmp_lt_f32_e64 s[4:5], |v3|, s3
	s_nop 1
	v_cndmask_b32_e64 v3, v3, v5, s[4:5]
	v_cndmask_b32_e32 v5, 0, v219, vcc
	v_sub_f32_e32 v3, v3, v5
	v_add_f32_e32 v5, v2, v3
	v_lshl_add_u64 v[2:3], s[70:71], 0, v[0:1]
	global_store_dword v[2:3], v4, off
	v_sub_f32_e32 v2, -0.5, v5
	v_mul_f32_e32 v2, 0x3fb8aa3b, v2
	v_exp_f32_e32 v2, v2
	v_lshl_add_u64 v[0:1], s[78:79], 0, v[0:1]
	v_mul_f32_e32 v2, 0xbfb8aa3b, v2
	v_exp_f32_e32 v2, v2
	global_store_dword v[0:1], v2, off
	s_nop 0
	v_ashrrev_i32_e32 v79, 31, v78
	v_lshlrev_b64 v[0:1], 7, v[78:79]
	v_lshl_add_u64 v[0:1], s[74:75], 0, v[0:1]
	v_lshl_add_u64 v[118:119], v[0:1], 0, v[178:179]
	v_add_co_u32_e32 v4, vcc, s6, v118
	global_load_dwordx4 v[124:127], v[118:119], off
	s_nop 0
	v_addc_co_u32_e32 v5, vcc, 0, v119, vcc
	global_load_dwordx4 v[128:131], v[4:5], off
	v_lshl_add_u64 v[120:121], v[118:119], 0, s[8:9]
	ds_read_b128 v[20:23], v104
	ds_read_b128 v[106:109], v104 offset:32
	global_load_dwordx4 v[132:135], v[118:119], off offset:32
	global_load_dwordx4 v[136:139], v[120:121], off offset:32
	global_load_dwordx4 v[140:143], v[118:119], off offset:64
	global_load_dwordx4 v[144:147], v[120:121], off offset:64
	global_load_dwordx4 v[152:155], v[118:119], off offset:96
	global_load_dwordx4 v[160:163], v[120:121], off offset:96
	s_waitcnt vmcnt(4) lgkmcnt(0)
	v_mfma_f32_32x32x16_bf16 v[0:15], v[20:23], v[124:127], 0
	v_lshl_add_u64 v[74:75], v[74:75], 0, v[78:79]
	v_lshlrev_b64 v[74:75], 2, v[74:75]
	v_lshl_add_u64 v[72:73], v[72:73], 0, v[78:79]
	s_movk_i32 s6, 0x4000
	v_mfma_f32_32x32x16_bf16 v[16:31], v[20:23], v[128:131], 0
	v_mfma_f32_32x32x16_bf16 v[0:15], v[106:109], v[132:135], v[0:15]
	v_mfma_f32_32x32x16_bf16 v[16:31], v[106:109], v[136:139], v[16:31]
	ds_read_b128 v[106:109], v104 offset:64
	s_waitcnt vmcnt(2) lgkmcnt(0)
	v_mfma_f32_32x32x16_bf16 v[0:15], v[106:109], v[140:143], v[0:15]
	v_mfma_f32_32x32x16_bf16 v[16:31], v[106:109], v[144:147], v[16:31]
	ds_read_b128 v[106:109], v104 offset:96
	s_waitcnt vmcnt(0) lgkmcnt(0)
	v_mfma_f32_32x32x16_bf16 v[0:15], v[106:109], v[152:155], v[0:15]
	v_mfma_f32_32x32x16_bf16 v[16:31], v[106:109], v[160:163], v[16:31]
	v_lshl_add_u64 v[106:107], v[78:79], 2, s[10:11]
	global_load_dword v33, v[106:107], off
	global_load_dword v35, v[106:107], off offset:2048
	s_waitcnt vmcnt(1)
	s_nop 6
	v_add_f32_e32 v0, v0, v33
	v_max_f32_e64 v106, -v0, 0
	v_mul_f32_e64 v0, |v0|, s92
	v_exp_f32_e32 v0, v0
	s_waitcnt vmcnt(0)
	v_add_f32_e32 v16, v16, v35
	v_add_f32_e32 v2, v2, v33
	v_add_f32_e32 v0, 1.0, v0
	v_cmp_gt_f32_e32 vcc, s96, v0
	s_nop 1
	v_cndmask_b32_e64 v107, 0, 32, vcc
	v_ldexp_f32 v0, v0, v107
	v_log_f32_e32 v0, v0
	s_nop 0
	v_mul_f32_e32 v107, 0x3f317217, v0
	v_fma_f32 v107, v0, s2, -v107
	v_fmac_f32_e32 v107, 0x3377d1cf, v0
	v_fmac_f32_e32 v107, 0x3f317217, v0
	v_cmp_lt_f32_e64 s[4:5], |v0|, s3
	s_nop 1
	v_cndmask_b32_e64 v0, v0, v107, s[4:5]
	v_cndmask_b32_e32 v107, 0, v219, vcc
	v_sub_f32_e32 v0, v0, v107
	v_add_f32_e32 v0, v106, v0
	v_max_f32_e64 v106, -v16, 0
	v_mul_f32_e64 v16, |v16|, s92
	v_exp_f32_e32 v16, v16
	v_sub_f32_e32 v0, -0.5, v0
	v_mul_f32_e32 v0, 0x3fb8aa3b, v0
	v_exp_f32_e32 v0, v0
	v_add_f32_e32 v16, 1.0, v16
	v_cmp_gt_f32_e32 vcc, s96, v16
	v_mul_f32_e32 v0, 0xbfb8aa3b, v0
	s_nop 0
	v_cndmask_b32_e64 v107, 0, 32, vcc
	v_ldexp_f32 v16, v16, v107
	v_log_f32_e32 v16, v16
	v_exp_f32_e32 v0, v0
	v_mul_f32_e32 v107, 0x3f317217, v16
	v_fma_f32 v107, v16, s2, -v107
	v_fmac_f32_e32 v107, 0x3377d1cf, v16
	v_fmac_f32_e32 v107, 0x3f317217, v16
	v_cmp_lt_f32_e64 s[4:5], |v16|, s3
	s_nop 1
	v_cndmask_b32_e64 v16, v16, v107, s[4:5]
	v_cndmask_b32_e32 v107, 0, v219, vcc
	v_sub_f32_e32 v16, v16, v107
	v_add_f32_e32 v16, v106, v16
	v_lshl_add_u64 v[106:107], s[70:71], 0, v[74:75]
	global_store_dword v[106:107], v0, off
	v_sub_f32_e32 v0, -0.5, v16
	v_mul_f32_e32 v0, 0x3fb8aa3b, v0
	v_exp_f32_e32 v0, v0
	v_lshl_add_u64 v[74:75], s[78:79], 0, v[74:75]
	v_mul_f32_e32 v0, 0xbfb8aa3b, v0
	v_exp_f32_e32 v0, v0
	global_store_dword v[74:75], v0, off
	v_add_f32_e32 v0, v1, v33
	v_max_f32_e64 v16, -v0, 0
	v_mul_f32_e64 v0, |v0|, s92
	v_exp_f32_e32 v0, v0
	v_add_f32_e32 v1, v17, v35
	v_add_f32_e32 v0, 1.0, v0
	v_cmp_gt_f32_e32 vcc, s96, v0
	s_nop 1
	v_cndmask_b32_e64 v17, 0, 32, vcc
	v_ldexp_f32 v0, v0, v17
	v_log_f32_e32 v0, v0
	s_nop 0
	v_mul_f32_e32 v17, 0x3f317217, v0
	v_fma_f32 v17, v0, s2, -v17
	v_fmac_f32_e32 v17, 0x3377d1cf, v0
	v_fmac_f32_e32 v17, 0x3f317217, v0
	v_cmp_lt_f32_e64 s[4:5], |v0|, s3
	s_nop 1
	v_cndmask_b32_e64 v0, v0, v17, s[4:5]
	v_cndmask_b32_e32 v17, 0, v219, vcc
	v_sub_f32_e32 v0, v0, v17
	v_add_f32_e32 v74, v16, v0
	v_max_f32_e64 v0, -v1, 0
	v_mul_f32_e64 v1, |v1|, s92
	v_exp_f32_e32 v1, v1
	s_nop 0
	v_add_f32_e32 v1, 1.0, v1
	v_cmp_gt_f32_e32 vcc, s96, v1
	s_nop 1
	v_cndmask_b32_e64 v16, 0, 32, vcc
	v_ldexp_f32 v1, v1, v16
	v_log_f32_e32 v1, v1
	s_nop 0
	v_mul_f32_e32 v16, 0x3f317217, v1
	v_fma_f32 v16, v1, s2, -v16
	v_fmac_f32_e32 v16, 0x3377d1cf, v1
	v_fmac_f32_e32 v16, 0x3f317217, v1
	v_cmp_lt_f32_e64 s[4:5], |v1|, s3
	s_nop 1
	v_cndmask_b32_e64 v1, v1, v16, s[4:5]
	v_cndmask_b32_e32 v16, 0, v219, vcc
	v_sub_f32_e32 v1, v1, v16
	v_add_f32_e32 v75, v0, v1
	v_lshlrev_b64 v[0:1], 2, v[72:73]
	v_sub_f32_e32 v72, -0.5, v74
	v_mul_f32_e32 v72, 0x3fb8aa3b, v72
	v_exp_f32_e32 v72, v72
	v_lshl_add_u64 v[16:17], s[70:71], 0, v[0:1]
	v_lshl_add_u64 v[0:1], s[78:79], 0, v[0:1]
	v_mul_f32_e32 v72, 0xbfb8aa3b, v72
	v_exp_f32_e32 v72, v72
	global_store_dword v[16:17], v72, off
	v_sub_f32_e32 v16, -0.5, v75
	v_mul_f32_e32 v16, 0x3fb8aa3b, v16
	v_exp_f32_e32 v16, v16
	v_max_f32_e64 v17, -v2, 0
	v_mul_f32_e64 v2, |v2|, s92
	v_exp_f32_e32 v2, v2
	v_mul_f32_e32 v16, 0xbfb8aa3b, v16
	v_exp_f32_e32 v16, v16
	v_add_f32_e32 v2, 1.0, v2
	v_cmp_gt_f32_e32 vcc, s96, v2
	global_store_dword v[0:1], v16, off
	v_add_f32_e32 v16, v18, v35
	v_cndmask_b32_e64 v18, 0, 32, vcc
	v_ldexp_f32 v2, v2, v18
	v_log_f32_e32 v2, v2
	v_lshl_add_u64 v[0:1], v[70:71], 0, v[78:79]
	v_lshlrev_b64 v[0:1], 2, v[0:1]
	v_mul_f32_e32 v18, 0x3f317217, v2
	v_fma_f32 v18, v2, s2, -v18
	v_fmac_f32_e32 v18, 0x3377d1cf, v2
	v_fmac_f32_e32 v18, 0x3f317217, v2
	v_cmp_lt_f32_e64 s[4:5], |v2|, s3
	s_nop 1
	v_cndmask_b32_e64 v2, v2, v18, s[4:5]
	v_cndmask_b32_e32 v18, 0, v219, vcc
	v_sub_f32_e32 v2, v2, v18
	v_add_f32_e32 v2, v17, v2
	v_max_f32_e64 v17, -v16, 0
	v_mul_f32_e64 v16, |v16|, s92
	v_exp_f32_e32 v16, v16
	v_sub_f32_e32 v2, -0.5, v2
	v_mul_f32_e32 v2, 0x3fb8aa3b, v2
	v_exp_f32_e32 v2, v2
	v_add_f32_e32 v16, 1.0, v16
	v_cmp_gt_f32_e32 vcc, s96, v16
	v_mul_f32_e32 v2, 0xbfb8aa3b, v2
	s_nop 0
	v_cndmask_b32_e64 v18, 0, 32, vcc
	v_ldexp_f32 v16, v16, v18
	v_log_f32_e32 v16, v16
	v_exp_f32_e32 v2, v2
	v_mul_f32_e32 v18, 0x3f317217, v16
	v_fma_f32 v18, v16, s2, -v18
	v_fmac_f32_e32 v18, 0x3377d1cf, v16
	v_fmac_f32_e32 v18, 0x3f317217, v16
	v_cmp_lt_f32_e64 s[4:5], |v16|, s3
	s_nop 1
	v_cndmask_b32_e64 v16, v16, v18, s[4:5]
	v_cndmask_b32_e32 v18, 0, v219, vcc
	v_sub_f32_e32 v16, v16, v18
	v_add_f32_e32 v18, v17, v16
	v_lshl_add_u64 v[16:17], s[70:71], 0, v[0:1]
	global_store_dword v[16:17], v2, off
	v_sub_f32_e32 v2, -0.5, v18
	v_mul_f32_e32 v2, 0x3fb8aa3b, v2
	v_exp_f32_e32 v2, v2
	v_lshl_add_u64 v[0:1], s[78:79], 0, v[0:1]
	v_mul_f32_e32 v2, 0xbfb8aa3b, v2
	v_exp_f32_e32 v2, v2
	global_store_dword v[0:1], v2, off
	v_add_f32_e32 v2, v3, v33
	v_max_f32_e64 v16, -v2, 0
	v_mul_f32_e64 v2, |v2|, s92
	v_exp_f32_e32 v2, v2
	v_add_f32_e32 v3, v19, v35
	v_lshl_add_u64 v[0:1], v[68:69], 0, v[78:79]
	v_lshlrev_b64 v[0:1], 2, v[0:1]
	v_add_f32_e32 v2, 1.0, v2
	v_cmp_gt_f32_e32 vcc, s96, v2
	s_nop 1
	v_cndmask_b32_e64 v17, 0, 32, vcc
	v_ldexp_f32 v2, v2, v17
	v_log_f32_e32 v2, v2
	s_nop 0
	v_mul_f32_e32 v17, 0x3f317217, v2
	v_fma_f32 v17, v2, s2, -v17
	v_fmac_f32_e32 v17, 0x3377d1cf, v2
	v_fmac_f32_e32 v17, 0x3f317217, v2
	v_cmp_lt_f32_e64 s[4:5], |v2|, s3
	s_nop 1
	v_cndmask_b32_e64 v2, v2, v17, s[4:5]
	v_cndmask_b32_e32 v17, 0, v219, vcc
	v_sub_f32_e32 v2, v2, v17
	v_add_f32_e32 v16, v16, v2
	v_max_f32_e64 v2, -v3, 0
	v_mul_f32_e64 v3, |v3|, s92
	v_exp_f32_e32 v3, v3
	v_sub_f32_e32 v16, -0.5, v16
	v_mul_f32_e32 v16, 0x3fb8aa3b, v16
	v_exp_f32_e32 v16, v16
	v_add_f32_e32 v3, 1.0, v3
	v_cmp_gt_f32_e32 vcc, s96, v3
	v_mul_f32_e32 v16, 0xbfb8aa3b, v16
	s_nop 0
	v_cndmask_b32_e64 v17, 0, 32, vcc
	v_ldexp_f32 v3, v3, v17
	v_log_f32_e32 v3, v3
	v_exp_f32_e32 v16, v16
	v_mul_f32_e32 v17, 0x3f317217, v3
	v_fma_f32 v17, v3, s2, -v17
	v_fmac_f32_e32 v17, 0x3377d1cf, v3
	v_fmac_f32_e32 v17, 0x3f317217, v3
	v_cmp_lt_f32_e64 s[4:5], |v3|, s3
	s_nop 1
	v_cndmask_b32_e64 v3, v3, v17, s[4:5]
	v_cndmask_b32_e32 v17, 0, v219, vcc
	v_sub_f32_e32 v3, v3, v17
	v_add_f32_e32 v17, v2, v3
	v_lshl_add_u64 v[2:3], s[70:71], 0, v[0:1]
	global_store_dword v[2:3], v16, off
	v_sub_f32_e32 v2, -0.5, v17
	v_mul_f32_e32 v2, 0x3fb8aa3b, v2
	v_exp_f32_e32 v2, v2
	v_lshl_add_u64 v[0:1], s[78:79], 0, v[0:1]
	v_add_f32_e32 v3, v20, v35
	v_mul_f32_e32 v2, 0xbfb8aa3b, v2
	v_exp_f32_e32 v2, v2
	global_store_dword v[0:1], v2, off
	v_add_f32_e32 v2, v4, v33
	v_max_f32_e64 v4, -v2, 0
	v_mul_f32_e64 v2, |v2|, s92
	v_exp_f32_e32 v2, v2
	v_lshl_add_u64 v[0:1], v[84:85], 0, v[78:79]
	v_lshlrev_b64 v[0:1], 2, v[0:1]
	v_add_f32_e32 v2, 1.0, v2
	v_cmp_gt_f32_e32 vcc, s96, v2
	s_nop 1
	v_cndmask_b32_e64 v16, 0, 32, vcc
	v_ldexp_f32 v2, v2, v16
	v_log_f32_e32 v2, v2
	s_nop 0
	v_mul_f32_e32 v16, 0x3f317217, v2
	v_fma_f32 v16, v2, s2, -v16
	v_fmac_f32_e32 v16, 0x3377d1cf, v2
	v_fmac_f32_e32 v16, 0x3f317217, v2
	v_cmp_lt_f32_e64 s[4:5], |v2|, s3
	s_nop 1
	v_cndmask_b32_e64 v2, v2, v16, s[4:5]
	v_cndmask_b32_e32 v16, 0, v219, vcc
	v_sub_f32_e32 v2, v2, v16
	v_add_f32_e32 v4, v4, v2
	v_max_f32_e64 v2, -v3, 0
	v_mul_f32_e64 v3, |v3|, s92
	v_exp_f32_e32 v3, v3
	v_sub_f32_e32 v4, -0.5, v4
	v_mul_f32_e32 v4, 0x3fb8aa3b, v4
	v_exp_f32_e32 v4, v4
	v_add_f32_e32 v3, 1.0, v3
	v_cmp_gt_f32_e32 vcc, s96, v3
	v_mul_f32_e32 v4, 0xbfb8aa3b, v4
	s_nop 0
	v_cndmask_b32_e64 v16, 0, 32, vcc
	v_ldexp_f32 v3, v3, v16
	v_log_f32_e32 v3, v3
	v_exp_f32_e32 v4, v4
	v_mul_f32_e32 v16, 0x3f317217, v3
	v_fma_f32 v16, v3, s2, -v16
	v_fmac_f32_e32 v16, 0x3377d1cf, v3
	v_fmac_f32_e32 v16, 0x3f317217, v3
	v_cmp_lt_f32_e64 s[4:5], |v3|, s3
	s_nop 1
	v_cndmask_b32_e64 v3, v3, v16, s[4:5]
	v_cndmask_b32_e32 v16, 0, v219, vcc
	v_sub_f32_e32 v3, v3, v16
	v_add_f32_e32 v16, v2, v3
	v_lshl_add_u64 v[2:3], s[70:71], 0, v[0:1]
	global_store_dword v[2:3], v4, off
	v_sub_f32_e32 v2, -0.5, v16
	v_mul_f32_e32 v2, 0x3fb8aa3b, v2
	v_exp_f32_e32 v2, v2
	v_lshl_add_u64 v[0:1], s[78:79], 0, v[0:1]
	v_add_f32_e32 v3, v21, v35
	v_mul_f32_e32 v2, 0xbfb8aa3b, v2
	v_exp_f32_e32 v2, v2
	global_store_dword v[0:1], v2, off
	v_add_f32_e32 v2, v5, v33
	v_max_f32_e64 v4, -v2, 0
	v_mul_f32_e64 v2, |v2|, s92
	v_exp_f32_e32 v2, v2
	v_lshl_add_u64 v[0:1], v[86:87], 0, v[78:79]
	v_lshlrev_b64 v[0:1], 2, v[0:1]
	v_add_f32_e32 v2, 1.0, v2
	v_cmp_gt_f32_e32 vcc, s96, v2
	s_nop 1
	v_cndmask_b32_e64 v5, 0, 32, vcc
	v_ldexp_f32 v2, v2, v5
	v_log_f32_e32 v2, v2
	s_nop 0
	v_mul_f32_e32 v5, 0x3f317217, v2
	v_fma_f32 v5, v2, s2, -v5
	v_fmac_f32_e32 v5, 0x3377d1cf, v2
	v_fmac_f32_e32 v5, 0x3f317217, v2
	v_cmp_lt_f32_e64 s[4:5], |v2|, s3
	s_nop 1
	v_cndmask_b32_e64 v2, v2, v5, s[4:5]
	v_cndmask_b32_e32 v5, 0, v219, vcc
	v_sub_f32_e32 v2, v2, v5
	v_add_f32_e32 v4, v4, v2
	v_max_f32_e64 v2, -v3, 0
	v_mul_f32_e64 v3, |v3|, s92
	v_exp_f32_e32 v3, v3
	v_sub_f32_e32 v4, -0.5, v4
	v_mul_f32_e32 v4, 0x3fb8aa3b, v4
	v_exp_f32_e32 v4, v4
	v_add_f32_e32 v3, 1.0, v3
	v_cmp_gt_f32_e32 vcc, s96, v3
	v_mul_f32_e32 v4, 0xbfb8aa3b, v4
	s_nop 0
	v_cndmask_b32_e64 v5, 0, 32, vcc
	v_ldexp_f32 v3, v3, v5
	v_log_f32_e32 v3, v3
	v_exp_f32_e32 v4, v4
	v_mul_f32_e32 v5, 0x3f317217, v3
	v_fma_f32 v5, v3, s2, -v5
	v_fmac_f32_e32 v5, 0x3377d1cf, v3
	v_fmac_f32_e32 v5, 0x3f317217, v3
	v_cmp_lt_f32_e64 s[4:5], |v3|, s3
	s_nop 1
	v_cndmask_b32_e64 v3, v3, v5, s[4:5]
	v_cndmask_b32_e32 v5, 0, v219, vcc
	v_sub_f32_e32 v3, v3, v5
	v_add_f32_e32 v5, v2, v3
	v_lshl_add_u64 v[2:3], s[70:71], 0, v[0:1]
	global_store_dword v[2:3], v4, off
	v_sub_f32_e32 v2, -0.5, v5
	v_mul_f32_e32 v2, 0x3fb8aa3b, v2
	v_exp_f32_e32 v2, v2
	v_lshl_add_u64 v[0:1], s[78:79], 0, v[0:1]
	v_add_f32_e32 v3, v22, v35
	v_mul_f32_e32 v2, 0xbfb8aa3b, v2
	v_exp_f32_e32 v2, v2
	global_store_dword v[0:1], v2, off
	v_add_f32_e32 v2, v6, v33
	v_max_f32_e64 v4, -v2, 0
	v_mul_f32_e64 v2, |v2|, s92
	v_exp_f32_e32 v2, v2
	v_lshl_add_u64 v[0:1], v[90:91], 0, v[78:79]
	v_lshlrev_b64 v[0:1], 2, v[0:1]
	v_add_f32_e32 v2, 1.0, v2
	v_cmp_gt_f32_e32 vcc, s96, v2
	s_nop 1
	v_cndmask_b32_e64 v5, 0, 32, vcc
	v_ldexp_f32 v2, v2, v5
	v_log_f32_e32 v2, v2
	s_nop 0
	v_mul_f32_e32 v5, 0x3f317217, v2
	v_fma_f32 v5, v2, s2, -v5
	v_fmac_f32_e32 v5, 0x3377d1cf, v2
	v_fmac_f32_e32 v5, 0x3f317217, v2
	v_cmp_lt_f32_e64 s[4:5], |v2|, s3
	s_nop 1
	v_cndmask_b32_e64 v2, v2, v5, s[4:5]
	v_cndmask_b32_e32 v5, 0, v219, vcc
	v_sub_f32_e32 v2, v2, v5
	v_add_f32_e32 v4, v4, v2
	v_max_f32_e64 v2, -v3, 0
	v_mul_f32_e64 v3, |v3|, s92
	v_exp_f32_e32 v3, v3
	v_sub_f32_e32 v4, -0.5, v4
	v_mul_f32_e32 v4, 0x3fb8aa3b, v4
	v_exp_f32_e32 v4, v4
	v_add_f32_e32 v3, 1.0, v3
	v_cmp_gt_f32_e32 vcc, s96, v3
	v_mul_f32_e32 v4, 0xbfb8aa3b, v4
	s_nop 0
	v_cndmask_b32_e64 v5, 0, 32, vcc
	v_ldexp_f32 v3, v3, v5
	v_log_f32_e32 v3, v3
	v_exp_f32_e32 v4, v4
	v_mul_f32_e32 v5, 0x3f317217, v3
	v_fma_f32 v5, v3, s2, -v5
	v_fmac_f32_e32 v5, 0x3377d1cf, v3
	v_fmac_f32_e32 v5, 0x3f317217, v3
	v_cmp_lt_f32_e64 s[4:5], |v3|, s3
	s_nop 1
	v_cndmask_b32_e64 v3, v3, v5, s[4:5]
	v_cndmask_b32_e32 v5, 0, v219, vcc
	v_sub_f32_e32 v3, v3, v5
	v_add_f32_e32 v5, v2, v3
	v_lshl_add_u64 v[2:3], s[70:71], 0, v[0:1]
	global_store_dword v[2:3], v4, off
	v_sub_f32_e32 v2, -0.5, v5
	v_mul_f32_e32 v2, 0x3fb8aa3b, v2
	v_exp_f32_e32 v2, v2
	v_lshl_add_u64 v[0:1], s[78:79], 0, v[0:1]
	v_add_f32_e32 v3, v23, v35
	v_mul_f32_e32 v2, 0xbfb8aa3b, v2
	v_exp_f32_e32 v2, v2
	global_store_dword v[0:1], v2, off
	v_add_f32_e32 v2, v7, v33
	v_max_f32_e64 v4, -v2, 0
	v_mul_f32_e64 v2, |v2|, s92
	v_exp_f32_e32 v2, v2
	v_lshl_add_u64 v[0:1], v[92:93], 0, v[78:79]
	v_lshlrev_b64 v[0:1], 2, v[0:1]
	v_add_f32_e32 v2, 1.0, v2
	v_cmp_gt_f32_e32 vcc, s96, v2
	s_nop 1
	v_cndmask_b32_e64 v5, 0, 32, vcc
	v_ldexp_f32 v2, v2, v5
	v_log_f32_e32 v2, v2
	s_nop 0
	v_mul_f32_e32 v5, 0x3f317217, v2
	v_fma_f32 v5, v2, s2, -v5
	v_fmac_f32_e32 v5, 0x3377d1cf, v2
	v_fmac_f32_e32 v5, 0x3f317217, v2
	v_cmp_lt_f32_e64 s[4:5], |v2|, s3
	s_nop 1
	v_cndmask_b32_e64 v2, v2, v5, s[4:5]
	v_cndmask_b32_e32 v5, 0, v219, vcc
	v_sub_f32_e32 v2, v2, v5
	v_add_f32_e32 v4, v4, v2
	v_max_f32_e64 v2, -v3, 0
	v_mul_f32_e64 v3, |v3|, s92
	v_exp_f32_e32 v3, v3
	v_sub_f32_e32 v4, -0.5, v4
	v_mul_f32_e32 v4, 0x3fb8aa3b, v4
	v_exp_f32_e32 v4, v4
	v_add_f32_e32 v3, 1.0, v3
	v_cmp_gt_f32_e32 vcc, s96, v3
	v_mul_f32_e32 v4, 0xbfb8aa3b, v4
	s_nop 0
	v_cndmask_b32_e64 v5, 0, 32, vcc
	v_ldexp_f32 v3, v3, v5
	v_log_f32_e32 v3, v3
	v_exp_f32_e32 v4, v4
	v_mul_f32_e32 v5, 0x3f317217, v3
	v_fma_f32 v5, v3, s2, -v5
	v_fmac_f32_e32 v5, 0x3377d1cf, v3
	v_fmac_f32_e32 v5, 0x3f317217, v3
	v_cmp_lt_f32_e64 s[4:5], |v3|, s3
	s_nop 1
	v_cndmask_b32_e64 v3, v3, v5, s[4:5]
	v_cndmask_b32_e32 v5, 0, v219, vcc
	v_sub_f32_e32 v3, v3, v5
	v_add_f32_e32 v5, v2, v3
	v_lshl_add_u64 v[2:3], s[70:71], 0, v[0:1]
	global_store_dword v[2:3], v4, off
	v_sub_f32_e32 v2, -0.5, v5
	v_mul_f32_e32 v2, 0x3fb8aa3b, v2
	v_exp_f32_e32 v2, v2
	v_lshl_add_u64 v[0:1], s[78:79], 0, v[0:1]
	v_add_f32_e32 v3, v24, v35
	v_mul_f32_e32 v2, 0xbfb8aa3b, v2
	v_exp_f32_e32 v2, v2
	global_store_dword v[0:1], v2, off
	v_add_f32_e32 v2, v8, v33
	v_max_f32_e64 v4, -v2, 0
	v_mul_f32_e64 v2, |v2|, s92
	v_exp_f32_e32 v2, v2
	v_lshl_add_u64 v[0:1], v[94:95], 0, v[78:79]
	v_lshlrev_b64 v[0:1], 2, v[0:1]
	v_add_f32_e32 v2, 1.0, v2
	v_cmp_gt_f32_e32 vcc, s96, v2
	s_nop 1
	v_cndmask_b32_e64 v5, 0, 32, vcc
	v_ldexp_f32 v2, v2, v5
	v_log_f32_e32 v2, v2
	s_nop 0
	v_mul_f32_e32 v5, 0x3f317217, v2
	v_fma_f32 v5, v2, s2, -v5
	v_fmac_f32_e32 v5, 0x3377d1cf, v2
	v_fmac_f32_e32 v5, 0x3f317217, v2
	v_cmp_lt_f32_e64 s[4:5], |v2|, s3
	s_nop 1
	v_cndmask_b32_e64 v2, v2, v5, s[4:5]
	v_cndmask_b32_e32 v5, 0, v219, vcc
	v_sub_f32_e32 v2, v2, v5
	v_add_f32_e32 v4, v4, v2
	v_max_f32_e64 v2, -v3, 0
	v_mul_f32_e64 v3, |v3|, s92
	v_exp_f32_e32 v3, v3
	v_sub_f32_e32 v4, -0.5, v4
	v_mul_f32_e32 v4, 0x3fb8aa3b, v4
	v_exp_f32_e32 v4, v4
	v_add_f32_e32 v3, 1.0, v3
	v_cmp_gt_f32_e32 vcc, s96, v3
	v_mul_f32_e32 v4, 0xbfb8aa3b, v4
	s_nop 0
	v_cndmask_b32_e64 v5, 0, 32, vcc
	v_ldexp_f32 v3, v3, v5
	v_log_f32_e32 v3, v3
	v_exp_f32_e32 v4, v4
	v_mul_f32_e32 v5, 0x3f317217, v3
	v_fma_f32 v5, v3, s2, -v5
	v_fmac_f32_e32 v5, 0x3377d1cf, v3
	v_fmac_f32_e32 v5, 0x3f317217, v3
	v_cmp_lt_f32_e64 s[4:5], |v3|, s3
	s_nop 1
	v_cndmask_b32_e64 v3, v3, v5, s[4:5]
	v_cndmask_b32_e32 v5, 0, v219, vcc
	v_sub_f32_e32 v3, v3, v5
	v_add_f32_e32 v5, v2, v3
	v_lshl_add_u64 v[2:3], s[70:71], 0, v[0:1]
	global_store_dword v[2:3], v4, off
	v_sub_f32_e32 v2, -0.5, v5
	v_mul_f32_e32 v2, 0x3fb8aa3b, v2
	v_exp_f32_e32 v2, v2
	v_lshl_add_u64 v[0:1], s[78:79], 0, v[0:1]
	v_add_f32_e32 v3, v25, v35
	v_mul_f32_e32 v2, 0xbfb8aa3b, v2
	v_exp_f32_e32 v2, v2
	global_store_dword v[0:1], v2, off
	v_add_f32_e32 v2, v9, v33
	v_max_f32_e64 v4, -v2, 0
	v_mul_f32_e64 v2, |v2|, s92
	v_exp_f32_e32 v2, v2
	v_lshl_add_u64 v[0:1], v[96:97], 0, v[78:79]
	v_lshlrev_b64 v[0:1], 2, v[0:1]
	v_add_f32_e32 v2, 1.0, v2
	v_cmp_gt_f32_e32 vcc, s96, v2
	s_nop 1
	v_cndmask_b32_e64 v5, 0, 32, vcc
	v_ldexp_f32 v2, v2, v5
	v_log_f32_e32 v2, v2
	s_nop 0
	v_mul_f32_e32 v5, 0x3f317217, v2
	v_fma_f32 v5, v2, s2, -v5
	v_fmac_f32_e32 v5, 0x3377d1cf, v2
	v_fmac_f32_e32 v5, 0x3f317217, v2
	v_cmp_lt_f32_e64 s[4:5], |v2|, s3
	s_nop 1
	v_cndmask_b32_e64 v2, v2, v5, s[4:5]
	v_cndmask_b32_e32 v5, 0, v219, vcc
	v_sub_f32_e32 v2, v2, v5
	v_add_f32_e32 v4, v4, v2
	v_max_f32_e64 v2, -v3, 0
	v_mul_f32_e64 v3, |v3|, s92
	v_exp_f32_e32 v3, v3
	v_sub_f32_e32 v4, -0.5, v4
	v_mul_f32_e32 v4, 0x3fb8aa3b, v4
	v_exp_f32_e32 v4, v4
	v_add_f32_e32 v3, 1.0, v3
	v_cmp_gt_f32_e32 vcc, s96, v3
	v_mul_f32_e32 v4, 0xbfb8aa3b, v4
	s_nop 0
	v_cndmask_b32_e64 v5, 0, 32, vcc
	v_ldexp_f32 v3, v3, v5
	v_log_f32_e32 v3, v3
	v_exp_f32_e32 v4, v4
	v_mul_f32_e32 v5, 0x3f317217, v3
	v_fma_f32 v5, v3, s2, -v5
	v_fmac_f32_e32 v5, 0x3377d1cf, v3
	v_fmac_f32_e32 v5, 0x3f317217, v3
	v_cmp_lt_f32_e64 s[4:5], |v3|, s3
	s_nop 1
	v_cndmask_b32_e64 v3, v3, v5, s[4:5]
	v_cndmask_b32_e32 v5, 0, v219, vcc
	v_sub_f32_e32 v3, v3, v5
	v_add_f32_e32 v5, v2, v3
	v_lshl_add_u64 v[2:3], s[70:71], 0, v[0:1]
	global_store_dword v[2:3], v4, off
	v_sub_f32_e32 v2, -0.5, v5
	v_mul_f32_e32 v2, 0x3fb8aa3b, v2
	v_exp_f32_e32 v2, v2
	v_lshl_add_u64 v[0:1], s[78:79], 0, v[0:1]
	v_add_f32_e32 v3, v26, v35
	v_mul_f32_e32 v2, 0xbfb8aa3b, v2
	v_exp_f32_e32 v2, v2
	global_store_dword v[0:1], v2, off
	v_add_f32_e32 v2, v10, v33
	v_max_f32_e64 v4, -v2, 0
	v_mul_f32_e64 v2, |v2|, s92
	v_exp_f32_e32 v2, v2
	v_lshl_add_u64 v[0:1], v[98:99], 0, v[78:79]
	v_lshlrev_b64 v[0:1], 2, v[0:1]
	v_add_f32_e32 v2, 1.0, v2
	v_cmp_gt_f32_e32 vcc, s96, v2
	s_nop 1
	v_cndmask_b32_e64 v5, 0, 32, vcc
	v_ldexp_f32 v2, v2, v5
	v_log_f32_e32 v2, v2
	s_nop 0
	v_mul_f32_e32 v5, 0x3f317217, v2
	v_fma_f32 v5, v2, s2, -v5
	v_fmac_f32_e32 v5, 0x3377d1cf, v2
	v_fmac_f32_e32 v5, 0x3f317217, v2
	v_cmp_lt_f32_e64 s[4:5], |v2|, s3
	s_nop 1
	v_cndmask_b32_e64 v2, v2, v5, s[4:5]
	v_cndmask_b32_e32 v5, 0, v219, vcc
	v_sub_f32_e32 v2, v2, v5
	v_add_f32_e32 v4, v4, v2
	v_max_f32_e64 v2, -v3, 0
	v_mul_f32_e64 v3, |v3|, s92
	v_exp_f32_e32 v3, v3
	v_sub_f32_e32 v4, -0.5, v4
	v_mul_f32_e32 v4, 0x3fb8aa3b, v4
	v_exp_f32_e32 v4, v4
	v_add_f32_e32 v3, 1.0, v3
	v_cmp_gt_f32_e32 vcc, s96, v3
	v_mul_f32_e32 v4, 0xbfb8aa3b, v4
	s_nop 0
	v_cndmask_b32_e64 v5, 0, 32, vcc
	v_ldexp_f32 v3, v3, v5
	v_log_f32_e32 v3, v3
	v_exp_f32_e32 v4, v4
	v_mul_f32_e32 v5, 0x3f317217, v3
	v_fma_f32 v5, v3, s2, -v5
	v_fmac_f32_e32 v5, 0x3377d1cf, v3
	v_fmac_f32_e32 v5, 0x3f317217, v3
	v_cmp_lt_f32_e64 s[4:5], |v3|, s3
	s_nop 1
	v_cndmask_b32_e64 v3, v3, v5, s[4:5]
	v_cndmask_b32_e32 v5, 0, v219, vcc
	v_sub_f32_e32 v3, v3, v5
	v_add_f32_e32 v5, v2, v3
	v_lshl_add_u64 v[2:3], s[70:71], 0, v[0:1]
	global_store_dword v[2:3], v4, off
	v_sub_f32_e32 v2, -0.5, v5
	v_mul_f32_e32 v2, 0x3fb8aa3b, v2
	v_exp_f32_e32 v2, v2
	v_lshl_add_u64 v[0:1], s[78:79], 0, v[0:1]
	v_add_f32_e32 v3, v27, v35
	v_mul_f32_e32 v2, 0xbfb8aa3b, v2
	v_exp_f32_e32 v2, v2
	global_store_dword v[0:1], v2, off
	v_add_f32_e32 v2, v11, v33
	v_max_f32_e64 v4, -v2, 0
	v_mul_f32_e64 v2, |v2|, s92
	v_exp_f32_e32 v2, v2
	v_lshl_add_u64 v[0:1], v[100:101], 0, v[78:79]
	v_lshlrev_b64 v[0:1], 2, v[0:1]
	v_add_f32_e32 v2, 1.0, v2
	v_cmp_gt_f32_e32 vcc, s96, v2
	s_nop 1
	v_cndmask_b32_e64 v5, 0, 32, vcc
	v_ldexp_f32 v2, v2, v5
	v_log_f32_e32 v2, v2
	s_nop 0
	v_mul_f32_e32 v5, 0x3f317217, v2
	v_fma_f32 v5, v2, s2, -v5
	v_fmac_f32_e32 v5, 0x3377d1cf, v2
	v_fmac_f32_e32 v5, 0x3f317217, v2
	v_cmp_lt_f32_e64 s[4:5], |v2|, s3
	s_nop 1
	v_cndmask_b32_e64 v2, v2, v5, s[4:5]
	v_cndmask_b32_e32 v5, 0, v219, vcc
	v_sub_f32_e32 v2, v2, v5
	v_add_f32_e32 v4, v4, v2
	v_max_f32_e64 v2, -v3, 0
	v_mul_f32_e64 v3, |v3|, s92
	v_exp_f32_e32 v3, v3
	v_sub_f32_e32 v4, -0.5, v4
	v_mul_f32_e32 v4, 0x3fb8aa3b, v4
	v_exp_f32_e32 v4, v4
	v_add_f32_e32 v3, 1.0, v3
	v_cmp_gt_f32_e32 vcc, s96, v3
	v_mul_f32_e32 v4, 0xbfb8aa3b, v4
	s_nop 0
	v_cndmask_b32_e64 v5, 0, 32, vcc
	v_ldexp_f32 v3, v3, v5
	v_log_f32_e32 v3, v3
	v_exp_f32_e32 v4, v4
	v_mul_f32_e32 v5, 0x3f317217, v3
	v_fma_f32 v5, v3, s2, -v5
	v_fmac_f32_e32 v5, 0x3377d1cf, v3
	v_fmac_f32_e32 v5, 0x3f317217, v3
	v_cmp_lt_f32_e64 s[4:5], |v3|, s3
	s_nop 1
	v_cndmask_b32_e64 v3, v3, v5, s[4:5]
	v_cndmask_b32_e32 v5, 0, v219, vcc
	v_sub_f32_e32 v3, v3, v5
	v_add_f32_e32 v5, v2, v3
	v_lshl_add_u64 v[2:3], s[70:71], 0, v[0:1]
	global_store_dword v[2:3], v4, off
	v_sub_f32_e32 v2, -0.5, v5
	v_mul_f32_e32 v2, 0x3fb8aa3b, v2
	v_exp_f32_e32 v2, v2
	v_lshl_add_u64 v[0:1], s[78:79], 0, v[0:1]
	v_add_f32_e32 v3, v28, v35
	v_mul_f32_e32 v2, 0xbfb8aa3b, v2
	v_exp_f32_e32 v2, v2
	global_store_dword v[0:1], v2, off
	v_add_f32_e32 v2, v12, v33
	v_max_f32_e64 v4, -v2, 0
	v_mul_f32_e64 v2, |v2|, s92
	v_exp_f32_e32 v2, v2
	v_lshl_add_u64 v[0:1], v[88:89], 0, v[78:79]
	v_lshlrev_b64 v[0:1], 2, v[0:1]
	v_add_f32_e32 v2, 1.0, v2
	v_cmp_gt_f32_e32 vcc, s96, v2
	s_nop 1
	v_cndmask_b32_e64 v5, 0, 32, vcc
	v_ldexp_f32 v2, v2, v5
	v_log_f32_e32 v2, v2
	s_nop 0
	v_mul_f32_e32 v5, 0x3f317217, v2
	v_fma_f32 v5, v2, s2, -v5
	v_fmac_f32_e32 v5, 0x3377d1cf, v2
	v_fmac_f32_e32 v5, 0x3f317217, v2
	v_cmp_lt_f32_e64 s[4:5], |v2|, s3
	s_nop 1
	v_cndmask_b32_e64 v2, v2, v5, s[4:5]
	v_cndmask_b32_e32 v5, 0, v219, vcc
	v_sub_f32_e32 v2, v2, v5
	v_add_f32_e32 v4, v4, v2
	v_max_f32_e64 v2, -v3, 0
	v_mul_f32_e64 v3, |v3|, s92
	v_exp_f32_e32 v3, v3
	v_sub_f32_e32 v4, -0.5, v4
	v_mul_f32_e32 v4, 0x3fb8aa3b, v4
	v_exp_f32_e32 v4, v4
	v_add_f32_e32 v3, 1.0, v3
	v_cmp_gt_f32_e32 vcc, s96, v3
	v_mul_f32_e32 v4, 0xbfb8aa3b, v4
	s_nop 0
	v_cndmask_b32_e64 v5, 0, 32, vcc
	v_ldexp_f32 v3, v3, v5
	v_log_f32_e32 v3, v3
	v_exp_f32_e32 v4, v4
	v_mul_f32_e32 v5, 0x3f317217, v3
	v_fma_f32 v5, v3, s2, -v5
	v_fmac_f32_e32 v5, 0x3377d1cf, v3
	v_fmac_f32_e32 v5, 0x3f317217, v3
	v_cmp_lt_f32_e64 s[4:5], |v3|, s3
	s_nop 1
	v_cndmask_b32_e64 v3, v3, v5, s[4:5]
	v_cndmask_b32_e32 v5, 0, v219, vcc
	v_sub_f32_e32 v3, v3, v5
	v_add_f32_e32 v5, v2, v3
	v_lshl_add_u64 v[2:3], s[70:71], 0, v[0:1]
	global_store_dword v[2:3], v4, off
	v_sub_f32_e32 v2, -0.5, v5
	v_mul_f32_e32 v2, 0x3fb8aa3b, v2
	v_exp_f32_e32 v2, v2
	v_lshl_add_u64 v[0:1], s[78:79], 0, v[0:1]
	v_add_f32_e32 v3, v29, v35
	v_mul_f32_e32 v2, 0xbfb8aa3b, v2
	v_exp_f32_e32 v2, v2
	global_store_dword v[0:1], v2, off
	v_add_f32_e32 v2, v13, v33
	v_max_f32_e64 v4, -v2, 0
	v_mul_f32_e64 v2, |v2|, s92
	v_exp_f32_e32 v2, v2
	v_lshl_add_u64 v[0:1], v[82:83], 0, v[78:79]
	v_lshlrev_b64 v[0:1], 2, v[0:1]
	v_add_f32_e32 v2, 1.0, v2
	v_cmp_gt_f32_e32 vcc, s96, v2
	s_nop 1
	v_cndmask_b32_e64 v5, 0, 32, vcc
	v_ldexp_f32 v2, v2, v5
	v_log_f32_e32 v2, v2
	s_nop 0
	v_mul_f32_e32 v5, 0x3f317217, v2
	v_fma_f32 v5, v2, s2, -v5
	v_fmac_f32_e32 v5, 0x3377d1cf, v2
	v_fmac_f32_e32 v5, 0x3f317217, v2
	v_cmp_lt_f32_e64 s[4:5], |v2|, s3
	s_nop 1
	v_cndmask_b32_e64 v2, v2, v5, s[4:5]
	v_cndmask_b32_e32 v5, 0, v219, vcc
	v_sub_f32_e32 v2, v2, v5
	v_add_f32_e32 v4, v4, v2
	v_max_f32_e64 v2, -v3, 0
	v_mul_f32_e64 v3, |v3|, s92
	v_exp_f32_e32 v3, v3
	v_sub_f32_e32 v4, -0.5, v4
	v_mul_f32_e32 v4, 0x3fb8aa3b, v4
	v_exp_f32_e32 v4, v4
	v_add_f32_e32 v3, 1.0, v3
	v_cmp_gt_f32_e32 vcc, s96, v3
	v_mul_f32_e32 v4, 0xbfb8aa3b, v4
	s_nop 0
	v_cndmask_b32_e64 v5, 0, 32, vcc
	v_ldexp_f32 v3, v3, v5
	v_log_f32_e32 v3, v3
	v_exp_f32_e32 v4, v4
	v_mul_f32_e32 v5, 0x3f317217, v3
	v_fma_f32 v5, v3, s2, -v5
	v_fmac_f32_e32 v5, 0x3377d1cf, v3
	v_fmac_f32_e32 v5, 0x3f317217, v3
	v_cmp_lt_f32_e64 s[4:5], |v3|, s3
	s_nop 1
	v_cndmask_b32_e64 v3, v3, v5, s[4:5]
	v_cndmask_b32_e32 v5, 0, v219, vcc
	v_sub_f32_e32 v3, v3, v5
	v_add_f32_e32 v5, v2, v3
	v_lshl_add_u64 v[2:3], s[70:71], 0, v[0:1]
	global_store_dword v[2:3], v4, off
	v_sub_f32_e32 v2, -0.5, v5
	v_mul_f32_e32 v2, 0x3fb8aa3b, v2
	v_exp_f32_e32 v2, v2
	v_lshl_add_u64 v[0:1], s[78:79], 0, v[0:1]
	v_add_f32_e32 v3, v30, v35
	v_mul_f32_e32 v2, 0xbfb8aa3b, v2
	v_exp_f32_e32 v2, v2
	global_store_dword v[0:1], v2, off
	v_add_f32_e32 v2, v14, v33
	v_max_f32_e64 v4, -v2, 0
	v_mul_f32_e64 v2, |v2|, s92
	v_exp_f32_e32 v2, v2
	v_lshl_add_u64 v[0:1], v[80:81], 0, v[78:79]
	v_lshlrev_b64 v[0:1], 2, v[0:1]
	v_add_f32_e32 v2, 1.0, v2
	v_cmp_gt_f32_e32 vcc, s96, v2
	s_nop 1
	v_cndmask_b32_e64 v5, 0, 32, vcc
	v_ldexp_f32 v2, v2, v5
	v_log_f32_e32 v2, v2
	s_nop 0
	v_mul_f32_e32 v5, 0x3f317217, v2
	v_fma_f32 v5, v2, s2, -v5
	v_fmac_f32_e32 v5, 0x3377d1cf, v2
	v_fmac_f32_e32 v5, 0x3f317217, v2
	v_cmp_lt_f32_e64 s[4:5], |v2|, s3
	s_nop 1
	v_cndmask_b32_e64 v2, v2, v5, s[4:5]
	v_cndmask_b32_e32 v5, 0, v219, vcc
	v_sub_f32_e32 v2, v2, v5
	v_add_f32_e32 v4, v4, v2
	v_max_f32_e64 v2, -v3, 0
	v_mul_f32_e64 v3, |v3|, s92
	v_exp_f32_e32 v3, v3
	v_sub_f32_e32 v4, -0.5, v4
	v_mul_f32_e32 v4, 0x3fb8aa3b, v4
	v_exp_f32_e32 v4, v4
	v_add_f32_e32 v3, 1.0, v3
	v_cmp_gt_f32_e32 vcc, s96, v3
	v_mul_f32_e32 v4, 0xbfb8aa3b, v4
	s_nop 0
	v_cndmask_b32_e64 v5, 0, 32, vcc
	v_ldexp_f32 v3, v3, v5
	v_log_f32_e32 v3, v3
	v_exp_f32_e32 v4, v4
	v_mul_f32_e32 v5, 0x3f317217, v3
	v_fma_f32 v5, v3, s2, -v5
	v_fmac_f32_e32 v5, 0x3377d1cf, v3
	v_fmac_f32_e32 v5, 0x3f317217, v3
	v_cmp_lt_f32_e64 s[4:5], |v3|, s3
	s_nop 1
	v_cndmask_b32_e64 v3, v3, v5, s[4:5]
	v_cndmask_b32_e32 v5, 0, v219, vcc
	v_sub_f32_e32 v3, v3, v5
	v_add_f32_e32 v5, v2, v3
	v_lshl_add_u64 v[2:3], s[70:71], 0, v[0:1]
	global_store_dword v[2:3], v4, off
	v_sub_f32_e32 v2, -0.5, v5
	v_mul_f32_e32 v2, 0x3fb8aa3b, v2
	v_exp_f32_e32 v2, v2
	v_lshl_add_u64 v[0:1], s[78:79], 0, v[0:1]
	v_add_f32_e32 v3, v31, v35
	v_mul_f32_e32 v2, 0xbfb8aa3b, v2
	v_exp_f32_e32 v2, v2
	global_store_dword v[0:1], v2, off
	v_add_f32_e32 v2, v15, v33
	v_max_f32_e64 v4, -v2, 0
	v_mul_f32_e64 v2, |v2|, s92
	v_exp_f32_e32 v2, v2
	v_lshl_add_u64 v[0:1], v[76:77], 0, v[78:79]
	v_lshlrev_b64 v[0:1], 2, v[0:1]
	v_add_f32_e32 v2, 1.0, v2
	v_cmp_gt_f32_e32 vcc, s96, v2
	s_nop 1
	v_cndmask_b32_e64 v5, 0, 32, vcc
	v_ldexp_f32 v2, v2, v5
	v_log_f32_e32 v2, v2
	s_nop 0
	v_mul_f32_e32 v5, 0x3f317217, v2
	v_fma_f32 v5, v2, s2, -v5
	v_fmac_f32_e32 v5, 0x3377d1cf, v2
	v_fmac_f32_e32 v5, 0x3f317217, v2
	v_cmp_lt_f32_e64 s[4:5], |v2|, s3
	s_nop 1
	v_cndmask_b32_e64 v2, v2, v5, s[4:5]
	v_cndmask_b32_e32 v5, 0, v219, vcc
	v_sub_f32_e32 v2, v2, v5
	v_add_f32_e32 v4, v4, v2
	v_max_f32_e64 v2, -v3, 0
	v_mul_f32_e64 v3, |v3|, s92
	v_exp_f32_e32 v3, v3
	v_sub_f32_e32 v4, -0.5, v4
	v_mul_f32_e32 v4, 0x3fb8aa3b, v4
	v_exp_f32_e32 v4, v4
	v_add_f32_e32 v3, 1.0, v3
	v_cmp_gt_f32_e32 vcc, s96, v3
	v_mul_f32_e32 v4, 0xbfb8aa3b, v4
	s_nop 0
	v_cndmask_b32_e64 v5, 0, 32, vcc
	v_ldexp_f32 v3, v3, v5
	v_log_f32_e32 v3, v3
	v_exp_f32_e32 v4, v4
	v_mul_f32_e32 v5, 0x3f317217, v3
	v_fma_f32 v5, v3, s2, -v5
	v_fmac_f32_e32 v5, 0x3377d1cf, v3
	v_fmac_f32_e32 v5, 0x3f317217, v3
	v_cmp_lt_f32_e64 s[4:5], |v3|, s3
	s_nop 1
	v_cndmask_b32_e64 v3, v3, v5, s[4:5]
	v_cndmask_b32_e32 v5, 0, v219, vcc
	v_sub_f32_e32 v3, v3, v5
	v_add_f32_e32 v5, v2, v3
	v_lshl_add_u64 v[2:3], s[70:71], 0, v[0:1]
	global_store_dword v[2:3], v4, off
	v_sub_f32_e32 v2, -0.5, v5
	v_mul_f32_e32 v2, 0x3fb8aa3b, v2
	v_exp_f32_e32 v2, v2
	v_lshl_add_u64 v[0:1], s[78:79], 0, v[0:1]
	s_movk_i32 s4, 0x1000
	s_movk_i32 s5, 0x2000
	v_mul_f32_e32 v2, 0xbfb8aa3b, v2
	v_exp_f32_e32 v2, v2
	global_store_dword v[0:1], v2, off
	s_nop 0
	v_ashrrev_i32_e32 v35, 31, v34
	v_lshlrev_b64 v[0:1], 8, v[34:35]
	v_lshl_add_u64 v[0:1], s[56:57], 0, v[0:1]
	v_lshl_add_u64 v[24:25], v[0:1], 0, v[178:179]
	global_load_dwordx4 v[28:31], v[24:25], off
	ds_read_b128 v[4:7], v104 offset:256
	ds_read_b128 v[16:19], v104 offset:288
	global_load_dwordx4 v[76:79], v[24:25], off offset:32
	global_load_dwordx4 v[80:83], v[24:25], off offset:64
	global_load_dwordx4 v[84:87], v[24:25], off offset:96
	global_load_dwordx4 v[88:91], v[24:25], off offset:128
	global_load_dwordx4 v[92:95], v[24:25], off offset:160
	global_load_dwordx4 v[96:99], v[24:25], off offset:192
	global_load_dwordx4 v[108:111], v[24:25], off offset:224
	s_waitcnt vmcnt(6) lgkmcnt(0)
	v_mfma_f32_32x32x16_bf16 v[0:15], v[4:7], v[28:31], 0
	v_lshlrev_b64 v[68:69], 2, v[34:35]
	v_mfma_f32_32x32x16_bf16 v[0:15], v[16:19], v[76:79], v[0:15]
	ds_read_b128 v[16:19], v104 offset:320
	s_waitcnt vmcnt(5) lgkmcnt(0)
	v_mfma_f32_32x32x16_bf16 v[0:15], v[16:19], v[80:83], v[0:15]
	ds_read_b128 v[16:19], v104 offset:352
	s_waitcnt vmcnt(4) lgkmcnt(0)
	v_mfma_f32_32x32x16_bf16 v[0:15], v[16:19], v[84:87], v[0:15]
	ds_read_b128 v[16:19], v104 offset:384
	s_waitcnt vmcnt(3) lgkmcnt(0)
	v_mfma_f32_32x32x16_bf16 v[0:15], v[16:19], v[88:91], v[0:15]
	ds_read_b128 v[16:19], v104 offset:416
	s_waitcnt vmcnt(2) lgkmcnt(0)
	v_mfma_f32_32x32x16_bf16 v[0:15], v[16:19], v[92:95], v[0:15]
	ds_read_b128 v[16:19], v104 offset:448
	s_waitcnt vmcnt(1) lgkmcnt(0)
	v_mfma_f32_32x32x16_bf16 v[0:15], v[16:19], v[96:99], v[0:15]
	ds_read_b128 v[16:19], v104 offset:480
	v_lshl_add_u32 v24, v34, 1, 0
	v_add_u32_e32 v72, v24, v103
	v_add_u32_e32 v34, 0x800, v72
	s_waitcnt vmcnt(0) lgkmcnt(0)
	v_mfma_f32_32x32x16_bf16 v[0:15], v[16:19], v[108:111], v[0:15]
	v_lshl_add_u64 v[16:17], s[76:77], 0, v[68:69]
	v_add_co_u32_e32 v18, vcc, s4, v16
	s_nop 1
	v_addc_co_u32_e32 v19, vcc, 0, v17, vcc
	global_load_dword v33, v[18:19], off
	v_add_co_u32_e32 v18, vcc, s5, v16
	s_nop 1
	v_addc_co_u32_e32 v19, vcc, 0, v17, vcc
	global_load_dword v70, v[18:19], off offset:3072
	v_add_co_u32_e32 v16, vcc, s6, v16
	s_nop 1
	v_addc_co_u32_e32 v17, vcc, 0, v17, vcc
	global_load_dword v71, v[16:17], off offset:2048
	ds_read_u16 v16, v72 offset:2048
	s_waitcnt lgkmcnt(0)
	v_lshlrev_b32_e32 v20, 16, v16
	ds_read_u16 v16, v72 offset:5664
	s_waitcnt lgkmcnt(0)
	v_lshlrev_b32_e32 v22, 16, v16
	ds_read_u16 v16, v72 offset:9280
	s_waitcnt lgkmcnt(0)
	v_lshlrev_b32_e32 v23, 16, v16
	ds_read_u16 v16, v72 offset:12896
	s_waitcnt lgkmcnt(0)
	v_lshlrev_b32_e32 v25, 16, v16
	ds_read_u16 v16, v72 offset:16512
	s_waitcnt lgkmcnt(0)
	v_lshlrev_b32_e32 v26, 16, v16
	ds_read_u16 v16, v72 offset:20128
	s_waitcnt lgkmcnt(0)
	v_lshlrev_b32_e32 v27, 16, v16
	v_lshlrev_b64 v[16:17], 11, v[36:37]
	v_lshl_add_u64 v[16:17], s[68:69], 0, v[16:17]
	v_lshl_add_u64 v[18:19], v[16:17], 0, v[68:69]
	s_waitcnt vmcnt(1)
	v_mul_f32_e32 v21, v70, v22
	v_fmac_f32_e32 v21, v33, v20
	s_waitcnt vmcnt(0)
	v_fmac_f32_e32 v21, v71, v23
	v_cvt_pk_bf16_f32 v0, v21, v0
	global_store_dword v[18:19], v0, off
	v_mul_f32_e32 v0, v70, v23
	v_lshlrev_b64 v[18:19], 11, v[38:39]
	v_fmac_f32_e32 v0, v33, v22
	v_lshl_add_u64 v[18:19], s[68:69], 0, v[18:19]
	v_fmac_f32_e32 v0, v71, v25
	v_lshl_add_u64 v[20:21], v[18:19], 0, v[68:69]
	v_cvt_pk_bf16_f32 v0, v0, v1
	global_store_dword v[20:21], v0, off
	v_lshlrev_b64 v[0:1], 11, v[40:41]
	v_mul_f32_e32 v22, v70, v25
	v_lshl_add_u64 v[20:21], s[68:69], 0, v[0:1]
	v_fmac_f32_e32 v22, v33, v23
	v_lshl_add_u64 v[0:1], v[20:21], 0, v[68:69]
	v_fmac_f32_e32 v22, v71, v26
	v_cvt_pk_bf16_f32 v2, v22, v2
	global_store_dword v[0:1], v2, off
	v_mul_f32_e32 v2, v70, v26
	v_lshlrev_b64 v[0:1], 11, v[42:43]
	v_fmac_f32_e32 v2, v33, v25
	v_lshl_add_u64 v[22:23], s[68:69], 0, v[0:1]
	v_fmac_f32_e32 v2, v71, v27
	v_lshl_add_u64 v[0:1], v[22:23], 0, v[68:69]
	v_cvt_pk_bf16_f32 v2, v2, v3
	global_store_dword v[0:1], v2, off
	v_add_u32_e32 v2, v24, v105
	ds_read_u16 v0, v2 offset:2048
	s_waitcnt lgkmcnt(0)
	v_lshlrev_b32_e32 v3, 16, v0
	ds_read_u16 v0, v72 offset:34592
	s_waitcnt lgkmcnt(0)
	v_lshlrev_b32_e32 v28, 16, v0
	ds_read_u16 v0, v72 offset:38208
	v_mul_f32_e32 v26, v70, v28
	v_fmac_f32_e32 v26, v33, v3
	s_waitcnt lgkmcnt(0)
	v_lshlrev_b32_e32 v30, 16, v0
	ds_read_u16 v0, v72 offset:41824
	v_fmac_f32_e32 v26, v71, v30
	s_waitcnt lgkmcnt(0)
	v_lshlrev_b32_e32 v35, 16, v0
	ds_read_u16 v0, v72 offset:45440
	s_waitcnt lgkmcnt(0)
	v_lshlrev_b32_e32 v36, 16, v0
	ds_read_u16 v0, v72 offset:49056
	v_cvt_pk_bf16_f32 v3, v26, v4
	s_waitcnt lgkmcnt(0)
	v_lshlrev_b32_e32 v37, 16, v0
	v_lshlrev_b64 v[0:1], 11, v[44:45]
	v_lshl_add_u64 v[24:25], s[68:69], 0, v[0:1]
	v_lshl_add_u64 v[0:1], v[24:25], 0, v[68:69]
	global_store_dword v[0:1], v3, off
	v_mul_f32_e32 v3, v70, v30
	v_lshlrev_b64 v[0:1], 11, v[46:47]
	v_fmac_f32_e32 v3, v33, v28
	v_lshl_add_u64 v[26:27], s[68:69], 0, v[0:1]
	v_fmac_f32_e32 v3, v71, v35
	v_lshl_add_u64 v[0:1], v[26:27], 0, v[68:69]
	v_cvt_pk_bf16_f32 v3, v3, v5
	global_store_dword v[0:1], v3, off
	v_mul_f32_e32 v3, v70, v35
	v_lshlrev_b64 v[0:1], 11, v[48:49]
	v_fmac_f32_e32 v3, v33, v30
	v_lshl_add_u64 v[28:29], s[68:69], 0, v[0:1]
	v_fmac_f32_e32 v3, v71, v36
	v_lshl_add_u64 v[0:1], v[28:29], 0, v[68:69]
	v_cvt_pk_bf16_f32 v3, v3, v6
	global_store_dword v[0:1], v3, off
	v_lshlrev_b64 v[0:1], 11, v[50:51]
	v_mul_f32_e32 v3, v70, v36
	v_lshl_add_u64 v[30:31], s[68:69], 0, v[0:1]
	v_fmac_f32_e32 v3, v33, v35
	v_lshl_add_u64 v[0:1], v[30:31], 0, v[68:69]
	v_fmac_f32_e32 v3, v71, v37
	v_cvt_pk_bf16_f32 v3, v3, v7
	global_store_dword v[0:1], v3, off
	ds_read_u16 v0, v2 offset:30976
	s_waitcnt lgkmcnt(0)
	v_lshlrev_b32_e32 v3, 16, v0
	ds_read_u16 v0, v72 offset:63520
	s_waitcnt lgkmcnt(0)
	v_lshlrev_b32_e32 v4, 16, v0
	ds_read_u16 v0, v34 offset:65088
	v_mul_f32_e32 v36, v70, v4
	v_fmac_f32_e32 v36, v33, v3
	s_waitcnt lgkmcnt(0)
	v_lshlrev_b32_e32 v5, 16, v0
	v_add_u32_e32 v0, 0x11460, v72
	ds_read_u16 v0, v0
	v_fmac_f32_e32 v36, v71, v5
	s_waitcnt lgkmcnt(0)
	v_lshlrev_b32_e32 v6, 16, v0
	v_add_u32_e32 v0, 0x12280, v72
	ds_read_u16 v0, v0
	s_waitcnt lgkmcnt(0)
	v_lshlrev_b32_e32 v7, 16, v0
	v_add_u32_e32 v0, 0x130a0, v72
	ds_read_u16 v0, v0
	v_cvt_pk_bf16_f32 v3, v36, v8
	s_waitcnt lgkmcnt(0)
	v_lshlrev_b32_e32 v42, 16, v0
	v_lshlrev_b64 v[0:1], 11, v[52:53]
	v_lshl_add_u64 v[34:35], s[68:69], 0, v[0:1]
	v_lshl_add_u64 v[0:1], v[34:35], 0, v[68:69]
	global_store_dword v[0:1], v3, off
	v_mul_f32_e32 v3, v70, v5
	v_lshlrev_b64 v[0:1], 11, v[54:55]
	v_fmac_f32_e32 v3, v33, v4
	v_lshl_add_u64 v[36:37], s[68:69], 0, v[0:1]
	v_fmac_f32_e32 v3, v71, v6
	v_lshl_add_u64 v[0:1], v[36:37], 0, v[68:69]
	v_cvt_pk_bf16_f32 v3, v3, v9
	global_store_dword v[0:1], v3, off
	v_mul_f32_e32 v3, v70, v6
	v_lshlrev_b64 v[0:1], 11, v[56:57]
	v_fmac_f32_e32 v3, v33, v5
	v_lshl_add_u64 v[38:39], s[68:69], 0, v[0:1]
	v_fmac_f32_e32 v3, v71, v7
	v_lshl_add_u64 v[0:1], v[38:39], 0, v[68:69]
	v_cvt_pk_bf16_f32 v3, v3, v10
	global_store_dword v[0:1], v3, off
	v_lshlrev_b64 v[0:1], 11, v[58:59]
	v_mul_f32_e32 v3, v70, v7
	v_lshl_add_u64 v[40:41], s[68:69], 0, v[0:1]
	v_fmac_f32_e32 v3, v33, v6
	v_lshl_add_u64 v[0:1], v[40:41], 0, v[68:69]
	v_fmac_f32_e32 v3, v71, v42
	v_cvt_pk_bf16_f32 v3, v3, v11
	global_store_dword v[0:1], v3, off
	ds_read_u16 v0, v2 offset:59904
	s_waitcnt lgkmcnt(0)
	v_lshlrev_b32_e32 v2, 16, v0
	v_add_u32_e32 v0, 0x16920, v72
	ds_read_u16 v0, v0
	s_waitcnt lgkmcnt(0)
	v_lshlrev_b32_e32 v3, 16, v0
	v_add_u32_e32 v0, 0x17740, v72
	ds_read_u16 v0, v0
	v_mul_f32_e32 v8, v70, v3
	v_fmac_f32_e32 v8, v33, v2
	s_waitcnt lgkmcnt(0)
	v_lshlrev_b32_e32 v4, 16, v0
	v_add_u32_e32 v0, 0x18560, v72
	ds_read_u16 v0, v0
	v_fmac_f32_e32 v8, v71, v4
	s_waitcnt lgkmcnt(0)
	v_lshlrev_b32_e32 v5, 16, v0
	v_add_u32_e32 v0, 0x19380, v72
	ds_read_u16 v0, v0
	s_waitcnt lgkmcnt(0)
	v_lshlrev_b32_e32 v6, 16, v0
	v_add_u32_e32 v0, 0x1a1a0, v72
	ds_read_u16 v0, v0
	v_cvt_pk_bf16_f32 v2, v8, v12
	s_waitcnt lgkmcnt(0)
	v_lshlrev_b32_e32 v7, 16, v0
	v_lshlrev_b64 v[0:1], 11, v[60:61]
	v_lshl_add_u64 v[42:43], s[68:69], 0, v[0:1]
	v_lshl_add_u64 v[0:1], v[42:43], 0, v[68:69]
	global_store_dword v[0:1], v2, off
	v_mul_f32_e32 v2, v70, v4
	v_lshlrev_b64 v[0:1], 11, v[62:63]
	v_fmac_f32_e32 v2, v33, v3
	v_lshl_add_u64 v[44:45], s[68:69], 0, v[0:1]
	v_fmac_f32_e32 v2, v71, v5
	v_lshl_add_u64 v[0:1], v[44:45], 0, v[68:69]
	v_cvt_pk_bf16_f32 v2, v2, v13
	global_store_dword v[0:1], v2, off
	v_mul_f32_e32 v2, v70, v5
	v_lshlrev_b64 v[0:1], 11, v[64:65]
	v_fmac_f32_e32 v2, v33, v4
	v_lshl_add_u64 v[46:47], s[68:69], 0, v[0:1]
	v_fmac_f32_e32 v2, v71, v6
	v_lshl_add_u64 v[0:1], v[46:47], 0, v[68:69]
	v_cvt_pk_bf16_f32 v2, v2, v14
	global_store_dword v[0:1], v2, off
	v_lshlrev_b64 v[0:1], 11, v[66:67]
	v_mul_f32_e32 v2, v70, v6
	v_lshl_add_u64 v[48:49], s[68:69], 0, v[0:1]
	v_fmac_f32_e32 v2, v33, v5
	v_lshl_add_u64 v[0:1], v[48:49], 0, v[68:69]
	v_fmac_f32_e32 v2, v71, v7
	v_cvt_pk_bf16_f32 v2, v2, v15
	global_store_dword v[0:1], v2, off
	s_nop 0
	v_ashrrev_i32_e32 v33, 31, v32
	v_lshlrev_b64 v[0:1], 8, v[32:33]
	v_lshl_add_u64 v[0:1], s[56:57], 0, v[0:1]
	v_lshl_add_u64 v[58:59], v[0:1], 0, v[178:179]
	global_load_dwordx4 v[64:67], v[58:59], off
	ds_read_b128 v[4:7], v104 offset:256
	ds_read_b128 v[50:53], v104 offset:288
	global_load_dwordx4 v[68:71], v[58:59], off offset:32
	global_load_dwordx4 v[72:75], v[58:59], off offset:64
	global_load_dwordx4 v[76:79], v[58:59], off offset:96
	global_load_dwordx4 v[80:83], v[58:59], off offset:128
	global_load_dwordx4 v[84:87], v[58:59], off offset:160
	global_load_dwordx4 v[88:91], v[58:59], off offset:192
	global_load_dwordx4 v[92:95], v[58:59], off offset:224
	s_waitcnt vmcnt(6) lgkmcnt(0)
	v_mfma_f32_32x32x16_bf16 v[0:15], v[4:7], v[64:67], 0
	v_mfma_f32_32x32x16_bf16 v[0:15], v[50:53], v[68:71], v[0:15]
	ds_read_b128 v[50:53], v104 offset:320
	s_waitcnt vmcnt(5) lgkmcnt(0)
	v_mfma_f32_32x32x16_bf16 v[0:15], v[50:53], v[72:75], v[0:15]
	ds_read_b128 v[50:53], v104 offset:352
	s_waitcnt vmcnt(4) lgkmcnt(0)
	v_mfma_f32_32x32x16_bf16 v[0:15], v[50:53], v[76:79], v[0:15]
	ds_read_b128 v[50:53], v104 offset:384
	s_waitcnt vmcnt(3) lgkmcnt(0)
	v_mfma_f32_32x32x16_bf16 v[0:15], v[50:53], v[80:83], v[0:15]
	ds_read_b128 v[50:53], v104 offset:416
	s_waitcnt vmcnt(2) lgkmcnt(0)
	v_mfma_f32_32x32x16_bf16 v[0:15], v[50:53], v[84:87], v[0:15]
	ds_read_b128 v[50:53], v104 offset:448
	s_waitcnt vmcnt(1) lgkmcnt(0)
	v_mfma_f32_32x32x16_bf16 v[0:15], v[50:53], v[88:91], v[0:15]
	ds_read_b128 v[50:53], v104 offset:480
	s_waitcnt vmcnt(0) lgkmcnt(0)
	v_mfma_f32_32x32x16_bf16 v[0:15], v[50:53], v[92:95], v[0:15]
	v_lshlrev_b64 v[50:51], 2, v[32:33]
	v_lshl_add_u64 v[52:53], s[76:77], 0, v[50:51]
	v_add_co_u32_e32 v54, vcc, s4, v52
	v_lshl_add_u32 v32, v32, 1, 0
	s_nop 0
	v_addc_co_u32_e32 v55, vcc, 0, v53, vcc
	global_load_dword v33, v[54:55], off
	v_add_co_u32_e32 v54, vcc, s5, v52
	v_lshl_add_u64 v[16:17], v[16:17], 0, v[50:51]
	s_nop 0
	v_addc_co_u32_e32 v55, vcc, 0, v53, vcc
	global_load_dword v54, v[54:55], off offset:3072
	v_add_co_u32_e32 v52, vcc, s6, v52
	v_readlane_b32 s4, v252, 3
	s_nop 0
	v_addc_co_u32_e32 v53, vcc, 0, v53, vcc
	global_load_dword v52, v[52:53], off offset:2048
	v_add_u32_e32 v53, v32, v103
	ds_read_u16 v56, v53 offset:2048
	ds_read_u16 v57, v53 offset:5664
	ds_read_u16 v58, v53 offset:9280
	ds_read_u16 v59, v53 offset:12896
	ds_read_u16 v60, v53 offset:16512
	ds_read_u16 v61, v53 offset:20128
	s_waitcnt lgkmcnt(4)
	v_lshlrev_b32_e32 v57, 16, v57
	v_lshlrev_b32_e32 v56, 16, v56
	s_waitcnt lgkmcnt(3)
	v_lshlrev_b32_e32 v58, 16, v58
	s_waitcnt lgkmcnt(2)
	v_lshlrev_b32_e32 v59, 16, v59
	s_waitcnt lgkmcnt(1)
	v_lshlrev_b32_e32 v60, 16, v60
	s_waitcnt lgkmcnt(0)
	v_lshlrev_b32_e32 v61, 16, v61
	v_add_u32_e32 v55, 0x800, v53
	s_add_i32 s86, s86, s4
	s_cmpk_lt_i32 s86, 0x280
	v_readlane_b32 s5, v252, 4
	s_waitcnt vmcnt(1)
	v_mul_f32_e32 v62, v54, v57
	v_fmac_f32_e32 v62, v33, v56
	s_waitcnt vmcnt(0)
	v_fmac_f32_e32 v62, v52, v58
	v_cvt_pk_bf16_f32 v0, v62, v0
	global_store_dword v[16:17], v0, off
	v_mul_f32_e32 v0, v54, v58
	v_fmac_f32_e32 v0, v33, v57
	v_lshl_add_u64 v[16:17], v[18:19], 0, v[50:51]
	v_fmac_f32_e32 v0, v52, v59
	v_cvt_pk_bf16_f32 v0, v0, v1
	global_store_dword v[16:17], v0, off
	v_mul_f32_e32 v16, v54, v59
	v_fmac_f32_e32 v16, v33, v58
	v_lshl_add_u64 v[0:1], v[20:21], 0, v[50:51]
	v_fmac_f32_e32 v16, v52, v60
	v_cvt_pk_bf16_f32 v2, v16, v2
	global_store_dword v[0:1], v2, off
	v_mul_f32_e32 v2, v54, v60
	v_fmac_f32_e32 v2, v33, v59
	v_fmac_f32_e32 v2, v52, v61
	v_lshl_add_u64 v[0:1], v[22:23], 0, v[50:51]
	v_cvt_pk_bf16_f32 v2, v2, v3
	global_store_dword v[0:1], v2, off
	v_add_u32_e32 v2, v32, v105
	ds_read_u16 v0, v2 offset:2048
	s_waitcnt lgkmcnt(0)
	v_lshlrev_b32_e32 v3, 16, v0
	ds_read_u16 v0, v53 offset:34592
	s_waitcnt lgkmcnt(0)
	v_lshlrev_b32_e32 v16, 16, v0
	ds_read_u16 v0, v53 offset:38208
	v_mul_f32_e32 v21, v54, v16
	v_fmac_f32_e32 v21, v33, v3
	s_waitcnt lgkmcnt(0)
	v_lshlrev_b32_e32 v17, 16, v0
	ds_read_u16 v0, v53 offset:41824
	v_fmac_f32_e32 v21, v52, v17
	s_waitcnt lgkmcnt(0)
	v_lshlrev_b32_e32 v18, 16, v0
	ds_read_u16 v0, v53 offset:45440
	s_waitcnt lgkmcnt(0)
	v_lshlrev_b32_e32 v19, 16, v0
	ds_read_u16 v0, v53 offset:49056
	v_cvt_pk_bf16_f32 v3, v21, v4
	s_waitcnt lgkmcnt(0)
	v_lshlrev_b32_e32 v20, 16, v0
	v_lshl_add_u64 v[0:1], v[24:25], 0, v[50:51]
	global_store_dword v[0:1], v3, off
	v_mul_f32_e32 v3, v54, v17
	v_fmac_f32_e32 v3, v33, v16
	v_fmac_f32_e32 v3, v52, v18
	v_lshl_add_u64 v[0:1], v[26:27], 0, v[50:51]
	v_cvt_pk_bf16_f32 v3, v3, v5
	global_store_dword v[0:1], v3, off
	v_mul_f32_e32 v3, v54, v18
	v_fmac_f32_e32 v3, v33, v17
	v_fmac_f32_e32 v3, v52, v19
	v_lshl_add_u64 v[0:1], v[28:29], 0, v[50:51]
	v_cvt_pk_bf16_f32 v3, v3, v6
	global_store_dword v[0:1], v3, off
	v_mul_f32_e32 v3, v54, v19
	v_fmac_f32_e32 v3, v33, v18
	v_lshl_add_u64 v[0:1], v[30:31], 0, v[50:51]
	v_fmac_f32_e32 v3, v52, v20
	v_cvt_pk_bf16_f32 v3, v3, v7
	global_store_dword v[0:1], v3, off
	ds_read_u16 v0, v2 offset:30976
	s_waitcnt lgkmcnt(0)
	v_lshlrev_b32_e32 v3, 16, v0
	ds_read_u16 v0, v53 offset:63520
	s_waitcnt lgkmcnt(0)
	v_lshlrev_b32_e32 v4, 16, v0
	ds_read_u16 v0, v55 offset:65088
	v_mul_f32_e32 v17, v54, v4
	v_fmac_f32_e32 v17, v33, v3
	s_waitcnt lgkmcnt(0)
	v_lshlrev_b32_e32 v5, 16, v0
	v_add_u32_e32 v0, 0x11460, v53
	ds_read_u16 v0, v0
	v_fmac_f32_e32 v17, v52, v5
	s_waitcnt lgkmcnt(0)
	v_lshlrev_b32_e32 v6, 16, v0
	v_add_u32_e32 v0, 0x12280, v53
	ds_read_u16 v0, v0
	s_waitcnt lgkmcnt(0)
	v_lshlrev_b32_e32 v7, 16, v0
	v_add_u32_e32 v0, 0x130a0, v53
	ds_read_u16 v0, v0
	v_cvt_pk_bf16_f32 v3, v17, v8
	s_waitcnt lgkmcnt(0)
	v_lshlrev_b32_e32 v16, 16, v0
	v_lshl_add_u64 v[0:1], v[34:35], 0, v[50:51]
	global_store_dword v[0:1], v3, off
	v_mul_f32_e32 v3, v54, v5
	v_fmac_f32_e32 v3, v33, v4
	v_fmac_f32_e32 v3, v52, v6
	v_lshl_add_u64 v[0:1], v[36:37], 0, v[50:51]
	v_cvt_pk_bf16_f32 v3, v3, v9
	global_store_dword v[0:1], v3, off
	v_mul_f32_e32 v3, v54, v6
	v_fmac_f32_e32 v3, v33, v5
	v_fmac_f32_e32 v3, v52, v7
	v_lshl_add_u64 v[0:1], v[38:39], 0, v[50:51]
	v_cvt_pk_bf16_f32 v3, v3, v10
	global_store_dword v[0:1], v3, off
	v_mul_f32_e32 v3, v54, v7
	v_fmac_f32_e32 v3, v33, v6
	v_lshl_add_u64 v[0:1], v[40:41], 0, v[50:51]
	v_fmac_f32_e32 v3, v52, v16
	v_cvt_pk_bf16_f32 v3, v3, v11
	global_store_dword v[0:1], v3, off
	ds_read_u16 v0, v2 offset:59904
	s_waitcnt lgkmcnt(0)
	v_lshlrev_b32_e32 v2, 16, v0
	v_add_u32_e32 v0, 0x16920, v53
	ds_read_u16 v0, v0
	s_waitcnt lgkmcnt(0)
	v_lshlrev_b32_e32 v3, 16, v0
	v_add_u32_e32 v0, 0x17740, v53
	ds_read_u16 v0, v0
	v_mul_f32_e32 v8, v54, v3
	v_fmac_f32_e32 v8, v33, v2
	s_waitcnt lgkmcnt(0)
	v_lshlrev_b32_e32 v4, 16, v0
	v_add_u32_e32 v0, 0x18560, v53
	ds_read_u16 v0, v0
	v_fmac_f32_e32 v8, v52, v4
	s_waitcnt lgkmcnt(0)
	v_lshlrev_b32_e32 v5, 16, v0
	v_add_u32_e32 v0, 0x19380, v53
	ds_read_u16 v0, v0
	s_waitcnt lgkmcnt(0)
	v_lshlrev_b32_e32 v6, 16, v0
	v_add_u32_e32 v0, 0x1a1a0, v53
	ds_read_u16 v0, v0
	v_cvt_pk_bf16_f32 v2, v8, v12
	s_waitcnt lgkmcnt(0)
	v_lshlrev_b32_e32 v7, 16, v0
	v_lshl_add_u64 v[0:1], v[42:43], 0, v[50:51]
	global_store_dword v[0:1], v2, off
	v_mul_f32_e32 v2, v54, v4
	v_fmac_f32_e32 v2, v33, v3
	v_fmac_f32_e32 v2, v52, v5
	v_lshl_add_u64 v[0:1], v[44:45], 0, v[50:51]
	v_cvt_pk_bf16_f32 v2, v2, v13
	global_store_dword v[0:1], v2, off
	v_mul_f32_e32 v2, v54, v5
	v_fmac_f32_e32 v2, v33, v4
	v_fmac_f32_e32 v2, v52, v6
	v_lshl_add_u64 v[0:1], v[46:47], 0, v[50:51]
	v_cvt_pk_bf16_f32 v2, v2, v14
	global_store_dword v[0:1], v2, off
	v_mul_f32_e32 v2, v54, v6
	v_fmac_f32_e32 v2, v33, v5
	v_lshl_add_u64 v[0:1], v[48:49], 0, v[50:51]
	v_fmac_f32_e32 v2, v52, v7
	v_cvt_pk_bf16_f32 v2, v2, v15
	global_store_dword v[0:1], v2, off
	s_barrier
	s_cbranch_scc0 .LBB0_698

.LBB0_666:
	v_and_b32_e32 v35, 31, v60
	s_ashr_i32 s6, s39, 6
	s_andn2_b32 s39, s39, 63
	v_or_b32_e32 v34, s39, v35
	v_mov_b32_e32 v0, v34
	s_waitcnt lgkmcnt(0)
	s_barrier
	v_bfe_u32 v33, v60, 5, 1
	v_ashrrev_i32_e32 v1, 31, v0
	v_lshlrev_b64 v[2:3], 2, v[0:1]
	v_lshl_add_u64 v[4:5], s[76:77], 0, v[2:3]
	s_movk_i32 s7, 0x2000
	v_add_co_u32_e32 v6, vcc, s7, v4
	v_mul_u32_u24_e32 v1, 0x1c40, v33
	s_nop 0
	v_addc_co_u32_e32 v7, vcc, 0, v5, vcc
	s_movk_i32 s8, 0x4000
	v_lshlrev_b32_e32 v0, 1, v0
	v_lshlrev_b32_e32 v103, 1, v1
	global_load_dword v12, v[4:5], off offset:2048
	v_add_co_u32_e32 v4, vcc, s8, v4
	v_lshl_add_u64 v[2:3], s[84:85], 0, v[2:3]
	v_add3_u32 v0, 0, v0, v103
	v_addc_co_u32_e32 v5, vcc, 0, v5, vcc
	global_load_dword v26, v[2:3], off
	v_add_u32_e32 v1, 0x400, v0
	v_add_u32_e32 v2, 0x11060, v0
	v_or_b32_e32 v32, 32, v34
	global_load_dword v16, v[6:7], off offset:1024
	global_load_dword v22, v[4:5], off
	v_add_u32_e32 v3, 0x11e80, v0
	v_add_u32_e32 v4, 0x12ca0, v0
	v_add_u32_e32 v5, 0x15700, v0
	v_add_u32_e32 v6, 0x16520, v0
	v_add_u32_e32 v7, 0x17340, v0
	v_add_u32_e32 v8, 0x18160, v0
	v_add_u32_e32 v9, 0x18f80, v0
	v_add_u32_e32 v10, 0x19da0, v0
	ds_read_u16 v11, v0 offset:11872
	ds_read_u16 v15, v0 offset:15488
	ds_read_u16 v18, v0 offset:19104
	ds_read_u16 v19, v0 offset:8256
	ds_read_u16 v20, v0 offset:4640
	ds_read_u16 v21, v0 offset:1024
	ds_read_u16 v24, v0 offset:40800
	ds_read_u16 v25, v0 offset:44416
	ds_read_u16 v36, v0 offset:48032
	ds_read_u16 v37, v0 offset:37184
	ds_read_u16 v38, v0 offset:33568
	ds_read_u16 v39, v0 offset:29952
	ds_read_u16 v48, v2
	ds_read_u16 v49, v3
	ds_read_u16 v50, v4
	ds_read_u16 v14, v1 offset:65088
	ds_read_u16 v1, v0 offset:62496
	ds_read_u16 v0, v0 offset:58880
	ds_read_u16 v46, v8
	ds_read_u16 v45, v9
	ds_read_u16 v44, v10
	ds_read_u16 v43, v7
	ds_read_u16 v41, v6
	ds_read_u16 v40, v5
	v_mov_b32_e32 v2, v32
	s_waitcnt lgkmcnt(14)
	v_lshlrev_b32_e32 v10, 16, v20
	v_ashrrev_i32_e32 v3, 31, v2
	v_lshlrev_b64 v[4:5], 2, v[2:3]
	v_lshl_add_u64 v[6:7], s[76:77], 0, v[4:5]
	v_add_co_u32_e32 v8, vcc, s7, v6
	global_load_dword v13, v[6:7], off offset:2048
	s_nop 0
	v_addc_co_u32_e32 v9, vcc, 0, v7, vcc
	global_load_dword v17, v[8:9], off offset:1024
	v_add_co_u32_e32 v6, vcc, s8, v6
	v_lshl_add_u64 v[4:5], s[84:85], 0, v[4:5]
	s_nop 0
	v_addc_co_u32_e32 v7, vcc, 0, v7, vcc
	global_load_dword v23, v[6:7], off
	global_load_dword v27, v[4:5], off
	v_lshlrev_b32_e32 v2, 1, v2
	v_add3_u32 v47, 0, v2, v103
	ds_read_u16 v3, v47 offset:11872
	ds_read_u16 v5, v47 offset:15488
	ds_read_u16 v7, v47 offset:19104
	ds_read_u16 v9, v47 offset:8256
	v_lshlrev_b32_e32 v2, 16, v11
	ds_read_u16 v11, v47 offset:4640
	v_lshlrev_b32_e32 v4, 16, v15
	ds_read_u16 v15, v47 offset:1024
	v_lshlrev_b32_e32 v6, 16, v18
	v_lshlrev_b32_e32 v8, 16, v19
	s_waitcnt lgkmcnt(1)
	v_lshlrev_b32_e32 v11, 16, v11
	v_lshlrev_b32_e32 v18, 16, v21
	s_waitcnt lgkmcnt(0)
	v_lshlrev_b32_e32 v19, 16, v15
	v_lshlrev_b32_e32 v9, 16, v9
	v_lshlrev_b32_e32 v3, 16, v3
	v_lshlrev_b32_e32 v5, 16, v5
	v_lshlrev_b32_e32 v7, 16, v7
	v_add_u32_e32 v51, 0x400, v47
	v_lshlrev_b32_e32 v0, 16, v0
	v_lshlrev_b32_e32 v46, 16, v46
	v_cmp_lt_i32_e32 vcc, v208, v203
	v_lshlrev_b32_e32 v44, 16, v44
	s_mov_b32 s10, 0x2b8cbccc
	v_mov_b32_e32 v76, v34
	v_lshlrev_b32_e32 v178, 4, v33
	v_mul_u32_u24_e32 v42, 0x210, v35
	s_movk_i32 s9, 0x3000
	v_readlane_b32 s12, v255, 14
	v_readlane_b32 s13, v255, 15
	v_readlane_b32 s14, v255, 16
	v_readlane_b32 s15, v255, 17
	s_mov_b64 s[16:17], s[64:65]
	ds_read_u16 v15, v47 offset:33568
	s_waitcnt vmcnt(2)
	v_pk_mul_f32 v[20:21], v[16:17], v[10:11]
	s_nop 0
	v_pk_fma_f32 v[18:19], v[12:13], v[18:19], v[20:21]
	v_lshlrev_b32_e32 v20, 16, v39
	s_waitcnt vmcnt(1)
	v_pk_fma_f32 v[18:19], v[22:23], v[8:9], v[18:19]
	s_waitcnt vmcnt(0)
	v_pk_mul_f32 v[18:19], v[26:27], v[18:19]
	s_nop 0
	v_pk_mul_f32 v[28:29], v[18:19], v[18:19]
	v_pk_mul_f32 v[18:19], v[16:17], v[8:9]
	s_nop 0
	v_pk_fma_f32 v[10:11], v[12:13], v[10:11], v[18:19]
	v_lshlrev_b32_e32 v18, 16, v36
	v_pk_fma_f32 v[10:11], v[22:23], v[2:3], v[10:11]
	s_nop 0
	v_pk_mul_f32 v[10:11], v[26:27], v[10:11]
	s_nop 0
	v_pk_mul_f32 v[30:31], v[10:11], v[10:11]
	v_pk_mul_f32 v[10:11], v[16:17], v[2:3]
	s_nop 0
	v_pk_fma_f32 v[8:9], v[12:13], v[8:9], v[10:11]
	s_nop 0
	v_pk_fma_f32 v[8:9], v[22:23], v[4:5], v[8:9]
	v_pk_mul_f32 v[4:5], v[16:17], v[4:5]
	v_pk_mul_f32 v[8:9], v[26:27], v[8:9]
	v_pk_fma_f32 v[2:3], v[12:13], v[2:3], v[4:5]
	ds_read_u16 v4, v47 offset:44416
	ds_read_u16 v5, v47 offset:37184
	v_pk_fma_f32 v[2:3], v[22:23], v[6:7], v[2:3]
	v_lshlrev_b32_e32 v6, 16, v25
	v_pk_mul_f32 v[2:3], v[26:27], v[2:3]
	s_waitcnt lgkmcnt(1)
	v_lshlrev_b32_e32 v7, 16, v4
	v_pk_mul_f32 v[10:11], v[2:3], v[2:3]
	ds_read_u16 v3, v47 offset:40800
	ds_read_u16 v4, v47 offset:48032
	v_lshlrev_b32_e32 v25, 16, v15
	ds_read_u16 v15, v47 offset:29952
	v_lshlrev_b32_e32 v2, 16, v24
	v_lshlrev_b32_e32 v24, 16, v38
	s_waitcnt lgkmcnt(1)
	v_lshlrev_b32_e32 v19, 16, v4
	v_lshlrev_b32_e32 v4, 16, v37
	v_lshlrev_b32_e32 v5, 16, v5
	s_waitcnt lgkmcnt(0)
	v_lshlrev_b32_e32 v21, 16, v15
	v_pk_mul_f32 v[36:37], v[16:17], v[24:25]
	v_lshlrev_b32_e32 v3, 16, v3
	v_pk_fma_f32 v[20:21], v[12:13], v[20:21], v[36:37]
	v_pk_mul_f32 v[36:37], v[16:17], v[4:5]
	v_pk_fma_f32 v[20:21], v[22:23], v[4:5], v[20:21]
	v_pk_fma_f32 v[24:25], v[12:13], v[24:25], v[36:37]
	v_pk_mul_f32 v[36:37], v[16:17], v[2:3]
	v_pk_fma_f32 v[24:25], v[22:23], v[2:3], v[24:25]
	v_pk_fma_f32 v[4:5], v[12:13], v[4:5], v[36:37]
	v_add_u32_e32 v15, 0x11e80, v47
	v_pk_fma_f32 v[4:5], v[22:23], v[6:7], v[4:5]
	v_pk_mul_f32 v[6:7], v[16:17], v[6:7]
	ds_read_u16 v15, v15
	v_pk_fma_f32 v[2:3], v[12:13], v[2:3], v[6:7]
	v_lshlrev_b32_e32 v36, 16, v49
	v_pk_fma_f32 v[2:3], v[22:23], v[18:19], v[2:3]
	v_add_u32_e32 v18, 0x12ca0, v47
	v_pk_mul_f32 v[2:3], v[26:27], v[2:3]
	s_waitcnt lgkmcnt(0)
	v_lshlrev_b32_e32 v37, 16, v15
	v_pk_mul_f32 v[6:7], v[2:3], v[2:3]
	v_add_u32_e32 v2, 0x11060, v47
	ds_read_u16 v3, v2
	ds_read_u16 v15, v18
	v_lshlrev_b32_e32 v2, 16, v48
	v_lshlrev_b32_e32 v48, 16, v14
	ds_read_u16 v14, v47 offset:62496
	v_lshlrev_b32_e32 v18, 16, v1
	s_waitcnt lgkmcnt(1)
	v_lshlrev_b32_e32 v39, 16, v15
	ds_read_u16 v15, v51 offset:65088
	ds_read_u16 v1, v47 offset:58880
	s_waitcnt lgkmcnt(2)
	v_lshlrev_b32_e32 v19, 16, v14
	v_lshlrev_b32_e32 v3, 16, v3
	v_lshlrev_b32_e32 v38, 16, v50
	s_waitcnt lgkmcnt(1)
	v_lshlrev_b32_e32 v49, 16, v15
	s_waitcnt lgkmcnt(0)
	v_lshlrev_b32_e32 v1, 16, v1
	v_pk_mul_f32 v[14:15], v[16:17], v[18:19]
	v_add_u32_e32 v50, 0x19da0, v47
	v_pk_fma_f32 v[0:1], v[12:13], v[0:1], v[14:15]
	v_pk_mul_f32 v[8:9], v[8:9], v[8:9]
	v_pk_fma_f32 v[0:1], v[22:23], v[48:49], v[0:1]
	v_pk_mul_f32 v[20:21], v[26:27], v[20:21]
	v_pk_mul_f32 v[0:1], v[26:27], v[0:1]
	v_pk_mul_f32 v[24:25], v[26:27], v[24:25]
	v_pk_mul_f32 v[14:15], v[0:1], v[0:1]
	v_pk_mul_f32 v[0:1], v[16:17], v[48:49]
	v_pk_mul_f32 v[20:21], v[20:21], v[20:21]
	v_pk_fma_f32 v[0:1], v[12:13], v[18:19], v[0:1]
	v_pk_mul_f32 v[24:25], v[24:25], v[24:25]
	v_pk_fma_f32 v[0:1], v[22:23], v[2:3], v[0:1]
	v_pk_mul_f32 v[4:5], v[26:27], v[4:5]
	v_pk_mul_f32 v[0:1], v[26:27], v[0:1]
	v_pk_mul_f32 v[4:5], v[4:5], v[4:5]
	v_pk_mul_f32 v[18:19], v[0:1], v[0:1]
	v_pk_mul_f32 v[0:1], v[16:17], v[2:3]
	s_nop 0
	v_pk_fma_f32 v[0:1], v[12:13], v[48:49], v[0:1]
	v_add_u32_e32 v48, 0x18f80, v47
	v_pk_fma_f32 v[0:1], v[22:23], v[36:37], v[0:1]
	v_pk_mul_f32 v[36:37], v[16:17], v[36:37]
	v_pk_mul_f32 v[0:1], v[26:27], v[0:1]
	v_pk_fma_f32 v[2:3], v[12:13], v[2:3], v[36:37]
	v_add_u32_e32 v37, 0x18160, v47
	ds_read_u16 v37, v37
	v_pk_fma_f32 v[2:3], v[22:23], v[38:39], v[2:3]
	v_add_u32_e32 v39, 0x16520, v47
	v_add_u32_e32 v38, 0x15700, v47
	v_add_u32_e32 v36, 0x17340, v47
	ds_read_u16 v39, v39
	s_waitcnt lgkmcnt(1)
	v_lshlrev_b32_e32 v47, 16, v37
	ds_read_u16 v37, v48
	v_lshlrev_b32_e32 v48, 16, v45
	v_pk_mul_f32 v[2:3], v[26:27], v[2:3]
	s_waitcnt lgkmcnt(1)
	v_lshlrev_b32_e32 v51, 16, v39
	ds_read_u16 v39, v38
	s_waitcnt lgkmcnt(1)
	v_lshlrev_b32_e32 v49, 16, v37
	ds_read_u16 v37, v50
	v_lshlrev_b32_e32 v50, 16, v41
	v_lshlrev_b32_e32 v38, 16, v40
	s_waitcnt lgkmcnt(1)
	v_lshlrev_b32_e32 v39, 16, v39
	v_pk_mul_f32 v[40:41], v[16:17], v[50:51]
	s_waitcnt lgkmcnt(0)
	v_lshlrev_b32_e32 v45, 16, v37
	ds_read_u16 v37, v36
	v_lshlrev_b32_e32 v36, 16, v43
	v_pk_fma_f32 v[38:39], v[12:13], v[38:39], v[40:41]
	v_pk_mul_f32 v[0:1], v[0:1], v[0:1]
	v_pk_mul_f32 v[2:3], v[2:3], v[2:3]
	s_waitcnt lgkmcnt(0)
	v_lshlrev_b32_e32 v37, 16, v37
	v_pk_mul_f32 v[40:41], v[16:17], v[36:37]
	v_pk_fma_f32 v[38:39], v[22:23], v[36:37], v[38:39]
	v_pk_fma_f32 v[40:41], v[12:13], v[50:51], v[40:41]
	v_pk_mul_f32 v[50:51], v[16:17], v[46:47]
	v_pk_mul_f32 v[16:17], v[16:17], v[48:49]
	v_pk_fma_f32 v[36:37], v[12:13], v[36:37], v[50:51]
	v_pk_fma_f32 v[12:13], v[12:13], v[46:47], v[16:17]
	v_cndmask_b32_e32 v16, v202, v208, vcc
	v_cmp_lt_i32_e32 vcc, v211, v203
	v_lshlrev_b32_e32 v106, 2, v16
	v_mov_b32_e32 v17, v28
	v_cndmask_b32_e32 v16, v202, v211, vcc
	v_cmp_lt_i32_e32 vcc, v222, v203
	v_lshlrev_b32_e32 v107, 2, v16
	v_mov_b32_e32 v28, v31
	v_cndmask_b32_e32 v16, v202, v222, vcc
	v_cmp_lt_i32_e32 vcc, v209, v203
	v_lshlrev_b32_e32 v108, 2, v16
	v_pk_fma_f32 v[40:41], v[22:23], v[46:47], v[40:41]
	v_cndmask_b32_e32 v16, v202, v209, vcc
	v_cmp_lt_i32_e32 vcc, v251, v203
	v_lshlrev_b32_e32 v109, 2, v16
	v_pk_fma_f32 v[36:37], v[22:23], v[48:49], v[36:37]
	v_cndmask_b32_e32 v16, v202, v251, vcc
	v_lshlrev_b32_e32 v110, 2, v16
	v_mov_b32_e32 v16, v30
	v_pk_add_f32 v[16:17], v[16:17], v[28:29]
	v_pk_fma_f32 v[12:13], v[22:23], v[44:45], v[12:13]
	ds_bpermute_b32 v23, v106, v17
	ds_bpermute_b32 v22, v106, v16
	v_pk_mul_f32 v[38:39], v[26:27], v[38:39]
	v_pk_mul_f32 v[40:41], v[26:27], v[40:41]
	v_pk_mul_f32 v[38:39], v[38:39], v[38:39]
	v_pk_mul_f32 v[40:41], v[40:41], v[40:41]
	s_waitcnt lgkmcnt(0)
	v_pk_add_f32 v[16:17], v[16:17], v[22:23]
	ds_bpermute_b32 v23, v107, v17
	ds_bpermute_b32 v22, v107, v16
	v_pk_mul_f32 v[36:37], v[26:27], v[36:37]
	v_pk_mul_f32 v[12:13], v[26:27], v[12:13]
	v_pk_mul_f32 v[36:37], v[36:37], v[36:37]
	v_pk_mul_f32 v[12:13], v[12:13], v[12:13]
	s_waitcnt lgkmcnt(0)
	v_pk_add_f32 v[16:17], v[16:17], v[22:23]
	ds_bpermute_b32 v23, v108, v17
	ds_bpermute_b32 v22, v108, v16
	s_waitcnt lgkmcnt(0)
	v_pk_add_f32 v[16:17], v[16:17], v[22:23]
	ds_bpermute_b32 v23, v109, v17
	ds_bpermute_b32 v22, v109, v16
	v_ashrrev_i32_e32 v77, 31, v76
	s_waitcnt lgkmcnt(0)
	v_pk_add_f32 v[16:17], v[16:17], v[22:23]
	ds_bpermute_b32 v23, v110, v17
	ds_bpermute_b32 v22, v110, v16
	s_waitcnt lgkmcnt(0)
	v_pk_add_f32 v[16:17], v[16:17], v[22:23]
	s_nop 0
	v_pk_add_f32 v[16:17], v[16:17], s[10:11] op_sel_hi:[1,0]
	s_nop 0
	v_mul_f32_e32 v22, 0x4b800000, v17
	v_cmp_gt_f32_e64 s[4:5], s96, v17
	v_cmp_gt_f32_e32 vcc, s96, v16
	s_nop 0
	v_cndmask_b32_e64 v17, v17, v22, s[4:5]
	v_rsq_f32_e32 v17, v17
	s_nop 0
	v_mul_f32_e32 v22, 0x45800000, v17
	v_cndmask_b32_e64 v126, v17, v22, s[4:5]
	v_mul_f32_e32 v17, 0x4b800000, v16
	v_cndmask_b32_e32 v16, v16, v17, vcc
	v_rsq_f32_e32 v16, v16
	s_nop 0
	v_mul_f32_e32 v17, 0x45800000, v16
	v_cndmask_b32_e32 v124, v16, v17, vcc
	v_mov_b32_e32 v16, v10
	v_mov_b32_e32 v17, v8
	v_mov_b32_e32 v8, v11
	v_pk_add_f32 v[8:9], v[16:17], v[8:9]
	ds_bpermute_b32 v11, v106, v9
	ds_bpermute_b32 v10, v106, v8
	s_waitcnt lgkmcnt(0)
	v_pk_add_f32 v[8:9], v[8:9], v[10:11]
	ds_bpermute_b32 v11, v107, v9
	ds_bpermute_b32 v10, v107, v8
	s_waitcnt lgkmcnt(0)
	v_pk_add_f32 v[8:9], v[8:9], v[10:11]
	ds_bpermute_b32 v11, v108, v9
	ds_bpermute_b32 v10, v108, v8
	s_waitcnt lgkmcnt(0)
	v_pk_add_f32 v[8:9], v[8:9], v[10:11]
	ds_bpermute_b32 v11, v109, v9
	ds_bpermute_b32 v10, v109, v8
	s_waitcnt lgkmcnt(0)
	v_pk_add_f32 v[8:9], v[8:9], v[10:11]
	ds_bpermute_b32 v11, v110, v9
	ds_bpermute_b32 v10, v110, v8
	s_waitcnt lgkmcnt(0)
	v_pk_add_f32 v[8:9], v[8:9], v[10:11]
	s_nop 0
	v_pk_add_f32 v[8:9], v[8:9], s[10:11] op_sel_hi:[1,0]
	s_nop 0
	v_mul_f32_e32 v10, 0x4b800000, v9
	v_cmp_gt_f32_e64 s[4:5], s96, v9
	v_cmp_gt_f32_e32 vcc, s96, v8
	s_nop 0
	v_cndmask_b32_e64 v9, v9, v10, s[4:5]
	v_rsq_f32_e32 v9, v9
	s_nop 0
	v_mul_f32_e32 v10, 0x45800000, v9
	v_cndmask_b32_e64 v127, v9, v10, s[4:5]
	v_mul_f32_e32 v9, 0x4b800000, v8
	v_cndmask_b32_e32 v8, v8, v9, vcc
	v_rsq_f32_e32 v8, v8
	s_nop 0
	v_mul_f32_e32 v9, 0x45800000, v8
	v_cndmask_b32_e32 v125, v8, v9, vcc
	v_mov_b32_e32 v8, v24
	v_mov_b32_e32 v9, v20
	v_mov_b32_e32 v20, v25
	v_pk_add_f32 v[8:9], v[8:9], v[20:21]
	ds_bpermute_b32 v11, v106, v9
	ds_bpermute_b32 v10, v106, v8
	s_waitcnt lgkmcnt(0)
	v_pk_add_f32 v[8:9], v[8:9], v[10:11]
	ds_bpermute_b32 v11, v107, v9
	ds_bpermute_b32 v10, v107, v8
	s_waitcnt lgkmcnt(0)
	v_pk_add_f32 v[8:9], v[8:9], v[10:11]
	ds_bpermute_b32 v11, v108, v9
	ds_bpermute_b32 v10, v108, v8
	s_waitcnt lgkmcnt(0)
	v_pk_add_f32 v[8:9], v[8:9], v[10:11]
	ds_bpermute_b32 v11, v109, v9
	ds_bpermute_b32 v10, v109, v8
	s_waitcnt lgkmcnt(0)
	v_pk_add_f32 v[8:9], v[8:9], v[10:11]
	ds_bpermute_b32 v11, v110, v9
	ds_bpermute_b32 v10, v110, v8
	s_waitcnt lgkmcnt(0)
	v_pk_add_f32 v[8:9], v[8:9], v[10:11]
	s_nop 0
	v_pk_add_f32 v[8:9], v[8:9], s[10:11] op_sel_hi:[1,0]
	s_nop 0
	v_mul_f32_e32 v10, 0x4b800000, v9
	v_cmp_gt_f32_e64 s[4:5], s96, v9
	v_cmp_gt_f32_e32 vcc, s96, v8
	s_nop 0
	v_cndmask_b32_e64 v9, v9, v10, s[4:5]
	v_rsq_f32_e32 v9, v9
	s_nop 0
	v_mul_f32_e32 v10, 0x45800000, v9
	v_cndmask_b32_e64 v122, v9, v10, s[4:5]
	v_mul_f32_e32 v9, 0x4b800000, v8
	v_cndmask_b32_e32 v8, v8, v9, vcc
	v_rsq_f32_e32 v8, v8
	s_nop 0
	v_mul_f32_e32 v9, 0x45800000, v8
	v_cndmask_b32_e32 v120, v8, v9, vcc
	v_mov_b32_e32 v8, v6
	v_mov_b32_e32 v9, v4
	v_mov_b32_e32 v4, v7
	v_pk_add_f32 v[4:5], v[8:9], v[4:5]
	ds_bpermute_b32 v7, v106, v5
	ds_bpermute_b32 v6, v106, v4
	s_waitcnt lgkmcnt(0)
	v_pk_add_f32 v[4:5], v[4:5], v[6:7]
	ds_bpermute_b32 v7, v107, v5
	ds_bpermute_b32 v6, v107, v4
	s_waitcnt lgkmcnt(0)
	v_pk_add_f32 v[4:5], v[4:5], v[6:7]
	ds_bpermute_b32 v7, v108, v5
	ds_bpermute_b32 v6, v108, v4
	s_waitcnt lgkmcnt(0)
	v_pk_add_f32 v[4:5], v[4:5], v[6:7]
	ds_bpermute_b32 v7, v109, v5
	ds_bpermute_b32 v6, v109, v4
	s_waitcnt lgkmcnt(0)
	v_pk_add_f32 v[4:5], v[4:5], v[6:7]
	ds_bpermute_b32 v7, v110, v5
	ds_bpermute_b32 v6, v110, v4
	s_waitcnt lgkmcnt(0)
	v_pk_add_f32 v[4:5], v[4:5], v[6:7]
	s_nop 0
	v_pk_add_f32 v[4:5], v[4:5], s[10:11] op_sel_hi:[1,0]
	s_nop 0
	v_mul_f32_e32 v6, 0x4b800000, v5
	v_cmp_gt_f32_e64 s[4:5], s96, v5
	v_cmp_gt_f32_e32 vcc, s96, v4
	s_nop 0
	v_cndmask_b32_e64 v5, v5, v6, s[4:5]
	v_rsq_f32_e32 v5, v5
	s_nop 0
	v_mul_f32_e32 v6, 0x45800000, v5
	v_cndmask_b32_e64 v123, v5, v6, s[4:5]
	v_mul_f32_e32 v5, 0x4b800000, v4
	v_cndmask_b32_e32 v4, v4, v5, vcc
	v_rsq_f32_e32 v4, v4
	s_nop 0
	v_mul_f32_e32 v5, 0x45800000, v4
	v_cndmask_b32_e32 v121, v4, v5, vcc
	v_mov_b32_e32 v4, v18
	v_mov_b32_e32 v5, v14
	v_mov_b32_e32 v14, v19
	v_pk_add_f32 v[4:5], v[4:5], v[14:15]
	ds_bpermute_b32 v7, v106, v5
	ds_bpermute_b32 v6, v106, v4
	s_waitcnt lgkmcnt(0)
	v_pk_add_f32 v[4:5], v[4:5], v[6:7]
	ds_bpermute_b32 v7, v107, v5
	ds_bpermute_b32 v6, v107, v4
	s_waitcnt lgkmcnt(0)
	v_pk_add_f32 v[4:5], v[4:5], v[6:7]
	ds_bpermute_b32 v7, v108, v5
	ds_bpermute_b32 v6, v108, v4
	s_waitcnt lgkmcnt(0)
	v_pk_add_f32 v[4:5], v[4:5], v[6:7]
	ds_bpermute_b32 v7, v109, v5
	ds_bpermute_b32 v6, v109, v4
	s_waitcnt lgkmcnt(0)
	v_pk_add_f32 v[4:5], v[4:5], v[6:7]
	ds_bpermute_b32 v7, v110, v5
	ds_bpermute_b32 v6, v110, v4
	s_waitcnt lgkmcnt(0)
	v_pk_add_f32 v[4:5], v[4:5], v[6:7]
	s_nop 0
	v_pk_add_f32 v[4:5], v[4:5], s[10:11] op_sel_hi:[1,0]
	s_nop 0
	v_mul_f32_e32 v6, 0x4b800000, v5
	v_cmp_gt_f32_e64 s[4:5], s96, v5
	v_cmp_gt_f32_e32 vcc, s96, v4
	s_nop 0
	v_cndmask_b32_e64 v5, v5, v6, s[4:5]
	v_rsq_f32_e32 v5, v5
	s_nop 0
	v_mul_f32_e32 v6, 0x45800000, v5
	v_cndmask_b32_e64 v119, v5, v6, s[4:5]
	v_mul_f32_e32 v5, 0x4b800000, v4
	v_cndmask_b32_e32 v4, v4, v5, vcc
	v_rsq_f32_e32 v4, v4
	s_nop 0
	v_mul_f32_e32 v5, 0x45800000, v4
	v_cndmask_b32_e32 v117, v4, v5, vcc
	v_mov_b32_e32 v4, v2
	v_mov_b32_e32 v5, v0
	v_mov_b32_e32 v0, v3
	v_pk_add_f32 v[0:1], v[4:5], v[0:1]
	ds_bpermute_b32 v3, v106, v1
	ds_bpermute_b32 v2, v106, v0
	s_waitcnt lgkmcnt(0)
	v_pk_add_f32 v[0:1], v[0:1], v[2:3]
	ds_bpermute_b32 v3, v107, v1
	ds_bpermute_b32 v2, v107, v0
	s_waitcnt lgkmcnt(0)
	v_pk_add_f32 v[0:1], v[0:1], v[2:3]
	ds_bpermute_b32 v3, v108, v1
	ds_bpermute_b32 v2, v108, v0
	s_waitcnt lgkmcnt(0)
	v_pk_add_f32 v[0:1], v[0:1], v[2:3]
	ds_bpermute_b32 v3, v109, v1
	ds_bpermute_b32 v2, v109, v0
	s_waitcnt lgkmcnt(0)
	v_pk_add_f32 v[0:1], v[0:1], v[2:3]
	ds_bpermute_b32 v3, v110, v1
	ds_bpermute_b32 v2, v110, v0
	s_waitcnt lgkmcnt(0)
	v_pk_add_f32 v[0:1], v[0:1], v[2:3]
	s_nop 0
	v_pk_add_f32 v[0:1], v[0:1], s[10:11] op_sel_hi:[1,0]
	s_nop 0
	v_mul_f32_e32 v2, 0x4b800000, v1
	v_cmp_gt_f32_e64 s[4:5], s96, v1
	v_cmp_gt_f32_e32 vcc, s96, v0
	s_nop 0
	v_cndmask_b32_e64 v1, v1, v2, s[4:5]
	v_rsq_f32_e32 v1, v1
	s_nop 0
	v_mul_f32_e32 v2, 0x45800000, v1
	v_cndmask_b32_e64 v118, v1, v2, s[4:5]
	v_mul_f32_e32 v1, 0x4b800000, v0
	v_cndmask_b32_e32 v0, v0, v1, vcc
	v_rsq_f32_e32 v0, v0
	s_nop 0
	v_mul_f32_e32 v1, 0x45800000, v0
	v_cndmask_b32_e32 v116, v0, v1, vcc
	v_mov_b32_e32 v0, v40
	v_mov_b32_e32 v1, v38
	v_mov_b32_e32 v38, v41
	v_pk_add_f32 v[0:1], v[0:1], v[38:39]
	ds_bpermute_b32 v3, v106, v1
	ds_bpermute_b32 v2, v106, v0
	s_waitcnt lgkmcnt(0)
	v_pk_add_f32 v[0:1], v[0:1], v[2:3]
	ds_bpermute_b32 v3, v107, v1
	ds_bpermute_b32 v2, v107, v0
	s_waitcnt lgkmcnt(0)
	v_pk_add_f32 v[0:1], v[0:1], v[2:3]
	ds_bpermute_b32 v3, v108, v1
	ds_bpermute_b32 v2, v108, v0
	s_waitcnt lgkmcnt(0)
	v_pk_add_f32 v[0:1], v[0:1], v[2:3]
	ds_bpermute_b32 v3, v109, v1
	ds_bpermute_b32 v2, v109, v0
	s_waitcnt lgkmcnt(0)
	v_pk_add_f32 v[0:1], v[0:1], v[2:3]
	ds_bpermute_b32 v3, v110, v1
	ds_bpermute_b32 v2, v110, v0
	s_waitcnt lgkmcnt(0)
	v_pk_add_f32 v[0:1], v[0:1], v[2:3]
	s_nop 0
	v_pk_add_f32 v[0:1], v[0:1], s[10:11] op_sel_hi:[1,0]
	s_nop 0
	v_mul_f32_e32 v2, 0x4b800000, v1
	v_cmp_gt_f32_e64 s[4:5], s96, v1
	v_cmp_gt_f32_e32 vcc, s96, v0
	s_nop 0
	v_cndmask_b32_e64 v1, v1, v2, s[4:5]
	v_rsq_f32_e32 v1, v1
	s_nop 0
	v_mul_f32_e32 v2, 0x45800000, v1
	v_cndmask_b32_e64 v114, v1, v2, s[4:5]
	v_mul_f32_e32 v1, 0x4b800000, v0
	v_cndmask_b32_e32 v0, v0, v1, vcc
	v_rsq_f32_e32 v0, v0
	s_nop 0
	v_mul_f32_e32 v1, 0x45800000, v0
	v_cndmask_b32_e32 v113, v0, v1, vcc
	v_mov_b32_e32 v0, v12
	v_mov_b32_e32 v1, v36
	v_mov_b32_e32 v36, v13
	v_pk_add_f32 v[0:1], v[0:1], v[36:37]
	ds_bpermute_b32 v3, v106, v1
	ds_bpermute_b32 v2, v106, v0
	s_waitcnt lgkmcnt(0)
	v_pk_add_f32 v[0:1], v[0:1], v[2:3]
	ds_bpermute_b32 v3, v107, v1
	ds_bpermute_b32 v2, v107, v0
	s_waitcnt lgkmcnt(0)
	v_pk_add_f32 v[0:1], v[0:1], v[2:3]
	ds_bpermute_b32 v3, v108, v1
	ds_bpermute_b32 v2, v108, v0
	s_waitcnt lgkmcnt(0)
	v_pk_add_f32 v[0:1], v[0:1], v[2:3]
	ds_bpermute_b32 v3, v109, v1
	ds_bpermute_b32 v2, v109, v0
	s_waitcnt lgkmcnt(0)
	v_pk_add_f32 v[0:1], v[0:1], v[2:3]
	ds_bpermute_b32 v3, v110, v1
	ds_bpermute_b32 v2, v110, v0
	s_waitcnt lgkmcnt(0)
	v_pk_add_f32 v[0:1], v[0:1], v[2:3]
	s_nop 0
	v_pk_add_f32 v[0:1], v[0:1], s[10:11] op_sel_hi:[1,0]
	s_mov_b64 s[10:11], 0x10000
	v_mul_f32_e32 v2, 0x4b800000, v1
	v_cmp_gt_f32_e64 s[4:5], s96, v1
	v_cmp_gt_f32_e32 vcc, s96, v0
	s_nop 0
	v_cndmask_b32_e64 v1, v1, v2, s[4:5]
	v_rsq_f32_e32 v1, v1
	s_nop 0
	v_mul_f32_e32 v2, 0x45800000, v1
	v_cndmask_b32_e64 v112, v1, v2, s[4:5]
	v_mul_f32_e32 v1, 0x4b800000, v0
	v_cndmask_b32_e32 v0, v0, v1, vcc
	v_rsq_f32_e32 v0, v0
	s_mov_b32 s5, 0x10000
	v_readlane_b32 s4, v254, 33
	v_mul_f32_e32 v1, 0x45800000, v0
	v_cndmask_b32_e32 v111, v0, v1, vcc
	v_lshlrev_b64 v[0:1], 7, v[76:77]
	v_lshl_add_u64 v[0:1], s[72:73], 0, v[0:1]
	v_lshl_add_u64 v[38:39], v[0:1], 0, v[178:179]
	v_add_co_u32_e32 v4, vcc, s5, v38
	global_load_dwordx4 v[52:55], v[38:39], off
	s_nop 0
	v_addc_co_u32_e32 v5, vcc, 0, v39, vcc
	global_load_dwordx4 v[56:59], v[4:5], off
	v_add3_u32 v104, s4, v42, v178
	v_lshl_add_u64 v[36:37], v[38:39], 0, s[10:11]
	ds_read_b128 v[8:11], v104 offset:128
	ds_read_b128 v[40:43], v104 offset:160
	global_load_dwordx4 v[60:63], v[38:39], off offset:32
	global_load_dwordx4 v[68:71], v[36:37], off offset:32
	global_load_dwordx4 v[72:75], v[38:39], off offset:64
	global_load_dwordx4 v[80:83], v[36:37], off offset:64
	global_load_dwordx4 v[84:87], v[38:39], off offset:96
	global_load_dwordx4 v[88:91], v[36:37], off offset:96
	s_waitcnt vmcnt(4) lgkmcnt(0)
	v_mfma_f32_32x32x16_bf16 v[16:31], v[8:11], v[52:55], 0
	s_movk_i32 s4, 0x1000
	v_mfma_f32_32x32x16_bf16 v[0:15], v[8:11], v[56:59], 0
	v_mfma_f32_32x32x16_bf16 v[16:31], v[40:43], v[60:63], v[16:31]
	v_mfma_f32_32x32x16_bf16 v[0:15], v[40:43], v[68:71], v[0:15]
	ds_read_b128 v[40:43], v104 offset:192
	s_waitcnt vmcnt(2) lgkmcnt(0)
	v_mfma_f32_32x32x16_bf16 v[16:31], v[40:43], v[72:75], v[16:31]
	v_mfma_f32_32x32x16_bf16 v[0:15], v[40:43], v[80:83], v[0:15]
	ds_read_b128 v[40:43], v104 offset:224
	s_nop 0
	s_waitcnt vmcnt(0) lgkmcnt(0)
	v_mfma_f32_32x32x16_bf16 v[0:15], v[40:43], v[88:91], v[0:15]
	v_lshlrev_b64 v[36:37], 2, v[76:77]
	v_lshl_add_u64 v[38:39], s[76:77], 0, v[36:37]
	global_load_dword v66, v[38:39], off
	v_mfma_f32_32x32x16_bf16 v[16:31], v[40:43], v[84:87], v[16:31]
	v_add_co_u32_e32 v40, vcc, s4, v38
	v_lshl_add_u32 v44, v76, 1, 0
	s_nop 0
	v_addc_co_u32_e32 v41, vcc, 0, v39, vcc
	global_load_dword v67, v[40:41], off offset:3072
	v_add_co_u32_e32 v40, vcc, s9, v38
	v_add_u32_e32 v60, v44, v103
	s_nop 0
	v_addc_co_u32_e32 v41, vcc, 0, v39, vcc
	global_load_dword v101, v[40:41], off offset:2048
	global_load_dword v100, v[38:39], off offset:2048
	v_add_co_u32_e32 v40, vcc, s7, v38
	v_lshlrev_b32_e32 v45, 2, v33
	s_nop 0
	v_addc_co_u32_e32 v41, vcc, 0, v39, vcc
	v_add_co_u32_e32 v38, vcc, s8, v38
	global_load_dword v172, v[40:41], off offset:1024
	s_nop 0
	v_addc_co_u32_e32 v39, vcc, 0, v39, vcc
	global_load_dword v174, v[38:39], off
	v_lshl_add_u64 v[38:39], s[12:13], 0, v[36:37]
	global_load_dword v175, v[38:39], off
	global_load_dword v173, v[38:39], off offset:2048
	v_lshl_add_u64 v[38:39], s[84:85], 0, v[36:37]
	global_load_dword v176, v[38:39], off
	v_lshl_add_u64 v[38:39], s[14:15], 0, v[36:37]
	global_load_dword v177, v[38:39], off
	v_lshl_add_u64 v[36:37], s[16:17], 0, v[36:37]
	global_load_dword v115, v[36:37], off
	ds_read_u16 v36, v60
	s_waitcnt lgkmcnt(0)
	v_lshlrev_b32_e32 v37, 16, v36
	ds_read_u16 v36, v60 offset:1024
	s_waitcnt lgkmcnt(0)
	v_lshlrev_b32_e32 v38, 16, v36
	ds_read_u16 v36, v60 offset:3616
	s_waitcnt lgkmcnt(0)
	v_lshlrev_b32_e32 v42, 16, v36
	ds_read_u16 v36, v60 offset:4640
	s_waitcnt lgkmcnt(0)
	v_lshlrev_b32_e32 v43, 16, v36
	ds_read_u16 v36, v60 offset:7232
	s_waitcnt lgkmcnt(0)
	v_lshlrev_b32_e32 v46, 16, v36
	ds_read_u16 v36, v60 offset:8256
	s_waitcnt lgkmcnt(0)
	v_lshlrev_b32_e32 v47, 16, v36
	ds_read_u16 v36, v60 offset:10848
	s_waitcnt lgkmcnt(0)
	v_lshlrev_b32_e32 v48, 16, v36
	ds_read_u16 v36, v60 offset:11872
	s_waitcnt lgkmcnt(0)
	v_lshlrev_b32_e32 v49, 16, v36
	ds_read_u16 v36, v60 offset:14464
	s_waitcnt lgkmcnt(0)
	v_lshlrev_b32_e32 v50, 16, v36
	ds_read_u16 v36, v60 offset:15488
	s_waitcnt vmcnt(9)
	v_mul_f32_e32 v54, v67, v42
	v_fmac_f32_e32 v54, v66, v37
	v_mul_f32_e32 v128, v67, v46
	v_fmac_f32_e32 v128, v66, v42
	s_waitcnt lgkmcnt(0)
	v_lshlrev_b32_e32 v51, 16, v36
	ds_read_u16 v36, v60 offset:18080
	s_waitcnt vmcnt(8)
	v_fmac_f32_e32 v54, v101, v46
	v_fmac_f32_e32 v128, v101, v48
	v_mul_f32_e32 v129, v67, v48
	v_fmac_f32_e32 v129, v66, v46
	s_waitcnt lgkmcnt(0)
	v_lshlrev_b32_e32 v52, 16, v36
	ds_read_u16 v36, v60 offset:19104
	v_fmac_f32_e32 v129, v101, v50
	s_waitcnt vmcnt(6)
	v_mul_f32_e32 v40, v172, v43
	v_fmac_f32_e32 v40, v100, v38
	v_mul_f32_e32 v133, v67, v50
	s_waitcnt vmcnt(5)
	v_fmac_f32_e32 v40, v174, v47
	s_waitcnt vmcnt(4)
	v_add_f32_e32 v16, v16, v175
	s_waitcnt vmcnt(3)
	v_add_f32_e32 v0, v0, v173
	v_mul_f32_e32 v0, 0xbfb8aa3b, v0
	v_mul_f32_e32 v16, 0xbfb8aa3b, v16
	v_exp_f32_e32 v0, v0
	v_exp_f32_e32 v16, v16
	s_waitcnt lgkmcnt(0)
	v_lshlrev_b32_e32 v53, 16, v36
	v_or_b32_e32 v36, s82, v45
	v_add_f32_e32 v0, 1.0, v0
	v_add_f32_e32 v16, 1.0, v16
	v_rcp_f32_e32 v0, v0
	v_rcp_f32_e32 v16, v16
	s_waitcnt vmcnt(2)
	v_mul_f32_e32 v41, v176, v40
	v_ashrrev_i32_e32 v37, 31, v36
	v_add_f32_e32 v57, -1.0, v0
	v_mul_f32_e32 v55, v126, v41
	v_add_f32_e32 v41, -1.0, v16
	s_waitcnt vmcnt(1)
	v_fma_f32 v57, v177, v57, 1.0
	v_lshlrev_b64 v[74:75], 9, v[36:37]
	v_fma_f32 v41, v177, v41, 1.0
	v_mul_f32_e32 v57, v57, v40
	v_lshl_add_u64 v[38:39], v[74:75], 0, v[76:77]
	v_mul_f32_e32 v56, v41, v40
	v_fma_f32 v40, v41, v40, v57
	v_mul_f32_e32 v40, v54, v40
	v_lshlrev_b64 v[38:39], 2, v[38:39]
	s_waitcnt vmcnt(0)
	v_fma_f32 v132, v115, v40, 0
	v_lshl_add_u64 v[40:41], s[60:61], 0, v[38:39]
	v_cvt_pk_bf16_f32 v54, v54, v55
	global_store_dword v[40:41], v54, off
	v_lshl_add_u64 v[40:41], s[62:63], 0, v[38:39]
	v_mul_f32_e32 v16, v16, v55
	v_mul_f32_e32 v0, v0, v55
	v_cvt_pk_bf16_f32 v54, v56, v57
	global_store_dword v[40:41], v54, off
	v_cvt_pk_bf16_f32 v0, v16, v0
	v_add_f32_e32 v16, v17, v175
	v_mul_f32_e32 v16, 0xbfb8aa3b, v16
	v_exp_f32_e32 v16, v16
	v_add_f32_e32 v1, v1, v173
	v_mul_f32_e32 v1, 0xbfb8aa3b, v1
	v_exp_f32_e32 v1, v1
	v_lshl_add_u64 v[38:39], s[66:67], 0, v[38:39]
	v_add_f32_e32 v16, 1.0, v16
	global_store_dword v[38:39], v0, off
	v_mul_f32_e32 v0, v172, v47
	v_rcp_f32_e32 v42, v16
	v_fmac_f32_e32 v0, v100, v43
	v_add_f32_e32 v1, 1.0, v1
	v_fmac_f32_e32 v0, v174, v49
	v_rcp_f32_e32 v43, v1
	v_mul_f32_e32 v1, v176, v0
	v_or_b32_e32 v38, 1, v36
	v_mul_f32_e32 v54, v124, v1
	v_add_f32_e32 v1, -1.0, v42
	v_ashrrev_i32_e32 v39, 31, v38
	v_fma_f32 v1, v177, v1, 1.0
	v_lshlrev_b64 v[72:73], 9, v[38:39]
	v_mul_f32_e32 v130, v1, v0
	v_add_f32_e32 v1, -1.0, v43
	v_lshl_add_u64 v[40:41], v[72:73], 0, v[76:77]
	v_fma_f32 v1, v177, v1, 1.0
	v_mul_f32_e32 v131, v1, v0
	v_lshlrev_b64 v[0:1], 2, v[40:41]
	v_lshl_add_u64 v[16:17], s[60:61], 0, v[0:1]
	v_cvt_pk_bf16_f32 v40, v128, v54
	global_store_dword v[16:17], v40, off
	v_lshl_add_u64 v[16:17], s[62:63], 0, v[0:1]
	v_cvt_pk_bf16_f32 v40, v130, v131
	global_store_dword v[16:17], v40, off
	v_mul_f32_e32 v16, v42, v54
	v_mul_f32_e32 v17, v43, v54
	v_cvt_pk_bf16_f32 v16, v16, v17
	v_add_f32_e32 v17, v18, v175
	v_mul_f32_e32 v17, 0xbfb8aa3b, v17
	v_exp_f32_e32 v17, v17
	v_add_f32_e32 v2, v2, v173
	v_mul_f32_e32 v2, 0xbfb8aa3b, v2
	v_exp_f32_e32 v2, v2
	v_lshl_add_u64 v[0:1], s[66:67], 0, v[0:1]
	v_add_f32_e32 v17, 1.0, v17
	global_store_dword v[0:1], v16, off
	v_mul_f32_e32 v16, v172, v49
	v_rcp_f32_e32 v18, v17
	v_fmac_f32_e32 v16, v100, v47
	v_add_f32_e32 v2, 1.0, v2
	v_fmac_f32_e32 v16, v174, v51
	v_rcp_f32_e32 v2, v2
	v_or_b32_e32 v40, 2, v36
	v_mul_f32_e32 v17, v176, v16
	v_ashrrev_i32_e32 v41, 31, v40
	v_mul_f32_e32 v42, v127, v17
	v_add_f32_e32 v17, -1.0, v18
	v_lshlrev_b64 v[70:71], 9, v[40:41]
	v_fma_f32 v17, v177, v17, 1.0
	v_lshl_add_u64 v[0:1], v[70:71], 0, v[76:77]
	v_mul_f32_e32 v134, v17, v16
	v_add_f32_e32 v17, -1.0, v2
	v_fma_f32 v17, v177, v17, 1.0
	v_lshlrev_b64 v[0:1], 2, v[0:1]
	v_mul_f32_e32 v135, v17, v16
	v_lshl_add_u64 v[16:17], s[60:61], 0, v[0:1]
	v_cvt_pk_bf16_f32 v43, v129, v42
	global_store_dword v[16:17], v43, off
	v_lshl_add_u64 v[16:17], s[62:63], 0, v[0:1]
	v_cvt_pk_bf16_f32 v43, v134, v135
	global_store_dword v[16:17], v43, off
	v_mul_f32_e32 v16, v18, v42
	v_mul_f32_e32 v2, v2, v42
	v_cvt_pk_bf16_f32 v2, v16, v2
	v_add_f32_e32 v16, v19, v175
	v_mul_f32_e32 v16, 0xbfb8aa3b, v16
	v_exp_f32_e32 v16, v16
	v_add_f32_e32 v3, v3, v173
	v_mul_f32_e32 v3, 0xbfb8aa3b, v3
	v_exp_f32_e32 v3, v3
	v_lshl_add_u64 v[0:1], s[66:67], 0, v[0:1]
	v_add_f32_e32 v16, 1.0, v16
	global_store_dword v[0:1], v2, off
	v_mul_f32_e32 v2, v172, v51
	v_rcp_f32_e32 v16, v16
	v_fmac_f32_e32 v2, v100, v49
	v_add_f32_e32 v3, 1.0, v3
	v_fmac_f32_e32 v2, v174, v53
	v_rcp_f32_e32 v17, v3
	v_or_b32_e32 v42, 3, v36
	v_mul_f32_e32 v3, v176, v2
	v_ashrrev_i32_e32 v43, 31, v42
	v_mul_f32_e32 v18, v125, v3
	v_add_f32_e32 v3, -1.0, v16
	v_lshlrev_b64 v[68:69], 9, v[42:43]
	v_fma_f32 v3, v177, v3, 1.0
	v_lshl_add_u64 v[0:1], v[68:69], 0, v[76:77]
	v_mul_f32_e32 v136, v3, v2
	v_add_f32_e32 v3, -1.0, v17
	v_fma_f32 v3, v177, v3, 1.0
	v_lshlrev_b64 v[0:1], 2, v[0:1]
	v_fmac_f32_e32 v133, v66, v48
	v_mul_f32_e32 v137, v3, v2
	v_lshl_add_u64 v[2:3], s[60:61], 0, v[0:1]
	v_fmac_f32_e32 v133, v101, v52
	v_cvt_pk_bf16_f32 v19, v133, v18
	global_store_dword v[2:3], v19, off
	v_lshl_add_u64 v[2:3], s[62:63], 0, v[0:1]
	v_cvt_pk_bf16_f32 v19, v136, v137
	global_store_dword v[2:3], v19, off
	v_mul_f32_e32 v2, v16, v18
	v_lshl_add_u64 v[0:1], s[66:67], 0, v[0:1]
	v_mul_f32_e32 v3, v17, v18
	v_cvt_pk_bf16_f32 v2, v2, v3
	ds_read_u16 v16, v60 offset:32544
	global_store_dword v[0:1], v2, off
	v_or_b32_e32 v1, 8, v45
	v_mul_u32_u24_e32 v0, 0x710, v1
	v_lshlrev_b32_e32 v105, 1, v0
	v_add_u32_e32 v0, v44, v105
	ds_read_u16 v2, v0
	ds_read_u16 v3, v0 offset:1024
	s_waitcnt lgkmcnt(2)
	v_lshlrev_b32_e32 v18, 16, v16
	ds_read_u16 v16, v60 offset:33568
	v_add_f32_e32 v4, v4, v173
	v_mul_f32_e32 v4, 0xbfb8aa3b, v4
	v_exp_f32_e32 v4, v4
	s_waitcnt lgkmcnt(1)
	v_lshlrev_b32_e32 v3, 16, v3
	s_waitcnt lgkmcnt(0)
	v_lshlrev_b32_e32 v19, 16, v16
	ds_read_u16 v16, v60 offset:36160
	v_or_b32_e32 v44, s82, v1
	v_mul_f32_e32 v1, v172, v19
	v_fmac_f32_e32 v1, v100, v3
	v_add_f32_e32 v4, 1.0, v4
	s_waitcnt lgkmcnt(0)
	v_lshlrev_b32_e32 v48, 16, v16
	ds_read_u16 v16, v60 offset:37184
	v_rcp_f32_e32 v4, v4
	v_ashrrev_i32_e32 v45, 31, v44
	v_lshlrev_b32_e32 v2, 16, v2
	v_mul_f32_e32 v138, v67, v18
	s_waitcnt lgkmcnt(0)
	v_lshlrev_b32_e32 v49, 16, v16
	ds_read_u16 v16, v60 offset:39776
	v_fmac_f32_e32 v1, v174, v49
	v_lshlrev_b64 v[78:79], 9, v[44:45]
	v_fmac_f32_e32 v138, v66, v2
	v_lshl_add_u64 v[2:3], v[78:79], 0, v[76:77]
	s_waitcnt lgkmcnt(0)
	v_lshlrev_b32_e32 v50, 16, v16
	ds_read_u16 v16, v60 offset:40800
	v_lshlrev_b64 v[2:3], 2, v[2:3]
	v_fmac_f32_e32 v138, v101, v48
	v_mul_f32_e32 v139, v67, v48
	v_fmac_f32_e32 v139, v66, v18
	s_waitcnt lgkmcnt(0)
	v_lshlrev_b32_e32 v51, 16, v16
	ds_read_u16 v16, v60 offset:43392
	v_fmac_f32_e32 v139, v101, v50
	v_mul_f32_e32 v142, v67, v50
	v_fmac_f32_e32 v142, v66, v48
	v_or_b32_e32 v48, 2, v44
	s_waitcnt lgkmcnt(0)
	v_lshlrev_b32_e32 v52, 16, v16
	ds_read_u16 v16, v60 offset:44416
	v_fmac_f32_e32 v142, v101, v52
	v_mul_f32_e32 v145, v67, v52
	v_fmac_f32_e32 v145, v66, v50
	v_or_b32_e32 v50, 3, v44
	s_waitcnt lgkmcnt(0)
	v_lshlrev_b32_e32 v53, 16, v16
	ds_read_u16 v16, v60 offset:47008
	v_or_b32_e32 v52, 16, v36
	v_or_b32_e32 v56, 18, v36
	v_ashrrev_i32_e32 v57, 31, v56
	v_lshlrev_b64 v[90:91], 9, v[56:57]
	s_waitcnt lgkmcnt(0)
	v_lshlrev_b32_e32 v54, 16, v16
	ds_read_u16 v16, v60 offset:48032
	v_fmac_f32_e32 v145, v101, v54
	v_or_b32_e32 v58, 19, v36
	v_ashrrev_i32_e32 v59, 31, v58
	v_lshlrev_b64 v[92:93], 9, v[58:59]
	s_waitcnt lgkmcnt(0)
	v_lshlrev_b32_e32 v55, 16, v16
	v_add_f32_e32 v16, v20, v175
	v_mul_f32_e32 v16, 0xbfb8aa3b, v16
	v_exp_f32_e32 v16, v16
	v_or_b32_e32 v62, 25, v36
	v_ashrrev_i32_e32 v63, 31, v62
	v_lshlrev_b64 v[96:97], 9, v[62:63]
	v_add_f32_e32 v16, 1.0, v16
	v_rcp_f32_e32 v20, v16
	v_mul_f32_e32 v16, v176, v1
	v_mul_f32_e32 v46, v122, v16
	v_or_b32_e32 v64, 26, v36
	v_add_f32_e32 v16, -1.0, v20
	v_fma_f32 v16, v177, v16, 1.0
	v_mul_f32_e32 v140, v16, v1
	v_add_f32_e32 v16, -1.0, v4
	v_fma_f32 v16, v177, v16, 1.0
	v_mul_f32_e32 v141, v16, v1
	v_lshl_add_u64 v[16:17], s[60:61], 0, v[2:3]
	v_cvt_pk_bf16_f32 v1, v138, v46
	global_store_dword v[16:17], v1, off
	v_lshl_add_u64 v[16:17], s[62:63], 0, v[2:3]
	v_cvt_pk_bf16_f32 v1, v140, v141
	global_store_dword v[16:17], v1, off
	v_mul_f32_e32 v1, v20, v46
	v_mul_f32_e32 v4, v4, v46
	v_cvt_pk_bf16_f32 v1, v1, v4
	v_add_f32_e32 v4, v21, v175
	v_mul_f32_e32 v4, 0xbfb8aa3b, v4
	v_exp_f32_e32 v4, v4
	v_lshl_add_u64 v[2:3], s[66:67], 0, v[2:3]
	global_store_dword v[2:3], v1, off
	v_mul_f32_e32 v1, v172, v49
	v_add_f32_e32 v4, 1.0, v4
	v_rcp_f32_e32 v16, v4
	v_add_f32_e32 v4, v5, v173
	v_mul_f32_e32 v4, 0xbfb8aa3b, v4
	v_exp_f32_e32 v4, v4
	v_fmac_f32_e32 v1, v100, v19
	v_fmac_f32_e32 v1, v174, v51
	v_or_b32_e32 v46, 1, v44
	v_add_f32_e32 v4, 1.0, v4
	v_rcp_f32_e32 v17, v4
	v_mul_f32_e32 v4, v176, v1
	v_ashrrev_i32_e32 v47, 31, v46
	v_mul_f32_e32 v18, v120, v4
	v_add_f32_e32 v4, -1.0, v16
	v_lshlrev_b64 v[80:81], 9, v[46:47]
	v_fma_f32 v4, v177, v4, 1.0
	v_lshl_add_u64 v[2:3], v[80:81], 0, v[76:77]
	v_mul_f32_e32 v143, v4, v1
	v_add_f32_e32 v4, -1.0, v17
	v_fma_f32 v4, v177, v4, 1.0
	v_lshlrev_b64 v[2:3], 2, v[2:3]
	v_mul_f32_e32 v144, v4, v1
	v_lshl_add_u64 v[4:5], s[60:61], 0, v[2:3]
	v_cvt_pk_bf16_f32 v1, v139, v18
	global_store_dword v[4:5], v1, off
	v_lshl_add_u64 v[4:5], s[62:63], 0, v[2:3]
	v_cvt_pk_bf16_f32 v1, v143, v144
	global_store_dword v[4:5], v1, off
	v_mul_f32_e32 v1, v16, v18
	v_mul_f32_e32 v4, v17, v18
	v_cvt_pk_bf16_f32 v1, v1, v4
	v_add_f32_e32 v4, v22, v175
	v_mul_f32_e32 v4, 0xbfb8aa3b, v4
	v_exp_f32_e32 v4, v4
	v_lshl_add_u64 v[2:3], s[66:67], 0, v[2:3]
	global_store_dword v[2:3], v1, off
	v_mul_f32_e32 v1, v172, v51
	v_add_f32_e32 v4, 1.0, v4
	v_rcp_f32_e32 v16, v4
	v_add_f32_e32 v4, v6, v173
	v_mul_f32_e32 v4, 0xbfb8aa3b, v4
	v_exp_f32_e32 v4, v4
	v_fmac_f32_e32 v1, v100, v49
	v_fmac_f32_e32 v1, v174, v53
	v_ashrrev_i32_e32 v49, 31, v48
	v_add_f32_e32 v4, 1.0, v4
	v_rcp_f32_e32 v6, v4
	v_mul_f32_e32 v4, v176, v1
	v_mul_f32_e32 v17, v123, v4
	v_add_f32_e32 v4, -1.0, v16
	v_lshlrev_b64 v[82:83], 9, v[48:49]
	v_fma_f32 v4, v177, v4, 1.0
	v_lshl_add_u64 v[2:3], v[82:83], 0, v[76:77]
	v_mul_f32_e32 v146, v4, v1
	v_add_f32_e32 v4, -1.0, v6
	v_fma_f32 v4, v177, v4, 1.0
	v_lshlrev_b64 v[2:3], 2, v[2:3]
	v_mul_f32_e32 v147, v4, v1
	v_lshl_add_u64 v[4:5], s[60:61], 0, v[2:3]
	v_cvt_pk_bf16_f32 v1, v142, v17
	global_store_dword v[4:5], v1, off
	v_lshl_add_u64 v[4:5], s[62:63], 0, v[2:3]
	v_cvt_pk_bf16_f32 v1, v146, v147
	global_store_dword v[4:5], v1, off
	v_mul_f32_e32 v1, v16, v17
	v_mul_f32_e32 v4, v6, v17
	v_cvt_pk_bf16_f32 v1, v1, v4
	v_add_f32_e32 v4, v23, v175
	v_mul_f32_e32 v4, 0xbfb8aa3b, v4
	v_exp_f32_e32 v4, v4
	v_lshl_add_u64 v[2:3], s[66:67], 0, v[2:3]
	global_store_dword v[2:3], v1, off
	v_mul_f32_e32 v1, v172, v53
	v_add_f32_e32 v4, 1.0, v4
	v_rcp_f32_e32 v6, v4
	v_add_f32_e32 v4, v7, v173
	v_mul_f32_e32 v4, 0xbfb8aa3b, v4
	v_exp_f32_e32 v4, v4
	v_fmac_f32_e32 v1, v100, v51
	v_fmac_f32_e32 v1, v174, v55
	v_ashrrev_i32_e32 v51, 31, v50
	v_add_f32_e32 v4, 1.0, v4
	v_rcp_f32_e32 v7, v4
	v_mul_f32_e32 v4, v176, v1
	v_mul_f32_e32 v16, v121, v4
	v_add_f32_e32 v4, -1.0, v6
	v_lshlrev_b64 v[84:85], 9, v[50:51]
	v_fma_f32 v4, v177, v4, 1.0
	v_lshl_add_u64 v[2:3], v[84:85], 0, v[76:77]
	v_mul_f32_e32 v148, v4, v1
	v_add_f32_e32 v4, -1.0, v7
	v_fma_f32 v4, v177, v4, 1.0
	v_lshlrev_b64 v[2:3], 2, v[2:3]
	v_mul_f32_e32 v149, v4, v1
	v_lshl_add_u64 v[4:5], s[60:61], 0, v[2:3]
	v_cvt_pk_bf16_f32 v1, v145, v16
	global_store_dword v[4:5], v1, off
	v_lshl_add_u64 v[4:5], s[62:63], 0, v[2:3]
	v_cvt_pk_bf16_f32 v1, v148, v149
	global_store_dword v[4:5], v1, off
	v_lshl_add_u64 v[2:3], s[66:67], 0, v[2:3]
	v_mul_f32_e32 v1, v6, v16
	v_mul_f32_e32 v4, v7, v16
	v_cvt_pk_bf16_f32 v1, v1, v4
	global_store_dword v[2:3], v1, off
	ds_read_u16 v3, v60 offset:61472
	ds_read_u16 v1, v0 offset:28928
	ds_read_u16 v2, v0 offset:29952
	v_add_f32_e32 v4, v24, v175
	v_mul_f32_e32 v4, 0xbfb8aa3b, v4
	s_waitcnt lgkmcnt(2)
	v_lshlrev_b32_e32 v6, 16, v3
	ds_read_u16 v3, v60 offset:62496
	v_exp_f32_e32 v4, v4
	v_mul_f32_e32 v150, v67, v6
	v_ashrrev_i32_e32 v53, 31, v52
	v_lshlrev_b64 v[86:87], 9, v[52:53]
	s_waitcnt lgkmcnt(0)
	v_lshlrev_b32_e32 v7, 16, v3
	ds_read_u16 v3, v60 offset:65088
	v_add_f32_e32 v4, 1.0, v4
	v_rcp_f32_e32 v24, v4
	v_add_f32_e32 v4, v8, v173
	v_mul_f32_e32 v4, 0xbfb8aa3b, v4
	s_waitcnt lgkmcnt(0)
	v_lshlrev_b32_e32 v16, 16, v3
	v_add_u32_e32 v3, 0x10240, v60
	ds_read_u16 v3, v3
	v_exp_f32_e32 v4, v4
	v_lshlrev_b32_e32 v1, 16, v1
	v_lshlrev_b32_e32 v2, 16, v2
	v_fmac_f32_e32 v150, v66, v1
	s_waitcnt lgkmcnt(0)
	v_lshlrev_b32_e32 v17, 16, v3
	v_add_u32_e32 v3, 0x10c60, v60
	ds_read_u16 v3, v3
	v_mul_f32_e32 v1, v172, v7
	v_fmac_f32_e32 v1, v100, v2
	v_add_f32_e32 v4, 1.0, v4
	v_fmac_f32_e32 v1, v174, v17
	s_waitcnt lgkmcnt(0)
	v_lshlrev_b32_e32 v18, 16, v3
	v_add_u32_e32 v3, 0x11060, v60
	ds_read_u16 v3, v3
	v_rcp_f32_e32 v8, v4
	v_mul_f32_e32 v4, v176, v1
	v_mul_f32_e32 v54, v119, v4
	v_add_f32_e32 v4, -1.0, v24
	s_waitcnt lgkmcnt(0)
	v_lshlrev_b32_e32 v19, 16, v3
	v_add_u32_e32 v3, 0x11a80, v60
	ds_read_u16 v3, v3
	v_fma_f32 v4, v177, v4, 1.0
	v_mul_f32_e32 v152, v4, v1
	v_add_f32_e32 v4, -1.0, v8
	v_fma_f32 v4, v177, v4, 1.0
	s_waitcnt lgkmcnt(0)
	v_lshlrev_b32_e32 v20, 16, v3
	v_add_u32_e32 v3, 0x11e80, v60
	ds_read_u16 v3, v3
	v_fmac_f32_e32 v150, v101, v16
	v_mul_f32_e32 v153, v4, v1
	v_mul_f32_e32 v151, v67, v16
	v_fmac_f32_e32 v151, v66, v6
	s_waitcnt lgkmcnt(0)
	v_lshlrev_b32_e32 v21, 16, v3
	v_add_u32_e32 v3, 0x128a0, v60
	ds_read_u16 v3, v3
	v_fmac_f32_e32 v151, v101, v18
	v_mul_f32_e32 v154, v67, v18
	v_fmac_f32_e32 v154, v66, v16
	v_fmac_f32_e32 v154, v101, v20
	s_waitcnt lgkmcnt(0)
	v_lshlrev_b32_e32 v22, 16, v3
	v_add_u32_e32 v3, 0x12ca0, v60
	ds_read_u16 v3, v3
	v_cvt_pk_bf16_f32 v1, v150, v54
	v_mul_f32_e32 v157, v67, v20
	v_fmac_f32_e32 v157, v66, v18
	v_fmac_f32_e32 v157, v101, v22
	s_waitcnt lgkmcnt(0)
	v_lshlrev_b32_e32 v23, 16, v3
	v_lshl_add_u64 v[2:3], v[86:87], 0, v[76:77]
	v_lshlrev_b64 v[2:3], 2, v[2:3]
	v_lshl_add_u64 v[4:5], s[60:61], 0, v[2:3]
	global_store_dword v[4:5], v1, off
	v_lshl_add_u64 v[4:5], s[62:63], 0, v[2:3]
	v_cvt_pk_bf16_f32 v1, v152, v153
	global_store_dword v[4:5], v1, off
	v_mul_f32_e32 v1, v24, v54
	v_mul_f32_e32 v4, v8, v54
	v_cvt_pk_bf16_f32 v1, v1, v4
	v_add_f32_e32 v4, v25, v175
	v_mul_f32_e32 v4, 0xbfb8aa3b, v4
	v_exp_f32_e32 v4, v4
	v_lshl_add_u64 v[2:3], s[66:67], 0, v[2:3]
	global_store_dword v[2:3], v1, off
	v_mul_f32_e32 v1, v172, v17
	v_add_f32_e32 v4, 1.0, v4
	v_rcp_f32_e32 v6, v4
	v_add_f32_e32 v4, v9, v173
	v_mul_f32_e32 v4, 0xbfb8aa3b, v4
	v_exp_f32_e32 v4, v4
	v_fmac_f32_e32 v1, v100, v7
	v_fmac_f32_e32 v1, v174, v19
	v_or_b32_e32 v54, 17, v36
	v_add_f32_e32 v4, 1.0, v4
	v_rcp_f32_e32 v7, v4
	v_mul_f32_e32 v4, v176, v1
	v_ashrrev_i32_e32 v55, 31, v54
	v_mul_f32_e32 v8, v117, v4
	v_add_f32_e32 v4, -1.0, v6
	v_lshlrev_b64 v[88:89], 9, v[54:55]
	v_fma_f32 v4, v177, v4, 1.0
	v_lshl_add_u64 v[2:3], v[88:89], 0, v[76:77]
	v_mul_f32_e32 v155, v4, v1
	v_add_f32_e32 v4, -1.0, v7
	v_fma_f32 v4, v177, v4, 1.0
	v_lshlrev_b64 v[2:3], 2, v[2:3]
	v_mul_f32_e32 v156, v4, v1
	v_lshl_add_u64 v[4:5], s[60:61], 0, v[2:3]
	v_cvt_pk_bf16_f32 v1, v151, v8
	global_store_dword v[4:5], v1, off
	v_lshl_add_u64 v[4:5], s[62:63], 0, v[2:3]
	v_cvt_pk_bf16_f32 v1, v155, v156
	global_store_dword v[4:5], v1, off
	v_mul_f32_e32 v1, v6, v8
	v_mul_f32_e32 v4, v7, v8
	v_cvt_pk_bf16_f32 v1, v1, v4
	v_add_f32_e32 v4, v26, v175
	v_mul_f32_e32 v4, 0xbfb8aa3b, v4
	v_exp_f32_e32 v4, v4
	v_lshl_add_u64 v[2:3], s[66:67], 0, v[2:3]
	global_store_dword v[2:3], v1, off
	v_mul_f32_e32 v1, v172, v19
	v_add_f32_e32 v4, 1.0, v4
	v_rcp_f32_e32 v6, v4
	v_add_f32_e32 v4, v10, v173
	v_mul_f32_e32 v4, 0xbfb8aa3b, v4
	v_exp_f32_e32 v4, v4
	v_fmac_f32_e32 v1, v100, v17
	v_fmac_f32_e32 v1, v174, v21
	v_lshl_add_u64 v[2:3], v[90:91], 0, v[76:77]
	v_add_f32_e32 v4, 1.0, v4
	v_rcp_f32_e32 v7, v4
	v_mul_f32_e32 v4, v176, v1
	v_mul_f32_e32 v8, v118, v4
	v_add_f32_e32 v4, -1.0, v6
	v_fma_f32 v4, v177, v4, 1.0
	v_mul_f32_e32 v158, v4, v1
	v_add_f32_e32 v4, -1.0, v7
	v_fma_f32 v4, v177, v4, 1.0
	v_lshlrev_b64 v[2:3], 2, v[2:3]
	v_mul_f32_e32 v159, v4, v1
	v_lshl_add_u64 v[4:5], s[60:61], 0, v[2:3]
	v_cvt_pk_bf16_f32 v1, v154, v8
	global_store_dword v[4:5], v1, off
	v_lshl_add_u64 v[4:5], s[62:63], 0, v[2:3]
	v_cvt_pk_bf16_f32 v1, v158, v159
	global_store_dword v[4:5], v1, off
	v_mul_f32_e32 v1, v6, v8
	v_mul_f32_e32 v4, v7, v8
	v_cvt_pk_bf16_f32 v1, v1, v4
	v_add_f32_e32 v4, v27, v175
	v_mul_f32_e32 v4, 0xbfb8aa3b, v4
	v_exp_f32_e32 v4, v4
	v_lshl_add_u64 v[2:3], s[66:67], 0, v[2:3]
	global_store_dword v[2:3], v1, off
	v_mul_f32_e32 v1, v172, v21
	v_add_f32_e32 v4, 1.0, v4
	v_rcp_f32_e32 v6, v4
	v_add_f32_e32 v4, v11, v173
	v_mul_f32_e32 v4, 0xbfb8aa3b, v4
	v_exp_f32_e32 v4, v4
	v_fmac_f32_e32 v1, v100, v19
	v_fmac_f32_e32 v1, v174, v23
	v_lshl_add_u64 v[2:3], v[92:93], 0, v[76:77]
	v_add_f32_e32 v4, 1.0, v4
	v_rcp_f32_e32 v7, v4
	v_mul_f32_e32 v4, v176, v1
	v_mul_f32_e32 v8, v116, v4
	v_add_f32_e32 v4, -1.0, v6
	v_fma_f32 v4, v177, v4, 1.0
	v_mul_f32_e32 v160, v4, v1
	v_add_f32_e32 v4, -1.0, v7
	v_fma_f32 v4, v177, v4, 1.0
	v_lshlrev_b64 v[2:3], 2, v[2:3]
	v_mul_f32_e32 v161, v4, v1
	v_lshl_add_u64 v[4:5], s[60:61], 0, v[2:3]
	v_cvt_pk_bf16_f32 v1, v157, v8
	global_store_dword v[4:5], v1, off
	v_lshl_add_u64 v[4:5], s[62:63], 0, v[2:3]
	v_cvt_pk_bf16_f32 v1, v160, v161
	global_store_dword v[4:5], v1, off
	v_lshl_add_u64 v[2:3], s[66:67], 0, v[2:3]
	v_mul_f32_e32 v1, v6, v8
	v_mul_f32_e32 v4, v7, v8
	v_cvt_pk_bf16_f32 v1, v1, v4
	global_store_dword v[2:3], v1, off
	v_add_u32_e32 v2, 0x16120, v60
	ds_read_u16 v1, v0 offset:57856
	ds_read_u16 v2, v2
	ds_read_u16 v0, v0 offset:58880
	v_add_f32_e32 v3, v28, v175
	v_mul_f32_e32 v3, 0xbfb8aa3b, v3
	v_exp_f32_e32 v3, v3
	s_waitcnt lgkmcnt(1)
	v_lshlrev_b32_e32 v4, 16, v2
	v_add_u32_e32 v2, 0x16520, v60
	ds_read_u16 v2, v2
	v_add_f32_e32 v3, 1.0, v3
	v_rcp_f32_e32 v18, v3
	v_add_f32_e32 v3, v12, v173
	v_mul_f32_e32 v3, 0xbfb8aa3b, v3
	s_waitcnt lgkmcnt(0)
	v_lshlrev_b32_e32 v5, 16, v2
	v_add_u32_e32 v2, 0x16f40, v60
	ds_read_u16 v2, v2
	v_exp_f32_e32 v3, v3
	v_lshlrev_b32_e32 v0, 16, v0
	v_lshlrev_b32_e32 v1, 16, v1
	v_mul_f32_e32 v162, v67, v4
	s_waitcnt lgkmcnt(0)
	v_lshlrev_b32_e32 v6, 16, v2
	v_add_u32_e32 v2, 0x17340, v60
	ds_read_u16 v2, v2
	v_add_f32_e32 v3, 1.0, v3
	v_rcp_f32_e32 v12, v3
	v_fmac_f32_e32 v162, v66, v1
	v_fmac_f32_e32 v162, v101, v6
	s_waitcnt lgkmcnt(0)
	v_lshlrev_b32_e32 v7, 16, v2
	v_add_u32_e32 v2, 0x17d60, v60
	ds_read_u16 v2, v2
	v_mul_f32_e32 v163, v67, v6
	v_fmac_f32_e32 v163, v66, v4
	v_ashrrev_i32_e32 v65, 31, v64
	v_lshlrev_b64 v[98:99], 9, v[64:65]
	s_waitcnt lgkmcnt(0)
	v_lshlrev_b32_e32 v8, 16, v2
	v_add_u32_e32 v2, 0x18160, v60
	ds_read_u16 v2, v2
	v_fmac_f32_e32 v163, v101, v8
	v_mul_f32_e32 v166, v67, v8
	v_fmac_f32_e32 v166, v66, v6
	s_waitcnt lgkmcnt(0)
	v_lshlrev_b32_e32 v9, 16, v2
	v_add_u32_e32 v2, 0x18b80, v60
	ds_read_u16 v2, v2
	s_waitcnt lgkmcnt(0)
	v_lshlrev_b32_e32 v10, 16, v2
	v_add_u32_e32 v2, 0x18f80, v60
	ds_read_u16 v2, v2
	v_fmac_f32_e32 v166, v101, v10
	v_mul_f32_e32 v169, v67, v10
	v_fmac_f32_e32 v169, v66, v8
	v_or_b32_e32 v66, 27, v36
	s_waitcnt lgkmcnt(0)
	v_lshlrev_b32_e32 v11, 16, v2
	v_add_u32_e32 v2, 0x199a0, v60
	ds_read_u16 v2, v2
	v_ashrrev_i32_e32 v67, 31, v66
	s_waitcnt lgkmcnt(0)
	v_lshlrev_b32_e32 v16, 16, v2
	v_add_u32_e32 v2, 0x19da0, v60
	ds_read_u16 v2, v2
	v_or_b32_e32 v60, 24, v36
	v_ashrrev_i32_e32 v61, 31, v60
	v_lshlrev_b64 v[94:95], 9, v[60:61]
	v_fmac_f32_e32 v169, v101, v16
	s_waitcnt lgkmcnt(0)
	v_lshlrev_b32_e32 v17, 16, v2
	v_mul_f32_e32 v2, v172, v5
	v_fmac_f32_e32 v2, v100, v0
	v_fmac_f32_e32 v2, v174, v7
	v_mul_f32_e32 v3, v176, v2
	v_mul_f32_e32 v19, v114, v3
	v_add_f32_e32 v3, -1.0, v18
	v_fma_f32 v3, v177, v3, 1.0
	v_lshl_add_u64 v[0:1], v[94:95], 0, v[76:77]
	v_mul_f32_e32 v164, v3, v2
	v_add_f32_e32 v3, -1.0, v12
	v_fma_f32 v3, v177, v3, 1.0
	v_lshlrev_b64 v[0:1], 2, v[0:1]
	v_mul_f32_e32 v165, v3, v2
	v_lshl_add_u64 v[2:3], s[60:61], 0, v[0:1]
	v_cvt_pk_bf16_f32 v20, v162, v19
	global_store_dword v[2:3], v20, off
	v_lshl_add_u64 v[2:3], s[62:63], 0, v[0:1]
	v_cvt_pk_bf16_f32 v20, v164, v165
	global_store_dword v[2:3], v20, off
	v_mul_f32_e32 v2, v18, v19
	v_mul_f32_e32 v3, v12, v19
	v_cvt_pk_bf16_f32 v2, v2, v3
	v_add_f32_e32 v3, v29, v175
	v_mul_f32_e32 v3, 0xbfb8aa3b, v3
	v_exp_f32_e32 v3, v3
	v_lshl_add_u64 v[0:1], s[66:67], 0, v[0:1]
	global_store_dword v[0:1], v2, off
	v_mul_f32_e32 v2, v172, v7
	v_add_f32_e32 v3, 1.0, v3
	v_rcp_f32_e32 v4, v3
	v_add_f32_e32 v3, v13, v173
	v_mul_f32_e32 v3, 0xbfb8aa3b, v3
	v_exp_f32_e32 v3, v3
	v_fmac_f32_e32 v2, v100, v5
	v_fmac_f32_e32 v2, v174, v9
	v_lshl_add_u64 v[0:1], v[96:97], 0, v[76:77]
	v_add_f32_e32 v3, 1.0, v3
	v_rcp_f32_e32 v5, v3
	v_mul_f32_e32 v3, v176, v2
	v_mul_f32_e32 v12, v113, v3
	v_add_f32_e32 v3, -1.0, v4
	v_fma_f32 v3, v177, v3, 1.0
	v_mul_f32_e32 v167, v3, v2
	v_add_f32_e32 v3, -1.0, v5
	v_fma_f32 v3, v177, v3, 1.0
	v_lshlrev_b64 v[0:1], 2, v[0:1]
	v_mul_f32_e32 v168, v3, v2
	v_lshl_add_u64 v[2:3], s[60:61], 0, v[0:1]
	v_cvt_pk_bf16_f32 v13, v163, v12
	global_store_dword v[2:3], v13, off
	v_lshl_add_u64 v[2:3], s[62:63], 0, v[0:1]
	v_cvt_pk_bf16_f32 v13, v167, v168
	global_store_dword v[2:3], v13, off
	v_mul_f32_e32 v2, v4, v12
	v_mul_f32_e32 v3, v5, v12
	v_cvt_pk_bf16_f32 v2, v2, v3
	v_add_f32_e32 v3, v30, v175
	v_mul_f32_e32 v3, 0xbfb8aa3b, v3
	v_exp_f32_e32 v3, v3
	v_lshl_add_u64 v[0:1], s[66:67], 0, v[0:1]
	global_store_dword v[0:1], v2, off
	v_mul_f32_e32 v2, v172, v9
	v_add_f32_e32 v3, 1.0, v3
	v_rcp_f32_e32 v4, v3
	v_add_f32_e32 v3, v14, v173
	v_mul_f32_e32 v3, 0xbfb8aa3b, v3
	v_exp_f32_e32 v3, v3
	v_fmac_f32_e32 v2, v100, v7
	v_fmac_f32_e32 v2, v174, v11
	v_lshl_add_u64 v[0:1], v[98:99], 0, v[76:77]
	v_add_f32_e32 v3, 1.0, v3
	v_rcp_f32_e32 v5, v3
	v_mul_f32_e32 v3, v176, v2
	v_mul_f32_e32 v6, v112, v3
	v_add_f32_e32 v3, -1.0, v4
	v_fma_f32 v3, v177, v3, 1.0
	v_mul_f32_e32 v170, v3, v2
	v_add_f32_e32 v3, -1.0, v5
	v_fma_f32 v3, v177, v3, 1.0
	v_lshlrev_b64 v[0:1], 2, v[0:1]
	v_mul_f32_e32 v171, v3, v2
	v_lshl_add_u64 v[2:3], s[60:61], 0, v[0:1]
	v_cvt_pk_bf16_f32 v7, v166, v6
	global_store_dword v[2:3], v7, off
	v_lshl_add_u64 v[2:3], s[62:63], 0, v[0:1]
	v_cvt_pk_bf16_f32 v7, v170, v171
	global_store_dword v[2:3], v7, off
	v_mul_f32_e32 v2, v4, v6
	v_mul_f32_e32 v3, v5, v6
	v_cvt_pk_bf16_f32 v2, v2, v3
	v_add_f32_e32 v3, v31, v175
	v_mul_f32_e32 v3, 0xbfb8aa3b, v3
	v_exp_f32_e32 v3, v3
	v_lshl_add_u64 v[0:1], s[66:67], 0, v[0:1]
	global_store_dword v[0:1], v2, off
	v_mul_f32_e32 v2, v172, v11
	v_add_f32_e32 v3, 1.0, v3
	v_rcp_f32_e32 v4, v3
	v_add_f32_e32 v3, v15, v173
	v_mul_f32_e32 v3, 0xbfb8aa3b, v3
	v_exp_f32_e32 v3, v3
	v_fmac_f32_e32 v2, v100, v9
	v_fmac_f32_e32 v2, v174, v17
	v_lshlrev_b64 v[100:101], 9, v[66:67]
	v_add_f32_e32 v3, 1.0, v3
	v_rcp_f32_e32 v5, v3
	v_mul_f32_e32 v3, v176, v2
	v_mul_f32_e32 v6, v111, v3
	v_add_f32_e32 v3, -1.0, v4
	v_fma_f32 v3, v177, v3, 1.0
	v_lshl_add_u64 v[0:1], v[100:101], 0, v[76:77]
	v_mul_f32_e32 v172, v3, v2
	v_add_f32_e32 v3, -1.0, v5
	v_fma_f32 v3, v177, v3, 1.0
	v_lshlrev_b64 v[0:1], 2, v[0:1]
	v_mul_f32_e32 v173, v3, v2
	v_lshl_add_u64 v[2:3], s[60:61], 0, v[0:1]
	v_cvt_pk_bf16_f32 v7, v169, v6
	global_store_dword v[2:3], v7, off
	v_lshl_add_u64 v[2:3], s[62:63], 0, v[0:1]
	v_cvt_pk_bf16_f32 v7, v172, v173
	global_store_dword v[2:3], v7, off
	v_lshl_add_u64 v[0:1], s[66:67], 0, v[0:1]
	v_mul_f32_e32 v2, v4, v6
	v_mul_f32_e32 v3, v5, v6
	v_cvt_pk_bf16_f32 v2, v2, v3
	global_store_dword v[0:1], v2, off
	v_mov_b32_e32 v76, v32
	s_nop 0
	v_ashrrev_i32_e32 v77, 31, v76
	v_lshlrev_b64 v[0:1], 7, v[76:77]
	v_lshl_add_u64 v[0:1], s[72:73], 0, v[0:1]
	v_lshl_add_u64 v[188:189], v[0:1], 0, v[178:179]
	v_add_co_u32_e32 v4, vcc, s5, v188
	global_load_dwordx4 v[192:195], v[188:189], off
	s_nop 0
	v_addc_co_u32_e32 v5, vcc, 0, v189, vcc
	global_load_dwordx4 v[196:199], v[4:5], off
	v_lshl_add_u64 v[190:191], v[188:189], 0, s[10:11]
	ds_read_b128 v[8:11], v104 offset:128
	ds_read_b128 v[174:177], v104 offset:160
	global_load_dwordx4 v[204:207], v[188:189], off offset:32
	global_load_dwordx4 v[212:215], v[190:191], off offset:32
	global_load_dwordx4 v[224:227], v[188:189], off offset:64
	global_load_dwordx4 v[228:231], v[190:191], off offset:64
	global_load_dwordx4 v[232:235], v[188:189], off offset:96
	global_load_dwordx4 v[236:239], v[190:191], off offset:96
	s_waitcnt vmcnt(4) lgkmcnt(0)
	v_mfma_f32_32x32x16_bf16 v[16:31], v[8:11], v[192:195], 0
	v_lshl_add_u64 v[80:81], v[80:81], 0, v[76:77]
	v_lshlrev_b64 v[80:81], 2, v[80:81]
	v_lshl_add_u64 v[82:83], v[82:83], 0, v[76:77]
	v_lshlrev_b64 v[82:83], 2, v[82:83]
	v_mfma_f32_32x32x16_bf16 v[0:15], v[8:11], v[196:199], 0
	v_mfma_f32_32x32x16_bf16 v[16:31], v[174:177], v[204:207], v[16:31]
	v_mfma_f32_32x32x16_bf16 v[0:15], v[174:177], v[212:215], v[0:15]
	ds_read_b128 v[174:177], v104 offset:192
	s_waitcnt vmcnt(2) lgkmcnt(0)
	v_mfma_f32_32x32x16_bf16 v[16:31], v[174:177], v[224:227], v[16:31]
	v_mfma_f32_32x32x16_bf16 v[0:15], v[174:177], v[228:231], v[0:15]
	ds_read_b128 v[174:177], v104 offset:224
	s_waitcnt vmcnt(0) lgkmcnt(0)
	v_mfma_f32_32x32x16_bf16 v[0:15], v[174:177], v[236:239], v[0:15]
	v_lshlrev_b64 v[186:187], 2, v[76:77]
	v_lshl_add_u64 v[188:189], s[14:15], 0, v[186:187]
	v_mfma_f32_32x32x16_bf16 v[16:31], v[174:177], v[232:235], v[16:31]
	v_lshl_add_u64 v[180:181], s[76:77], 0, v[186:187]
	v_add_co_u32_e32 v176, vcc, s4, v180
	global_load_dword v175, v[180:181], off
	s_nop 0
	v_addc_co_u32_e32 v177, vcc, 0, v181, vcc
	v_add_co_u32_e32 v182, vcc, s9, v180
	global_load_dword v176, v[176:177], off offset:3072
	s_nop 0
	v_addc_co_u32_e32 v183, vcc, 0, v181, vcc
	global_load_dword v178, v[182:183], off offset:2048
	global_load_dword v177, v[180:181], off offset:2048
	v_add_co_u32_e32 v182, vcc, s7, v180
	s_ashr_i32 s7, s6, 31
	s_nop 0
	v_addc_co_u32_e32 v183, vcc, 0, v181, vcc
	v_add_co_u32_e32 v180, vcc, s8, v180
	global_load_dword v182, v[182:183], off offset:1024
	s_nop 0
	v_addc_co_u32_e32 v181, vcc, 0, v181, vcc
	global_load_dword v184, v[180:181], off
	v_lshl_add_u64 v[180:181], s[12:13], 0, v[186:187]
	global_load_dword v185, v[180:181], off
	global_load_dword v183, v[180:181], off offset:2048
	v_lshl_add_u64 v[180:181], s[84:85], 0, v[186:187]
	global_load_dword v181, v[180:181], off
	v_lshl_add_u64 v[186:187], s[16:17], 0, v[186:187]
	global_load_dword v180, v[188:189], off
	global_load_dword v174, v[186:187], off
	v_lshl_add_u32 v187, v76, 1, 0
	v_add_u32_e32 v186, v187, v103
	ds_read_u16 v188, v186
	ds_read_u16 v189, v186 offset:1024
	ds_read_u16 v190, v186 offset:3616
	v_cmp_eq_u32_e32 vcc, 0, v35
	s_lshl_b64 s[4:5], s[6:7], 2
	s_waitcnt lgkmcnt(2)
	v_lshlrev_b32_e32 v188, 16, v188
	s_waitcnt lgkmcnt(1)
	v_lshlrev_b32_e32 v189, 16, v189
	s_waitcnt lgkmcnt(0)
	v_lshlrev_b32_e32 v192, 16, v190
	ds_read_u16 v190, v186 offset:4640
	v_readlane_b32 s6, v255, 9
	s_add_u32 s4, s6, s4
	s_addc_u32 s5, s83, s5
	s_waitcnt lgkmcnt(0)
	v_lshlrev_b32_e32 v193, 16, v190
	ds_read_u16 v190, v186 offset:7232
	s_waitcnt lgkmcnt(0)
	v_lshlrev_b32_e32 v194, 16, v190
	ds_read_u16 v190, v186 offset:8256
	s_waitcnt lgkmcnt(0)
	v_lshlrev_b32_e32 v195, 16, v190
	ds_read_u16 v190, v186 offset:10848
	s_waitcnt lgkmcnt(0)
	v_lshlrev_b32_e32 v196, 16, v190
	ds_read_u16 v190, v186 offset:11872
	s_waitcnt lgkmcnt(0)
	v_lshlrev_b32_e32 v197, 16, v190
	ds_read_u16 v190, v186 offset:14464
	s_waitcnt lgkmcnt(0)
	v_lshlrev_b32_e32 v198, 16, v190
	ds_read_u16 v190, v186 offset:15488
	s_waitcnt lgkmcnt(0)
	v_lshlrev_b32_e32 v199, 16, v190
	ds_read_u16 v190, v186 offset:18080
	s_waitcnt lgkmcnt(0)
	v_lshlrev_b32_e32 v204, 16, v190
	ds_read_u16 v190, v186 offset:19104
	s_waitcnt vmcnt(9)
	v_mul_f32_e32 v206, v176, v192
	v_fmac_f32_e32 v206, v175, v188
	s_waitcnt vmcnt(8)
	v_fmac_f32_e32 v206, v178, v194
	s_waitcnt lgkmcnt(0)
	v_lshlrev_b32_e32 v205, 16, v190
	s_waitcnt vmcnt(6)
	v_mul_f32_e32 v190, v182, v193
	v_fmac_f32_e32 v190, v177, v189
	v_lshl_add_u64 v[188:189], v[74:75], 0, v[76:77]
	s_waitcnt vmcnt(5)
	v_fmac_f32_e32 v190, v184, v195
	s_waitcnt vmcnt(4)
	v_add_f32_e32 v16, v16, v185
	s_waitcnt vmcnt(3)
	v_add_f32_e32 v0, v0, v183
	v_mul_f32_e32 v0, 0xbfb8aa3b, v0
	v_mul_f32_e32 v16, 0xbfb8aa3b, v16
	v_exp_f32_e32 v0, v0
	v_exp_f32_e32 v16, v16
	s_waitcnt vmcnt(2)
	v_mul_f32_e32 v191, v181, v190
	v_mul_f32_e32 v126, v126, v191
	v_add_f32_e32 v0, 1.0, v0
	v_add_f32_e32 v16, 1.0, v16
	v_rcp_f32_e32 v0, v0
	v_rcp_f32_e32 v16, v16
	v_lshlrev_b64 v[188:189], 2, v[188:189]
	v_add_f32_e32 v1, v1, v183
	v_add_f32_e32 v212, -1.0, v0
	v_add_f32_e32 v191, -1.0, v16
	s_waitcnt vmcnt(1)
	v_fma_f32 v212, v180, v212, 1.0
	v_fma_f32 v191, v180, v191, 1.0
	v_mul_f32_e32 v212, v212, v190
	v_mul_f32_e32 v207, v191, v190
	v_fma_f32 v190, v191, v190, v212
	v_mul_f32_e32 v190, v206, v190
	s_waitcnt vmcnt(0)
	v_fmac_f32_e32 v132, v174, v190
	v_lshl_add_u64 v[190:191], s[60:61], 0, v[188:189]
	v_cvt_pk_bf16_f32 v206, v206, v126
	global_store_dword v[190:191], v206, off
	v_lshl_add_u64 v[190:191], s[62:63], 0, v[188:189]
	v_mul_f32_e32 v16, v16, v126
	v_mul_f32_e32 v0, v0, v126
	v_cvt_pk_bf16_f32 v206, v207, v212
	global_store_dword v[190:191], v206, off
	v_cvt_pk_bf16_f32 v0, v16, v0
	v_add_f32_e32 v16, v17, v185
	v_mul_f32_e32 v16, 0xbfb8aa3b, v16
	v_mul_f32_e32 v1, 0xbfb8aa3b, v1
	v_exp_f32_e32 v16, v16
	v_exp_f32_e32 v1, v1
	v_lshl_add_u64 v[188:189], s[66:67], 0, v[188:189]
	global_store_dword v[188:189], v0, off
	v_mul_f32_e32 v0, v176, v194
	v_add_f32_e32 v16, 1.0, v16
	v_add_f32_e32 v1, 1.0, v1
	v_fmac_f32_e32 v0, v175, v192
	v_mul_f32_e32 v126, v182, v195
	v_rcp_f32_e32 v192, v16
	v_rcp_f32_e32 v1, v1
	v_fmac_f32_e32 v126, v177, v193
	v_add_f32_e32 v18, v18, v185
	v_add_f32_e32 v2, v2, v183
	v_fmac_f32_e32 v126, v184, v197
	v_mul_f32_e32 v18, 0xbfb8aa3b, v18
	v_mul_f32_e32 v2, 0xbfb8aa3b, v2
	v_mul_f32_e32 v16, v181, v126
	v_exp_f32_e32 v18, v18
	v_exp_f32_e32 v2, v2
	v_lshl_add_u64 v[188:189], v[72:73], 0, v[76:77]
	v_mul_f32_e32 v124, v124, v16
	v_add_f32_e32 v16, -1.0, v192
	v_add_f32_e32 v17, -1.0, v1
	v_fma_f32 v16, v180, v16, 1.0
	v_fma_f32 v17, v180, v17, 1.0
	v_lshlrev_b64 v[188:189], 2, v[188:189]
	v_fmac_f32_e32 v0, v178, v196
	v_mul_f32_e32 v16, v16, v126
	v_mul_f32_e32 v17, v17, v126
	v_lshl_add_u64 v[190:191], s[60:61], 0, v[188:189]
	v_cvt_pk_bf16_f32 v126, v0, v124
	global_store_dword v[190:191], v126, off
	v_lshl_add_u64 v[190:191], s[62:63], 0, v[188:189]
	v_cvt_pk_bf16_f32 v126, v16, v17
	v_add_f32_e32 v18, 1.0, v18
	v_add_f32_e32 v2, 1.0, v2
	global_store_dword v[190:191], v126, off
	v_mul_f32_e32 v126, v192, v124
	v_mul_f32_e32 v1, v1, v124
	v_mul_f32_e32 v124, v182, v197
	v_rcp_f32_e32 v190, v18
	v_rcp_f32_e32 v2, v2
	v_fmac_f32_e32 v124, v177, v195
	v_fmac_f32_e32 v124, v184, v199
	v_mul_f32_e32 v18, v181, v124
	v_add_f32_e32 v19, v19, v185
	v_add_f32_e32 v3, v3, v183
	v_lshl_add_u64 v[188:189], s[66:67], 0, v[188:189]
	v_cvt_pk_bf16_f32 v1, v126, v1
	v_mul_f32_e32 v191, v127, v18
	v_add_f32_e32 v18, -1.0, v190
	v_add_f32_e32 v126, -1.0, v2
	v_mul_f32_e32 v19, 0xbfb8aa3b, v19
	v_mul_f32_e32 v3, 0xbfb8aa3b, v3
	global_store_dword v[188:189], v1, off
	v_lshl_add_u64 v[188:189], v[70:71], 0, v[76:77]
	v_fma_f32 v18, v180, v18, 1.0
	v_fma_f32 v126, v180, v126, 1.0
	v_exp_f32_e32 v19, v19
	v_exp_f32_e32 v3, v3
	v_mul_f32_e32 v1, v176, v196
	v_mul_f32_e32 v18, v18, v124
	v_mul_f32_e32 v124, v126, v124
	v_lshlrev_b64 v[126:127], 2, v[188:189]
	v_fmac_f32_e32 v1, v175, v194
	v_lshl_add_u64 v[188:189], s[60:61], 0, v[126:127]
	v_fmac_f32_e32 v1, v178, v198
	v_cvt_pk_bf16_f32 v192, v1, v191
	global_store_dword v[188:189], v192, off
	v_lshl_add_u64 v[188:189], s[62:63], 0, v[126:127]
	v_cvt_pk_bf16_f32 v192, v18, v124
	global_store_dword v[188:189], v192, off
	v_mul_f32_e32 v188, v190, v191
	v_mul_f32_e32 v2, v2, v191
	v_add_f32_e32 v19, 1.0, v19
	v_add_f32_e32 v3, 1.0, v3
	v_cvt_pk_bf16_f32 v2, v188, v2
	v_mul_f32_e32 v188, v182, v199
	v_rcp_f32_e32 v190, v19
	v_rcp_f32_e32 v191, v3
	v_fmac_f32_e32 v188, v177, v197
	v_fmac_f32_e32 v188, v184, v205
	v_lshl_add_u64 v[126:127], s[66:67], 0, v[126:127]
	v_mul_f32_e32 v3, v181, v188
	global_store_dword v[126:127], v2, off
	v_lshl_add_u64 v[126:127], v[68:69], 0, v[76:77]
	v_mul_f32_e32 v125, v125, v3
	v_add_f32_e32 v3, -1.0, v190
	v_add_f32_e32 v19, -1.0, v191
	v_mul_f32_e32 v2, v176, v198
	v_fma_f32 v3, v180, v3, 1.0
	v_fma_f32 v19, v180, v19, 1.0
	v_lshlrev_b64 v[126:127], 2, v[126:127]
	v_fmac_f32_e32 v2, v175, v196
	v_mul_f32_e32 v3, v3, v188
	v_mul_f32_e32 v19, v19, v188
	v_lshl_add_u64 v[188:189], s[60:61], 0, v[126:127]
	v_fmac_f32_e32 v2, v178, v204
	v_cvt_pk_bf16_f32 v192, v2, v125
	global_store_dword v[188:189], v192, off
	v_lshl_add_u64 v[188:189], s[62:63], 0, v[126:127]
	v_cvt_pk_bf16_f32 v192, v3, v19
	global_store_dword v[188:189], v192, off
	v_lshl_add_u64 v[126:127], s[66:67], 0, v[126:127]
	v_mul_f32_e32 v188, v190, v125
	v_mul_f32_e32 v125, v191, v125
	v_cvt_pk_bf16_f32 v125, v188, v125
	global_store_dword v[126:127], v125, off
	v_add_u32_e32 v126, v187, v105
	ds_read_u16 v125, v126
	v_add_f32_e32 v20, v20, v185
	v_add_f32_e32 v4, v4, v183
	v_mul_f32_e32 v20, 0xbfb8aa3b, v20
	v_mul_f32_e32 v4, 0xbfb8aa3b, v4
	s_waitcnt lgkmcnt(0)
	v_lshlrev_b32_e32 v127, 16, v125
	ds_read_u16 v125, v126 offset:1024
	v_exp_f32_e32 v20, v20
	v_exp_f32_e32 v4, v4
	v_lshl_add_u64 v[188:189], v[78:79], 0, v[76:77]
	v_add_f32_e32 v21, v21, v185
	s_waitcnt lgkmcnt(0)
	v_lshlrev_b32_e32 v187, 16, v125
	ds_read_u16 v125, v186 offset:32544
	v_add_f32_e32 v20, 1.0, v20
	v_add_f32_e32 v4, 1.0, v4
	v_rcp_f32_e32 v79, v20
	v_rcp_f32_e32 v4, v4
	s_waitcnt lgkmcnt(0)
	v_lshlrev_b32_e32 v192, 16, v125
	ds_read_u16 v125, v186 offset:33568
	v_add_f32_e32 v5, v5, v183
	v_mul_f32_e32 v21, 0xbfb8aa3b, v21
	v_mul_f32_e32 v5, 0xbfb8aa3b, v5
	v_exp_f32_e32 v21, v21
	s_waitcnt lgkmcnt(0)
	v_lshlrev_b32_e32 v193, 16, v125
	ds_read_u16 v125, v186 offset:36160
	v_exp_f32_e32 v5, v5
	v_add_f32_e32 v78, -1.0, v4
	v_lshlrev_b64 v[188:189], 2, v[188:189]
	v_fma_f32 v78, v180, v78, 1.0
	s_waitcnt lgkmcnt(0)
	v_lshlrev_b32_e32 v194, 16, v125
	ds_read_u16 v125, v186 offset:37184
	v_lshl_add_u64 v[190:191], s[60:61], 0, v[188:189]
	v_add_f32_e32 v21, 1.0, v21
	v_add_f32_e32 v5, 1.0, v5
	v_rcp_f32_e32 v5, v5
	s_waitcnt lgkmcnt(0)
	v_lshlrev_b32_e32 v195, 16, v125
	ds_read_u16 v125, v186 offset:39776
	v_add_f32_e32 v22, v22, v185
	v_add_f32_e32 v6, v6, v183
	v_mul_f32_e32 v22, 0xbfb8aa3b, v22
	v_mul_f32_e32 v6, 0xbfb8aa3b, v6
	s_waitcnt lgkmcnt(0)
	v_lshlrev_b32_e32 v196, 16, v125
	ds_read_u16 v125, v186 offset:40800
	v_exp_f32_e32 v22, v22
	v_exp_f32_e32 v6, v6
	v_add_f32_e32 v23, v23, v185
	v_add_f32_e32 v7, v7, v183
	s_waitcnt lgkmcnt(0)
	v_lshlrev_b32_e32 v197, 16, v125
	ds_read_u16 v125, v186 offset:43392
	v_add_f32_e32 v22, 1.0, v22
	v_add_f32_e32 v6, 1.0, v6
	v_rcp_f32_e32 v6, v6
	v_mul_f32_e32 v23, 0xbfb8aa3b, v23
	s_waitcnt lgkmcnt(0)
	v_lshlrev_b32_e32 v198, 16, v125
	ds_read_u16 v125, v186 offset:44416
	v_mul_f32_e32 v7, 0xbfb8aa3b, v7
	v_exp_f32_e32 v23, v23
	v_exp_f32_e32 v7, v7
	v_add_f32_e32 v24, v24, v185
	s_waitcnt lgkmcnt(0)
	v_lshlrev_b32_e32 v199, 16, v125
	ds_read_u16 v125, v186 offset:47008
	v_add_f32_e32 v23, 1.0, v23
	v_add_f32_e32 v7, 1.0, v7
	v_add_f32_e32 v8, v8, v183
	v_mul_f32_e32 v24, 0xbfb8aa3b, v24
	s_waitcnt lgkmcnt(0)
	v_lshlrev_b32_e32 v204, 16, v125
	ds_read_u16 v125, v186 offset:48032
	v_mul_f32_e32 v8, 0xbfb8aa3b, v8
	v_exp_f32_e32 v24, v24
	v_exp_f32_e32 v8, v8
	v_add_f32_e32 v25, v25, v185
	s_waitcnt lgkmcnt(0)
	v_lshlrev_b32_e32 v205, 16, v125
	v_mul_f32_e32 v125, v176, v192
	v_fmac_f32_e32 v125, v175, v127
	v_mul_f32_e32 v127, v182, v193
	v_fmac_f32_e32 v127, v177, v187
	v_fmac_f32_e32 v127, v184, v195
	v_mul_f32_e32 v20, v181, v127
	v_mul_f32_e32 v122, v122, v20
	v_add_f32_e32 v20, -1.0, v79
	v_fma_f32 v20, v180, v20, 1.0
	v_fmac_f32_e32 v125, v178, v194
	v_mul_f32_e32 v20, v20, v127
	v_mul_f32_e32 v78, v78, v127
	v_cvt_pk_bf16_f32 v127, v125, v122
	global_store_dword v[190:191], v127, off
	v_lshl_add_u64 v[190:191], s[62:63], 0, v[188:189]
	v_mul_f32_e32 v79, v79, v122
	v_mul_f32_e32 v4, v4, v122
	v_cvt_pk_bf16_f32 v127, v20, v78
	global_store_dword v[190:191], v127, off
	v_cvt_pk_bf16_f32 v4, v79, v4
	v_mul_f32_e32 v79, v182, v195
	v_rcp_f32_e32 v122, v21
	v_fmac_f32_e32 v79, v177, v193
	v_fmac_f32_e32 v79, v184, v197
	v_lshl_add_u64 v[188:189], s[66:67], 0, v[188:189]
	v_mul_f32_e32 v21, v181, v79
	global_store_dword v[188:189], v4, off
	v_mul_f32_e32 v4, v176, v194
	v_mul_f32_e32 v120, v120, v21
	v_add_f32_e32 v21, -1.0, v122
	v_add_f32_e32 v127, -1.0, v5
	v_fmac_f32_e32 v4, v175, v192
	v_fma_f32 v21, v180, v21, 1.0
	v_fma_f32 v127, v180, v127, 1.0
	v_lshl_add_u64 v[188:189], s[60:61], 0, v[80:81]
	v_fmac_f32_e32 v4, v178, v196
	v_mul_f32_e32 v21, v21, v79
	v_mul_f32_e32 v79, v127, v79
	v_cvt_pk_bf16_f32 v127, v4, v120
	global_store_dword v[188:189], v127, off
	v_lshl_add_u64 v[188:189], s[62:63], 0, v[80:81]
	v_lshl_add_u64 v[80:81], s[66:67], 0, v[80:81]
	v_mul_f32_e32 v5, v5, v120
	v_cvt_pk_bf16_f32 v127, v21, v79
	global_store_dword v[188:189], v127, off
	v_mul_f32_e32 v122, v122, v120
	v_cvt_pk_bf16_f32 v5, v122, v5
	global_store_dword v[80:81], v5, off
	v_mul_f32_e32 v80, v182, v197
	v_rcp_f32_e32 v81, v22
	v_fmac_f32_e32 v80, v177, v195
	v_fmac_f32_e32 v80, v184, v199
	v_mul_f32_e32 v22, v181, v80
	v_mul_f32_e32 v120, v123, v22
	v_add_f32_e32 v22, -1.0, v81
	v_add_f32_e32 v122, -1.0, v6
	v_mul_f32_e32 v5, v176, v196
	v_fma_f32 v22, v180, v22, 1.0
	v_fma_f32 v122, v180, v122, 1.0
	v_fmac_f32_e32 v5, v175, v194
	v_mul_f32_e32 v22, v22, v80
	v_mul_f32_e32 v80, v122, v80
	v_lshl_add_u64 v[122:123], s[60:61], 0, v[82:83]
	v_fmac_f32_e32 v5, v178, v198
	v_cvt_pk_bf16_f32 v127, v5, v120
	global_store_dword v[122:123], v127, off
	v_lshl_add_u64 v[122:123], s[62:63], 0, v[82:83]
	v_mul_f32_e32 v81, v81, v120
	v_mul_f32_e32 v6, v6, v120
	v_cvt_pk_bf16_f32 v127, v22, v80
	global_store_dword v[122:123], v127, off
	v_cvt_pk_bf16_f32 v6, v81, v6
	v_mul_f32_e32 v81, v182, v199
	v_rcp_f32_e32 v120, v23
	v_rcp_f32_e32 v122, v7
	v_fmac_f32_e32 v81, v177, v197
	v_fmac_f32_e32 v81, v184, v205
	v_lshl_add_u64 v[82:83], s[66:67], 0, v[82:83]
	v_mul_f32_e32 v7, v181, v81
	global_store_dword v[82:83], v6, off
	v_mul_f32_e32 v6, v176, v198
	v_lshl_add_u64 v[82:83], v[84:85], 0, v[76:77]
	v_mul_f32_e32 v121, v121, v7
	v_add_f32_e32 v7, -1.0, v120
	v_add_f32_e32 v23, -1.0, v122
	v_fmac_f32_e32 v6, v175, v196
	v_fma_f32 v7, v180, v7, 1.0
	v_fma_f32 v23, v180, v23, 1.0
	v_lshlrev_b64 v[82:83], 2, v[82:83]
	v_fmac_f32_e32 v6, v178, v204
	v_mul_f32_e32 v7, v7, v81
	v_mul_f32_e32 v23, v23, v81
	v_lshl_add_u64 v[84:85], s[60:61], 0, v[82:83]
	v_cvt_pk_bf16_f32 v81, v6, v121
	global_store_dword v[84:85], v81, off
	v_lshl_add_u64 v[84:85], s[62:63], 0, v[82:83]
	v_cvt_pk_bf16_f32 v81, v7, v23
	global_store_dword v[84:85], v81, off
	v_mul_f32_e32 v81, v120, v121
	v_lshl_add_u64 v[82:83], s[66:67], 0, v[82:83]
	v_mul_f32_e32 v84, v122, v121
	v_cvt_pk_bf16_f32 v81, v81, v84
	global_store_dword v[82:83], v81, off
	ds_read_u16 v81, v126 offset:28928
	v_add_f32_e32 v24, 1.0, v24
	v_add_f32_e32 v8, 1.0, v8
	v_rcp_f32_e32 v8, v8
	v_add_f32_e32 v9, v9, v183
	s_waitcnt lgkmcnt(0)
	v_lshlrev_b32_e32 v82, 16, v81
	ds_read_u16 v81, v126 offset:29952
	v_mul_f32_e32 v25, 0xbfb8aa3b, v25
	v_mul_f32_e32 v9, 0xbfb8aa3b, v9
	v_exp_f32_e32 v25, v25
	v_exp_f32_e32 v9, v9
	s_waitcnt lgkmcnt(0)
	v_lshlrev_b32_e32 v83, 16, v81
	ds_read_u16 v81, v186 offset:61472
	v_lshl_add_u64 v[84:85], v[86:87], 0, v[76:77]
	v_add_f32_e32 v86, -1.0, v8
	v_fma_f32 v86, v180, v86, 1.0
	v_lshlrev_b64 v[84:85], 2, v[84:85]
	s_waitcnt lgkmcnt(0)
	v_lshlrev_b32_e32 v120, 16, v81
	ds_read_u16 v81, v186 offset:62496
	v_add_f32_e32 v25, 1.0, v25
	v_add_f32_e32 v9, 1.0, v9
	v_rcp_f32_e32 v9, v9
	v_add_f32_e32 v26, v26, v185
	s_waitcnt lgkmcnt(0)
	v_lshlrev_b32_e32 v121, 16, v81
	ds_read_u16 v81, v186 offset:65088
	v_add_f32_e32 v10, v10, v183
	v_mul_f32_e32 v26, 0xbfb8aa3b, v26
	v_mul_f32_e32 v10, 0xbfb8aa3b, v10
	v_exp_f32_e32 v26, v26
	s_waitcnt lgkmcnt(0)
	v_lshlrev_b32_e32 v122, 16, v81
	v_add_u32_e32 v81, 0x10240, v186
	ds_read_u16 v81, v81
	v_exp_f32_e32 v10, v10
	v_add_f32_e32 v26, 1.0, v26
	v_add_f32_e32 v27, v27, v185
	v_add_f32_e32 v11, v11, v183
	s_waitcnt lgkmcnt(0)
	v_lshlrev_b32_e32 v123, 16, v81
	v_add_u32_e32 v81, 0x10c60, v186
	ds_read_u16 v81, v81
	v_add_f32_e32 v10, 1.0, v10
	v_rcp_f32_e32 v10, v10
	v_mul_f32_e32 v27, 0xbfb8aa3b, v27
	v_mul_f32_e32 v11, 0xbfb8aa3b, v11
	s_waitcnt lgkmcnt(0)
	v_lshlrev_b32_e32 v127, 16, v81
	v_add_u32_e32 v81, 0x11060, v186
	ds_read_u16 v81, v81
	v_exp_f32_e32 v27, v27
	v_exp_f32_e32 v11, v11
	v_add_f32_e32 v28, v28, v185
	v_add_f32_e32 v12, v12, v183
	s_waitcnt lgkmcnt(0)
	v_lshlrev_b32_e32 v187, 16, v81
	v_add_u32_e32 v81, 0x11a80, v186
	ds_read_u16 v81, v81
	v_add_f32_e32 v27, 1.0, v27
	v_add_f32_e32 v11, 1.0, v11
	v_mul_f32_e32 v28, 0xbfb8aa3b, v28
	v_mul_f32_e32 v12, 0xbfb8aa3b, v12
	s_waitcnt lgkmcnt(0)
	v_lshlrev_b32_e32 v188, 16, v81
	v_add_u32_e32 v81, 0x11e80, v186
	ds_read_u16 v81, v81
	v_exp_f32_e32 v28, v28
	v_exp_f32_e32 v12, v12
	v_add_f32_e32 v29, v29, v185
	v_add_f32_e32 v13, v13, v183
	s_waitcnt lgkmcnt(0)
	v_lshlrev_b32_e32 v189, 16, v81
	v_add_u32_e32 v81, 0x128a0, v186
	ds_read_u16 v81, v81
	v_add_f32_e32 v28, 1.0, v28
	v_add_f32_e32 v12, 1.0, v12
	v_rcp_f32_e32 v12, v12
	v_mul_f32_e32 v29, 0xbfb8aa3b, v29
	s_waitcnt lgkmcnt(0)
	v_lshlrev_b32_e32 v190, 16, v81
	v_add_u32_e32 v81, 0x12ca0, v186
	ds_read_u16 v81, v81
	v_mul_f32_e32 v13, 0xbfb8aa3b, v13
	v_exp_f32_e32 v29, v29
	v_exp_f32_e32 v13, v13
	v_add_f32_e32 v30, v30, v185
	s_waitcnt lgkmcnt(0)
	v_lshlrev_b32_e32 v191, 16, v81
	v_mul_f32_e32 v81, v176, v120
	v_fmac_f32_e32 v81, v175, v82
	v_mul_f32_e32 v82, v182, v121
	v_fmac_f32_e32 v82, v177, v83
	v_rcp_f32_e32 v83, v24
	v_fmac_f32_e32 v82, v184, v123
	v_mul_f32_e32 v24, v181, v82
	v_mul_f32_e32 v119, v119, v24
	v_add_f32_e32 v24, -1.0, v83
	v_fma_f32 v24, v180, v24, 1.0
	v_mul_f32_e32 v24, v24, v82
	v_mul_f32_e32 v82, v86, v82
	v_lshl_add_u64 v[86:87], s[60:61], 0, v[84:85]
	v_fmac_f32_e32 v81, v178, v122
	v_cvt_pk_bf16_f32 v192, v81, v119
	global_store_dword v[86:87], v192, off
	v_lshl_add_u64 v[86:87], s[62:63], 0, v[84:85]
	v_lshl_add_u64 v[84:85], s[66:67], 0, v[84:85]
	v_mul_f32_e32 v83, v83, v119
	v_mul_f32_e32 v8, v8, v119
	v_cvt_pk_bf16_f32 v192, v24, v82
	global_store_dword v[86:87], v192, off
	v_cvt_pk_bf16_f32 v8, v83, v8
	global_store_dword v[84:85], v8, off
	v_mul_f32_e32 v83, v182, v123
	v_lshl_add_u64 v[84:85], v[88:89], 0, v[76:77]
	v_rcp_f32_e32 v88, v25
	v_fmac_f32_e32 v83, v177, v121
	v_fmac_f32_e32 v83, v184, v187
	v_mul_f32_e32 v25, v181, v83
	v_mul_f32_e32 v89, v117, v25
	v_add_f32_e32 v25, -1.0, v88
	v_add_f32_e32 v86, -1.0, v9
	v_mul_f32_e32 v8, v176, v122
	v_fma_f32 v25, v180, v25, 1.0
	v_fma_f32 v86, v180, v86, 1.0
	v_lshlrev_b64 v[84:85], 2, v[84:85]
	v_fmac_f32_e32 v8, v175, v120
	v_mul_f32_e32 v25, v25, v83
	v_mul_f32_e32 v83, v86, v83
	v_lshl_add_u64 v[86:87], s[60:61], 0, v[84:85]
	v_fmac_f32_e32 v8, v178, v127
	v_cvt_pk_bf16_f32 v117, v8, v89
	global_store_dword v[86:87], v117, off
	v_lshl_add_u64 v[86:87], s[62:63], 0, v[84:85]
	v_cvt_pk_bf16_f32 v117, v25, v83
	global_store_dword v[86:87], v117, off
	v_mul_f32_e32 v86, v88, v89
	v_mul_f32_e32 v9, v9, v89
	v_cvt_pk_bf16_f32 v9, v86, v9
	v_mul_f32_e32 v86, v182, v187
	v_rcp_f32_e32 v89, v26
	v_fmac_f32_e32 v86, v177, v123
	v_fmac_f32_e32 v86, v184, v189
	v_lshl_add_u64 v[84:85], s[66:67], 0, v[84:85]
	v_mul_f32_e32 v26, v181, v86
	global_store_dword v[84:85], v9, off
	v_lshl_add_u64 v[84:85], v[90:91], 0, v[76:77]
	v_mul_f32_e32 v90, v118, v26
	v_add_f32_e32 v26, -1.0, v89
	v_add_f32_e32 v87, -1.0, v10
	v_mul_f32_e32 v9, v176, v127
	v_fma_f32 v26, v180, v26, 1.0
	v_fma_f32 v87, v180, v87, 1.0
	v_lshlrev_b64 v[84:85], 2, v[84:85]
	v_fmac_f32_e32 v9, v175, v122
	v_mul_f32_e32 v26, v26, v86
	v_mul_f32_e32 v88, v87, v86
	v_lshl_add_u64 v[86:87], s[60:61], 0, v[84:85]
	v_fmac_f32_e32 v9, v178, v188
	v_cvt_pk_bf16_f32 v91, v9, v90
	global_store_dword v[86:87], v91, off
	v_lshl_add_u64 v[86:87], s[62:63], 0, v[84:85]
	v_cvt_pk_bf16_f32 v91, v26, v88
	global_store_dword v[86:87], v91, off
	v_mul_f32_e32 v86, v89, v90
	v_mul_f32_e32 v10, v10, v90
	v_cvt_pk_bf16_f32 v10, v86, v10
	v_mul_f32_e32 v86, v182, v189
	v_rcp_f32_e32 v89, v27
	v_rcp_f32_e32 v90, v11
	v_fmac_f32_e32 v86, v177, v187
	v_fmac_f32_e32 v86, v184, v191
	v_lshl_add_u64 v[84:85], s[66:67], 0, v[84:85]
	v_mul_f32_e32 v11, v181, v86
	global_store_dword v[84:85], v10, off
	v_lshl_add_u64 v[84:85], v[92:93], 0, v[76:77]
	v_mul_f32_e32 v91, v116, v11
	v_add_f32_e32 v11, -1.0, v89
	v_add_f32_e32 v27, -1.0, v90
	v_mul_f32_e32 v10, v176, v188
	v_fma_f32 v11, v180, v11, 1.0
	v_fma_f32 v27, v180, v27, 1.0
	v_lshlrev_b64 v[84:85], 2, v[84:85]
	v_fmac_f32_e32 v10, v175, v127
	v_mul_f32_e32 v11, v11, v86
	v_mul_f32_e32 v27, v27, v86
	v_lshl_add_u64 v[86:87], s[60:61], 0, v[84:85]
	v_fmac_f32_e32 v10, v178, v190
	v_cvt_pk_bf16_f32 v92, v10, v91
	global_store_dword v[86:87], v92, off
	v_lshl_add_u64 v[86:87], s[62:63], 0, v[84:85]
	v_cvt_pk_bf16_f32 v92, v11, v27
	global_store_dword v[86:87], v92, off
	v_mul_f32_e32 v86, v89, v91
	v_lshl_add_u64 v[84:85], s[66:67], 0, v[84:85]
	v_mul_f32_e32 v87, v90, v91
	v_cvt_pk_bf16_f32 v86, v86, v87
	global_store_dword v[84:85], v86, off
	v_add_u32_e32 v86, 0x16120, v186
	ds_read_u16 v84, v126 offset:57856
	ds_read_u16 v86, v86
	ds_read_u16 v85, v126 offset:58880
	v_add_f32_e32 v87, -1.0, v12
	v_fma_f32 v87, v180, v87, 1.0
	s_waitcnt lgkmcnt(2)
	v_lshlrev_b32_e32 v84, 16, v84
	s_waitcnt lgkmcnt(1)
	v_lshlrev_b32_e32 v90, 16, v86
	v_add_u32_e32 v86, 0x16520, v186
	ds_read_u16 v86, v86
	s_waitcnt lgkmcnt(1)
	v_lshlrev_b32_e32 v85, 16, v85
	v_mul_f32_e32 v89, v176, v90
	v_fmac_f32_e32 v89, v175, v84
	v_add_f32_e32 v29, 1.0, v29
	s_waitcnt lgkmcnt(0)
	v_lshlrev_b32_e32 v91, 16, v86
	v_add_u32_e32 v86, 0x16f40, v186
	ds_read_u16 v86, v86
	v_add_f32_e32 v13, 1.0, v13
	v_rcp_f32_e32 v13, v13
	v_add_f32_e32 v14, v14, v183
	v_mul_f32_e32 v30, 0xbfb8aa3b, v30
	s_waitcnt lgkmcnt(0)
	v_lshlrev_b32_e32 v92, 16, v86
	v_add_u32_e32 v86, 0x17340, v186
	ds_read_u16 v86, v86
	v_fmac_f32_e32 v89, v178, v92
	v_mul_f32_e32 v14, 0xbfb8aa3b, v14
	v_exp_f32_e32 v30, v30
	v_exp_f32_e32 v14, v14
	s_waitcnt lgkmcnt(0)
	v_lshlrev_b32_e32 v93, 16, v86
	v_add_u32_e32 v86, 0x17d60, v186
	ds_read_u16 v86, v86
	v_add_f32_e32 v30, 1.0, v30
	v_add_f32_e32 v14, 1.0, v14
	v_rcp_f32_e32 v14, v14
	v_add_f32_e32 v31, v31, v185
	s_waitcnt lgkmcnt(0)
	v_lshlrev_b32_e32 v116, 16, v86
	v_add_u32_e32 v86, 0x18160, v186
	ds_read_u16 v86, v86
	v_add_f32_e32 v15, v15, v183
	v_mul_f32_e32 v31, 0xbfb8aa3b, v31
	v_mul_f32_e32 v15, 0xbfb8aa3b, v15
	v_exp_f32_e32 v31, v31
	s_waitcnt lgkmcnt(0)
	v_lshlrev_b32_e32 v117, 16, v86
	v_add_u32_e32 v86, 0x18b80, v186
	ds_read_u16 v86, v86
	v_exp_f32_e32 v15, v15
	v_add_f32_e32 v31, 1.0, v31
	ds_bpermute_b32 v35, v106, v132
	s_waitcnt lgkmcnt(1)
	v_lshlrev_b32_e32 v118, 16, v86
	v_add_u32_e32 v86, 0x18f80, v186
	ds_read_u16 v86, v86
	v_add_f32_e32 v15, 1.0, v15
	s_waitcnt lgkmcnt(1)
	v_add_f32_e32 v35, v132, v35
	s_waitcnt lgkmcnt(0)
	v_lshlrev_b32_e32 v119, 16, v86
	v_add_u32_e32 v86, 0x199a0, v186
	ds_read_u16 v86, v86
	s_waitcnt lgkmcnt(0)
	v_lshlrev_b32_e32 v120, 16, v86
	v_add_u32_e32 v86, 0x19da0, v186
	ds_read_u16 v86, v86
	s_waitcnt lgkmcnt(0)
	v_lshlrev_b32_e32 v121, 16, v86
	v_mul_f32_e32 v86, v182, v91
	v_fmac_f32_e32 v86, v177, v85
	v_lshl_add_u64 v[84:85], v[94:95], 0, v[76:77]
	v_rcp_f32_e32 v94, v28
	v_fmac_f32_e32 v86, v184, v93
	v_mul_f32_e32 v28, v181, v86
	v_mul_f32_e32 v95, v114, v28
	v_add_f32_e32 v28, -1.0, v94
	v_fma_f32 v28, v180, v28, 1.0
	v_lshlrev_b64 v[84:85], 2, v[84:85]
	v_mul_f32_e32 v28, v28, v86
	v_mul_f32_e32 v114, v87, v86
	v_lshl_add_u64 v[86:87], s[60:61], 0, v[84:85]
	v_cvt_pk_bf16_f32 v122, v89, v95
	global_store_dword v[86:87], v122, off
	v_lshl_add_u64 v[86:87], s[62:63], 0, v[84:85]
	v_mul_f32_e32 v12, v12, v95
	v_cvt_pk_bf16_f32 v122, v28, v114
	global_store_dword v[86:87], v122, off
	v_lshl_add_u64 v[84:85], s[66:67], 0, v[84:85]
	v_mul_f32_e32 v86, v94, v95
	v_cvt_pk_bf16_f32 v12, v86, v12
	global_store_dword v[84:85], v12, off
	v_mul_f32_e32 v12, v176, v92
	v_fmac_f32_e32 v12, v175, v90
	v_mul_f32_e32 v86, v182, v93
	v_rcp_f32_e32 v90, v29
	v_fmac_f32_e32 v86, v177, v91
	v_fmac_f32_e32 v86, v184, v117
	v_mul_f32_e32 v29, v181, v86
	v_lshl_add_u64 v[84:85], v[96:97], 0, v[76:77]
	v_mul_f32_e32 v91, v113, v29
	v_add_f32_e32 v29, -1.0, v90
	v_add_f32_e32 v87, -1.0, v13
	v_fma_f32 v29, v180, v29, 1.0
	v_fma_f32 v87, v180, v87, 1.0
	v_lshlrev_b64 v[84:85], 2, v[84:85]
	v_mul_f32_e32 v29, v29, v86
	v_mul_f32_e32 v113, v87, v86
	v_lshl_add_u64 v[86:87], s[60:61], 0, v[84:85]
	v_fmac_f32_e32 v12, v178, v116
	v_cvt_pk_bf16_f32 v94, v12, v91
	global_store_dword v[86:87], v94, off
	v_lshl_add_u64 v[86:87], s[62:63], 0, v[84:85]
	v_cvt_pk_bf16_f32 v94, v29, v113
	global_store_dword v[86:87], v94, off
	v_mul_f32_e32 v86, v90, v91
	v_mul_f32_e32 v13, v13, v91
	v_cvt_pk_bf16_f32 v13, v86, v13
	v_mul_f32_e32 v86, v182, v117
	v_rcp_f32_e32 v90, v30
	v_fmac_f32_e32 v86, v177, v93
	v_fmac_f32_e32 v86, v184, v119
	v_lshl_add_u64 v[84:85], s[66:67], 0, v[84:85]
	v_mul_f32_e32 v30, v181, v86
	global_store_dword v[84:85], v13, off
	v_lshl_add_u64 v[84:85], v[98:99], 0, v[76:77]
	v_mul_f32_e32 v91, v112, v30
	v_add_f32_e32 v30, -1.0, v90
	v_add_f32_e32 v87, -1.0, v14
	v_mul_f32_e32 v13, v176, v116
	v_fma_f32 v30, v180, v30, 1.0
	v_fma_f32 v87, v180, v87, 1.0
	v_lshlrev_b64 v[84:85], 2, v[84:85]
	v_fmac_f32_e32 v13, v175, v92
	v_mul_f32_e32 v30, v30, v86
	v_mul_f32_e32 v112, v87, v86
	v_lshl_add_u64 v[86:87], s[60:61], 0, v[84:85]
	v_fmac_f32_e32 v13, v178, v118
	v_cvt_pk_bf16_f32 v92, v13, v91
	global_store_dword v[86:87], v92, off
	v_lshl_add_u64 v[86:87], s[62:63], 0, v[84:85]
	v_cvt_pk_bf16_f32 v92, v30, v112
	global_store_dword v[86:87], v92, off
	v_lshl_add_u64 v[84:85], s[66:67], 0, v[84:85]
	v_mul_f32_e32 v86, v90, v91
	v_mul_f32_e32 v14, v14, v91
	v_cvt_pk_bf16_f32 v14, v86, v14
	global_store_dword v[84:85], v14, off
	v_mul_f32_e32 v84, v182, v119
	v_rcp_f32_e32 v86, v31
	v_rcp_f32_e32 v87, v15
	v_fmac_f32_e32 v84, v177, v117
	v_fmac_f32_e32 v84, v184, v121
	v_mul_f32_e32 v15, v181, v84
	v_lshl_add_u64 v[76:77], v[100:101], 0, v[76:77]
	v_mul_f32_e32 v90, v111, v15
	v_add_f32_e32 v15, -1.0, v86
	v_add_f32_e32 v31, -1.0, v87
	v_mul_f32_e32 v14, v176, v118
	v_fma_f32 v15, v180, v15, 1.0
	v_fma_f32 v31, v180, v31, 1.0
	v_lshlrev_b64 v[76:77], 2, v[76:77]
	v_fmac_f32_e32 v14, v175, v116
	v_mul_f32_e32 v15, v15, v84
	v_mul_f32_e32 v31, v31, v84
	v_lshl_add_u64 v[84:85], s[60:61], 0, v[76:77]
	v_fmac_f32_e32 v14, v178, v120
	v_cvt_pk_bf16_f32 v91, v14, v90
	global_store_dword v[84:85], v91, off
	v_lshl_add_u64 v[84:85], s[62:63], 0, v[76:77]
	v_cvt_pk_bf16_f32 v91, v15, v31
	global_store_dword v[84:85], v91, off
	v_lshl_add_u64 v[76:77], s[66:67], 0, v[76:77]
	v_mul_f32_e32 v84, v86, v90
	v_mul_f32_e32 v85, v87, v90
	v_cvt_pk_bf16_f32 v84, v84, v85
	global_store_dword v[76:77], v84, off
	ds_bpermute_b32 v76, v107, v35
	s_waitcnt lgkmcnt(0)
	v_add_f32_e32 v35, v35, v76
	ds_bpermute_b32 v76, v108, v35
	s_waitcnt lgkmcnt(0)
	v_add_f32_e32 v35, v35, v76
	ds_bpermute_b32 v76, v109, v35
	s_waitcnt lgkmcnt(0)
	v_add_f32_e32 v35, v35, v76
	ds_bpermute_b32 v76, v110, v35
	s_and_saveexec_b64 s[6:7], vcc
	s_cbranch_execz .LBB0_668
	v_lshlrev_b64 v[84:85], 5, v[36:37]
	v_lshl_add_u64 v[84:85], s[4:5], 0, v[84:85]
	s_waitcnt lgkmcnt(0)
	v_add_f32_e32 v35, v35, v76
	flat_store_dword v[84:85], v35
